# EpiResid y loads: two 32-row groups in flight (G0+G1 at epilogue start, G2 at G1 start), vmcnt 15/23/15
# speedup vs baseline: 1.0397x; 1.0031x over previous
.LBB0_681:
	s_add_i32 s9, s7, 1
	s_bitcmp1_b32 s9, 0
	s_cselect_b32 s10, 0xe000, 0
	v_add_u32_e32 v115, s10, v109
	v_lshl_add_u64 v[116:117], v[98:99], 0, s[2:3]
	v_readfirstlane_b32 s10, v115
	v_add_u32_e32 v120, 0x2000, v115
	v_lshl_add_u64 v[118:119], v[116:117], 0, s[12:13]
	s_mov_b32 m0, s10
	v_readfirstlane_b32 s10, v120
	s_waitcnt vmcnt(0)
	s_waitcnt vmcnt(0) lgkmcnt(0)
	s_barrier
	global_load_lds_dwordx4 v[118:119], off
	v_lshl_add_u64 v[118:119], v[116:117], 0, s[16:17]
	s_mov_b32 m0, s10
	v_lshl_add_u64 v[116:117], v[116:117], 0, s[18:19]
	global_load_lds_dwordx4 v[118:119], off
	v_add_u32_e32 v118, 0x4000, v115
	v_add_u32_e32 v120, 0x6000, v115
	v_readfirstlane_b32 s10, v118
	s_mov_b32 m0, s10
	s_mov_b64 s[10:11], 0x6a94080
	global_load_lds_dwordx4 v[116:117], off
	v_lshl_add_u64 v[116:117], v[96:97], 0, s[2:3]
	v_lshl_add_u64 v[118:119], v[116:117], 0, s[10:11]
	v_readfirstlane_b32 s10, v120
	s_mov_b32 m0, s10
	s_mov_b64 s[10:11], 0x6ab4080
	v_add_u32_e32 v120, 0x8000, v115
	global_load_lds_dwordx4 v[118:119], off
	v_lshl_add_u64 v[118:119], v[116:117], 0, s[10:11]
	v_readfirstlane_b32 s10, v120
	s_mov_b32 m0, s10
	s_mov_b64 s[10:11], 0x6ad4080
	v_add_u32_e32 v120, 0xa000, v115
	global_load_lds_dwordx4 v[118:119], off
	v_lshl_add_u64 v[118:119], v[116:117], 0, s[10:11]
	v_readfirstlane_b32 s10, v120
	s_mov_b32 m0, s10
	s_mov_b64 s[10:11], 0x6af4080
	v_add_u32_e32 v115, 0xc000, v115
	v_lshl_add_u64 v[116:117], v[116:117], 0, s[10:11]
	v_readfirstlane_b32 s10, v115
	global_load_lds_dwordx4 v[118:119], off
	s_mov_b32 m0, s10
	s_nop 0
	global_load_lds_dwordx4 v[116:117], off
	s_bitcmp1_b32 s7, 0
	s_cselect_b32 s7, 0xe000, 0
	v_add_u32_e32 v115, s7, v114
	v_add_u32_e32 v120, v115, v111
	ds_read_b128 v[116:119], v120 offset:0
	v_add_u32_e32 v128, s7, v113
	ds_read_b128 v[120:123], v120 offset:0x1000
	v_add_u32_e32 v134, v128, v111
	ds_read_b128 v[124:127], v134 offset:0
	ds_read_b128 v[130:133], v134 offset:0x1000
	ds_read_b128 v[134:137], v134 offset:0x2000
	v_add_u32_e32 v148, v115, v110
	ds_read_b128 v[144:147], v148 offset:0
	ds_read_b128 v[148:151], v148 offset:0x1000
	v_add_u32_e32 v152, v128, v110
	ds_read_b128 v[182:185], v152 offset:0
	ds_read_b128 v[186:189], v152 offset:0x1000
	ds_read_b128 v[190:193], v152 offset:0x2000
	s_waitcnt lgkmcnt(5)
	s_nop 0
	v_mfma_f32_32x32x16_bf16 v[64:79], v[116:119], v[124:127], v[64:79]
	v_mfma_f32_32x32x16_bf16 v[32:47], v[116:119], v[130:133], v[32:47]
	v_mfma_f32_32x32x16_bf16 v[0:15], v[116:119], v[134:137], v[0:15]
	v_mfma_f32_32x32x16_bf16 v[80:95], v[120:123], v[124:127], v[80:95]
	v_mfma_f32_32x32x16_bf16 v[48:63], v[120:123], v[130:133], v[48:63]
	v_mfma_f32_32x32x16_bf16 v[16:31], v[120:123], v[134:137], v[16:31]
	v_add_u32_e32 v120, v115, v108
	ds_read_b128 v[116:119], v120 offset:0
	ds_read_b128 v[120:123], v120 offset:0x1000
	v_add_u32_e32 v134, v128, v108
	ds_read_b128 v[124:127], v134 offset:0
	ds_read_b128 v[130:133], v134 offset:0x1000
	ds_read_b128 v[134:137], v134 offset:0x2000
	s_waitcnt lgkmcnt(5)
	s_nop 0
	v_mfma_f32_32x32x16_bf16 v[64:79], v[144:147], v[182:185], v[64:79]
	v_mfma_f32_32x32x16_bf16 v[32:47], v[144:147], v[186:189], v[32:47]
	v_mfma_f32_32x32x16_bf16 v[0:15], v[144:147], v[190:193], v[0:15]
	v_mfma_f32_32x32x16_bf16 v[80:95], v[148:151], v[182:185], v[80:95]
	v_mfma_f32_32x32x16_bf16 v[48:63], v[148:151], v[186:189], v[48:63]
	v_mfma_f32_32x32x16_bf16 v[16:31], v[148:151], v[190:193], v[16:31]
	v_add_u32_e32 v115, v115, v107
	ds_read_b128 v[144:147], v115 offset:0
	ds_read_b128 v[148:151], v115 offset:0x1000
	v_add_u32_e32 v115, v128, v107
	ds_read_b128 v[182:185], v115 offset:0
	ds_read_b128 v[186:189], v115 offset:0x1000
	ds_read_b128 v[190:193], v115 offset:0x2000
	s_waitcnt lgkmcnt(5)
	s_nop 0
	v_mfma_f32_32x32x16_bf16 v[64:79], v[116:119], v[124:127], v[64:79]
	v_mfma_f32_32x32x16_bf16 v[32:47], v[116:119], v[130:133], v[32:47]
	v_mfma_f32_32x32x16_bf16 v[0:15], v[116:119], v[134:137], v[0:15]
	v_mfma_f32_32x32x16_bf16 v[80:95], v[120:123], v[124:127], v[80:95]
	v_mfma_f32_32x32x16_bf16 v[48:63], v[120:123], v[130:133], v[48:63]
	v_mfma_f32_32x32x16_bf16 v[16:31], v[120:123], v[134:137], v[16:31]
	s_waitcnt lgkmcnt(0)
	s_nop 0
	v_mfma_f32_32x32x16_bf16 v[64:79], v[144:147], v[182:185], v[64:79]
	v_mfma_f32_32x32x16_bf16 v[32:47], v[144:147], v[186:189], v[32:47]
	v_mfma_f32_32x32x16_bf16 v[0:15], v[144:147], v[190:193], v[0:15]
	v_mfma_f32_32x32x16_bf16 v[80:95], v[148:151], v[182:185], v[80:95]
	v_mfma_f32_32x32x16_bf16 v[48:63], v[148:151], v[186:189], v[48:63]
	v_mfma_f32_32x32x16_bf16 v[16:31], v[148:151], v[190:193], v[16:31]
	s_add_u32 s2, s2, 0x80
	s_addc_u32 s3, s3, 0
	s_cmpk_eq_i32 s2, 0x780
	s_mov_b32 s7, s9
	s_cbranch_scc0 .LBB0_681
	s_waitcnt vmcnt(0)
	s_waitcnt vmcnt(0) lgkmcnt(0)
	s_barrier
	v_add_u32_e32 v109, 0x14000, v112
	v_add_u32_e32 v112, v109, v111
	ds_read_b128 v[96:99], v112 offset:0
	v_add_u32_e32 v128, 0xe000, v113
	ds_read_b128 v[112:115], v112 offset:0x1000
	v_add_u32_e32 v111, v128, v111
	ds_read_b128 v[116:119], v111 offset:0
	ds_read_b128 v[120:123], v111 offset:0x1000
	ds_read_b128 v[124:127], v111 offset:0x2000
	v_add_u32_e32 v111, v109, v110
	ds_read_b128 v[130:133], v111 offset:0
	ds_read_b128 v[134:137], v111 offset:0x1000
	v_add_u32_e32 v110, v128, v110
	ds_read_b128 v[144:147], v110 offset:0
	ds_read_b128 v[148:151], v110 offset:0x1000
	ds_read_b128 v[182:185], v110 offset:0x2000
	s_waitcnt lgkmcnt(5)
	s_nop 0
	v_mfma_f32_32x32x16_bf16 v[64:79], v[96:99], v[116:119], v[64:79]
	v_mfma_f32_32x32x16_bf16 v[32:47], v[96:99], v[120:123], v[32:47]
	v_mfma_f32_32x32x16_bf16 v[0:15], v[96:99], v[124:127], v[0:15]
	v_mfma_f32_32x32x16_bf16 v[48:63], v[112:115], v[120:123], v[48:63]
	v_mfma_f32_32x32x16_bf16 v[16:31], v[112:115], v[124:127], v[16:31]
	v_mfma_f32_32x32x16_bf16 v[80:95], v[112:115], v[116:119], v[80:95]
	v_add_u32_e32 v110, v109, v108
	ds_read_b128 v[96:99], v110 offset:0
	ds_read_b128 v[110:113], v110 offset:0x1000
	v_add_u32_e32 v108, v128, v108
	ds_read_b128 v[114:117], v108 offset:0
	ds_read_b128 v[118:121], v108 offset:0x1000
	ds_read_b128 v[122:125], v108 offset:0x2000
	s_waitcnt lgkmcnt(5)
	s_nop 0
	v_mfma_f32_32x32x16_bf16 v[64:79], v[130:133], v[144:147], v[64:79]
	v_mfma_f32_32x32x16_bf16 v[32:47], v[130:133], v[148:151], v[32:47]
	v_mfma_f32_32x32x16_bf16 v[0:15], v[130:133], v[182:185], v[0:15]
	v_mfma_f32_32x32x16_bf16 v[48:63], v[134:137], v[148:151], v[48:63]
	v_mfma_f32_32x32x16_bf16 v[16:31], v[134:137], v[182:185], v[16:31]
	v_mfma_f32_32x32x16_bf16 v[80:95], v[134:137], v[144:147], v[80:95]
	v_add_u32_e32 v108, v109, v107
	ds_read_b128 v[130:133], v108 offset:0
	ds_read_b128 v[134:137], v108 offset:0x1000
	v_add_u32_e32 v107, v128, v107
	ds_read_b128 v[144:147], v107 offset:0
	ds_read_b128 v[148:151], v107 offset:0x1000
	ds_read_b128 v[182:185], v107 offset:0x2000
	s_waitcnt lgkmcnt(5)
	s_nop 0
	v_mfma_f32_32x32x16_bf16 v[64:79], v[96:99], v[114:117], v[64:79]
	v_mfma_f32_32x32x16_bf16 v[32:47], v[96:99], v[118:121], v[32:47]
	v_mfma_f32_32x32x16_bf16 v[0:15], v[96:99], v[122:125], v[0:15]
	v_mfma_f32_32x32x16_bf16 v[48:63], v[110:113], v[118:121], v[48:63]
	v_mfma_f32_32x32x16_bf16 v[16:31], v[110:113], v[122:125], v[16:31]
	v_mfma_f32_32x32x16_bf16 v[80:95], v[110:113], v[114:117], v[80:95]
	s_waitcnt lgkmcnt(0)
	s_nop 0
	v_mfma_f32_32x32x16_bf16 v[64:79], v[130:133], v[144:147], v[64:79]
	v_mfma_f32_32x32x16_bf16 v[32:47], v[130:133], v[148:151], v[32:47]
	v_mfma_f32_32x32x16_bf16 v[0:15], v[130:133], v[182:185], v[0:15]
	v_mfma_f32_32x32x16_bf16 v[48:63], v[134:137], v[148:151], v[48:63]
	v_mfma_f32_32x32x16_bf16 v[16:31], v[134:137], v[182:185], v[16:31]
	v_mfma_f32_32x32x16_bf16 v[80:95], v[134:137], v[144:147], v[80:95]
	v_add_u32_e32 v96, s4, v106
	v_lshrrev_b32_e32 v128, 4, v101
	v_and_b32_e32 v112, 15, v100
	v_or_b32_e32 v100, v96, v128
	v_add_u32_e32 v105, s8, v105
	v_ashrrev_i32_e32 v101, 31, v100
	v_lshl_or_b32 v98, v112, 2, v105
	v_lshlrev_b64 v[106:107], 12, v[100:101]
	v_ashrrev_i32_e32 v99, 31, v98
	v_lshl_add_u64 v[106:107], s[40:41], 0, v[106:107]
	v_lshl_add_u64 v[110:111], v[98:99], 2, v[106:107]
	s_barrier
	global_load_dwordx4 v[198:201], v[110:111], off
	v_add_co_u32_e32 v182, vcc, 0x4000, v110
	s_nop 1
	v_addc_co_u32_e32 v183, vcc, 0, v111, vcc
	global_load_dwordx4 v[202:205], v[182:183], off
	v_add_co_u32_e32 v182, vcc, 0x4000, v182
	s_nop 1
	v_addc_co_u32_e32 v183, vcc, 0, v183, vcc
	global_load_dwordx4 v[206:209], v[182:183], off
	v_add_co_u32_e32 v182, vcc, 0x4000, v182
	s_nop 1
	v_addc_co_u32_e32 v183, vcc, 0, v183, vcc
	global_load_dwordx4 v[210:213], v[182:183], off
	v_add_co_u32_e32 v182, vcc, 0x4000, v182
	s_nop 1
	v_addc_co_u32_e32 v183, vcc, 0, v183, vcc
	global_load_dwordx4 v[214:217], v[182:183], off
	v_add_co_u32_e32 v182, vcc, 0x4000, v182
	s_nop 1
	v_addc_co_u32_e32 v183, vcc, 0, v183, vcc
	global_load_dwordx4 v[218:221], v[182:183], off
	v_add_co_u32_e32 v182, vcc, 0x4000, v182
	s_nop 1
	v_addc_co_u32_e32 v183, vcc, 0, v183, vcc
	global_load_dwordx4 v[222:225], v[182:183], off
	v_add_co_u32_e32 v182, vcc, 0x4000, v182
	s_nop 1
	v_addc_co_u32_e32 v183, vcc, 0, v183, vcc
	global_load_dwordx4 v[226:229], v[182:183], off
	v_add_co_u32_e32 v182, vcc, 0x4000, v182
	s_nop 1
	v_addc_co_u32_e32 v183, vcc, 0, v183, vcc
	global_load_dwordx4 v[184:187], v[182:183], off
	v_add_co_u32_e32 v182, vcc, 0x4000, v182
	s_nop 1
	v_addc_co_u32_e32 v183, vcc, 0, v183, vcc
	global_load_dwordx4 v[188:191], v[182:183], off
	v_add_co_u32_e32 v182, vcc, 0x4000, v182
	s_nop 1
	v_addc_co_u32_e32 v183, vcc, 0, v183, vcc
	global_load_dwordx4 v[192:195], v[182:183], off
	v_add_co_u32_e32 v182, vcc, 0x4000, v182
	s_nop 1
	v_addc_co_u32_e32 v183, vcc, 0, v183, vcc
	global_load_dwordx4 v[116:119], v[182:183], off
	v_add_co_u32_e32 v182, vcc, 0x4000, v182
	s_nop 1
	v_addc_co_u32_e32 v183, vcc, 0, v183, vcc
	global_load_dwordx4 v[120:123], v[182:183], off
	v_add_co_u32_e32 v182, vcc, 0x4000, v182
	s_nop 1
	v_addc_co_u32_e32 v183, vcc, 0, v183, vcc
	global_load_dwordx4 v[124:127], v[182:183], off
	v_add_co_u32_e32 v182, vcc, 0x4000, v182
	s_nop 1
	v_addc_co_u32_e32 v183, vcc, 0, v183, vcc
	global_load_dwordx4 v[130:133], v[182:183], off
	v_add_co_u32_e32 v182, vcc, 0x4000, v182
	s_nop 1
	v_addc_co_u32_e32 v183, vcc, 0, v183, vcc
	global_load_dwordx4 v[134:137], v[182:183], off
	s_movk_i32 s2, 0x2400
	s_cmp_lt_i32 s5, 22
	v_mul_lo_u32 v97, v103, s2
	s_cselect_b64 s[2:3], -1, 0
	s_cmp_gt_i32 s5, 21
	s_movk_i32 s5, 0x110
	v_and_b32_e32 v103, 16, v104
	v_mad_u32_u24 v104, v102, s5, v97
	v_add_u32_e32 v113, 0xfffff000, v96
	v_cndmask_b32_e64 v102, 0, 1, s[2:3]
	s_cselect_b64 s[2:3], -1, 0
	s_add_i32 s7, s4, 0xfffff000
	v_add_u32_e32 v104, v104, v103
	ds_write_b128 v104, v[64:67]
	ds_write_b128 v104, v[68:71] offset:32
	ds_write_b128 v104, v[72:75] offset:64
	ds_write_b128 v104, v[76:79] offset:96
	ds_write_b128 v104, v[80:83] offset:128
	ds_write_b128 v104, v[84:87] offset:160
	ds_write_b128 v104, v[88:91] offset:192
	ds_write_b128 v104, v[92:95] offset:224
	v_xor_b32_e32 v64, s7, v113
	s_movk_i32 s4, 0x400
	v_lshl_or_b32 v97, v112, 4, v97
	v_cmp_gt_u32_e32 vcc, s4, v64
	v_mad_u32_u24 v115, v128, s5, v97
	s_and_b64 s[4:5], s[2:3], vcc
	v_cndmask_b32_e64 v71, 0, 1, s[4:5]
	s_movk_i32 s4, 0x1000
	v_cmp_gt_i32_e32 vcc, s4, v100
	v_subrev_u32_e32 v114, s8, v98
	v_lshl_add_u32 v103, v114, 2, v167
	v_cndmask_b32_e32 v64, v71, v102, vcc
	v_and_b32_e32 v64, 1, v64
	v_cmp_eq_u32_e32 vcc, 1, v64
	v_ashrrev_i32_e32 v68, 6, v105
	s_mov_b32 s4, 0xc000
	v_cndmask_b32_e64 v64, v171, 0, vcc
	v_add_u32_e32 v70, v103, v64
	ds_read_b128 v[64:67], v115
	ds_read_b128 v[72:75], v70
	v_cmp_eq_u32_e64 s[36:37], 0, v112
	v_mad_i64_i32 v[68:69], s[4:5], v68, s4, 0
	s_and_b64 vcc, exec, s[0:1]
	s_waitcnt vmcnt(15) lgkmcnt(0)
	v_pk_fma_f32 v[66:67], v[66:67], v[74:75], v[200:201]
	v_pk_fma_f32 v[64:65], v[64:65], v[72:73], v[198:199]
	global_store_dwordx4 v[110:111], v[64:67], off
	s_cbranch_vccnz .LBB0_686
	ds_read_b128 v[72:75], v70 offset:2048
	v_lshlrev_b64 v[76:77], 10, v[100:101]
	v_lshl_add_u64 v[76:77], v[76:77], 1, s[42:43]
	v_lshl_add_u64 v[76:77], v[98:99], 1, v[76:77]
	s_waitcnt lgkmcnt(0)
	v_pk_mul_f32 v[72:73], v[64:65], v[72:73]
	v_pk_mul_f32 v[64:65], v[64:65], v[64:65]
	v_pk_mul_f32 v[74:75], v[66:67], v[74:75]
	v_pk_mul_f32 v[66:67], v[66:67], v[66:67]
	v_add_f32_e32 v64, v64, v65
	v_add_f32_e32 v64, v66, v64
	v_add_f32_e32 v64, v67, v64
	v_cvt_pk_bf16_f32 v72, v72, v73
	v_cvt_pk_bf16_f32 v73, v74, v75
	v_add_f32_dpp v64, v64, v64 quad_perm:[1,0,3,2] row_mask:0xf bank_mask:0xf bound_ctrl:1
	global_store_dwordx2 v[76:77], v[72:73], off
	s_nop 0
	v_add_f32_dpp v64, v64, v64 quad_perm:[2,3,0,1] row_mask:0xf bank_mask:0xf bound_ctrl:1
	s_nop 1
	v_add_f32_dpp v64, v64, v64 row_half_mirror row_mask:0xf bank_mask:0xf bound_ctrl:1
	s_nop 1
	v_mov_b32_dpp v65, v64 row_mirror row_mask:0xf bank_mask:0xf bound_ctrl:1
	s_and_saveexec_b64 s[4:5], s[36:37]
	s_cbranch_execz .LBB0_685
	v_lshl_add_u64 v[66:67], s[52:53], 0, v[68:69]
	v_lshl_add_u64 v[66:67], v[100:101], 2, v[66:67]
	v_add_f32_e32 v64, v64, v65
	global_store_dword v[66:67], v64, off

.LBB0_686:
	v_or_b32_e32 v70, 4, v128
	v_or_b32_e32 v72, v96, v70
	v_ashrrev_i32_e32 v73, 31, v72
	v_lshlrev_b64 v[64:65], 12, v[72:73]
	v_lshl_add_u64 v[64:65], s[40:41], 0, v[64:65]
	v_lshl_add_u64 v[84:85], v[98:99], 2, v[64:65]
	s_movk_i32 s4, 0x1000
	v_mul_u32_u24_e32 v74, 0x110, v128
	v_cmp_gt_i32_e32 vcc, s4, v72
	v_add_u32_e32 v86, v74, v97
	s_nop 0
	v_cndmask_b32_e32 v74, v71, v102, vcc
	v_and_b32_e32 v74, 1, v74
	v_cmp_eq_u32_e32 vcc, 1, v74
	s_nop 1
	v_cndmask_b32_e64 v74, v171, 0, vcc
	v_add_u32_e32 v74, v103, v74
	ds_read_b128 v[76:79], v86 offset:1088
	ds_read_b128 v[80:83], v74
	s_and_b64 vcc, exec, s[0:1]
	s_waitcnt vmcnt(15) lgkmcnt(0)
	v_pk_fma_f32 v[66:67], v[78:79], v[82:83], v[204:205]
	v_pk_fma_f32 v[64:65], v[76:77], v[80:81], v[202:203]
	global_store_dwordx4 v[84:85], v[64:67], off
	s_cbranch_vccnz .LBB0_690
	ds_read_b128 v[74:77], v74 offset:2048
	v_lshlrev_b64 v[72:73], 10, v[72:73]
	v_lshl_add_u64 v[72:73], v[72:73], 1, s[42:43]
	v_lshl_add_u64 v[72:73], v[98:99], 1, v[72:73]
	s_waitcnt lgkmcnt(0)
	v_pk_mul_f32 v[74:75], v[64:65], v[74:75]
	v_pk_mul_f32 v[64:65], v[64:65], v[64:65]
	v_pk_mul_f32 v[76:77], v[66:67], v[76:77]
	v_pk_mul_f32 v[66:67], v[66:67], v[66:67]
	v_add_f32_e32 v64, v64, v65
	v_add_f32_e32 v64, v66, v64
	v_add_f32_e32 v64, v67, v64
	v_cvt_pk_bf16_f32 v74, v74, v75
	v_cvt_pk_bf16_f32 v75, v76, v77
	v_add_f32_dpp v64, v64, v64 quad_perm:[1,0,3,2] row_mask:0xf bank_mask:0xf bound_ctrl:1
	global_store_dwordx2 v[72:73], v[74:75], off
	s_nop 0
	v_add_f32_dpp v64, v64, v64 quad_perm:[2,3,0,1] row_mask:0xf bank_mask:0xf bound_ctrl:1
	s_nop 1
	v_add_f32_dpp v64, v64, v64 row_half_mirror row_mask:0xf bank_mask:0xf bound_ctrl:1
	s_nop 1
	v_mov_b32_dpp v65, v64 row_mirror row_mask:0xf bank_mask:0xf bound_ctrl:1
	s_and_saveexec_b64 s[4:5], s[36:37]
	s_cbranch_execz .LBB0_689
	v_ashrrev_i32_e32 v97, 31, v96
	v_lshl_add_u64 v[66:67], s[52:53], 0, v[68:69]
	v_lshl_add_u64 v[72:73], v[96:97], 0, v[128:129]
	v_lshl_add_u64 v[66:67], v[72:73], 2, v[66:67]
	v_add_f32_e32 v64, v64, v65
	global_store_dword v[66:67], v64, off offset:16

.LBB0_690:
	v_or_b32_e32 v72, 8, v128
	v_or_b32_e32 v74, v96, v72
	v_ashrrev_i32_e32 v75, 31, v74
	v_lshlrev_b64 v[64:65], 12, v[74:75]
	v_lshl_add_u64 v[64:65], s[40:41], 0, v[64:65]
	v_lshl_add_u64 v[84:85], v[98:99], 2, v[64:65]
	s_movk_i32 s4, 0x1000
	v_cmp_gt_i32_e32 vcc, s4, v74
	s_nop 1
	v_cndmask_b32_e32 v73, v71, v102, vcc
	v_and_b32_e32 v73, 1, v73
	v_cmp_eq_u32_e32 vcc, 1, v73
	s_nop 1
	v_cndmask_b32_e64 v73, v171, 0, vcc
	v_add_u32_e32 v73, v103, v73
	ds_read_b128 v[76:79], v86 offset:2176
	ds_read_b128 v[80:83], v73
	s_and_b64 vcc, exec, s[0:1]
	s_waitcnt vmcnt(15) lgkmcnt(0)
	v_pk_fma_f32 v[66:67], v[78:79], v[82:83], v[208:209]
	v_pk_fma_f32 v[64:65], v[76:77], v[80:81], v[206:207]
	global_store_dwordx4 v[84:85], v[64:67], off
	s_cbranch_vccnz .LBB0_694
	ds_read_b128 v[76:79], v73 offset:2048
	v_lshlrev_b64 v[74:75], 10, v[74:75]
	v_lshl_add_u64 v[74:75], v[74:75], 1, s[42:43]
	v_lshl_add_u64 v[74:75], v[98:99], 1, v[74:75]
	s_waitcnt lgkmcnt(0)
	v_pk_mul_f32 v[76:77], v[64:65], v[76:77]
	v_pk_mul_f32 v[64:65], v[64:65], v[64:65]
	v_pk_mul_f32 v[78:79], v[66:67], v[78:79]
	v_pk_mul_f32 v[66:67], v[66:67], v[66:67]
	v_add_f32_e32 v64, v64, v65
	v_add_f32_e32 v64, v66, v64
	v_add_f32_e32 v64, v67, v64
	v_cvt_pk_bf16_f32 v76, v76, v77
	v_cvt_pk_bf16_f32 v77, v78, v79
	v_add_f32_dpp v64, v64, v64 quad_perm:[1,0,3,2] row_mask:0xf bank_mask:0xf bound_ctrl:1
	global_store_dwordx2 v[74:75], v[76:77], off
	s_nop 0
	v_add_f32_dpp v64, v64, v64 quad_perm:[2,3,0,1] row_mask:0xf bank_mask:0xf bound_ctrl:1
	s_nop 1
	v_add_f32_dpp v64, v64, v64 row_half_mirror row_mask:0xf bank_mask:0xf bound_ctrl:1
	s_nop 1
	v_mov_b32_dpp v65, v64 row_mirror row_mask:0xf bank_mask:0xf bound_ctrl:1
	s_and_saveexec_b64 s[4:5], s[36:37]
	s_cbranch_execz .LBB0_693
	v_ashrrev_i32_e32 v97, 31, v96
	v_lshl_add_u64 v[66:67], s[52:53], 0, v[68:69]
	v_lshl_add_u64 v[74:75], v[96:97], 0, v[128:129]
	v_lshl_add_u64 v[66:67], v[74:75], 2, v[66:67]
	v_add_f32_e32 v64, v64, v65
	global_store_dword v[66:67], v64, off offset:32

.LBB0_694:
	v_or_b32_e32 v74, 12, v128
	v_or_b32_e32 v76, v96, v74
	v_ashrrev_i32_e32 v77, 31, v76
	v_lshlrev_b64 v[64:65], 12, v[76:77]
	v_lshl_add_u64 v[64:65], s[40:41], 0, v[64:65]
	v_lshl_add_u64 v[88:89], v[98:99], 2, v[64:65]
	s_movk_i32 s4, 0x1000
	v_cmp_gt_i32_e32 vcc, s4, v76
	s_nop 1
	v_cndmask_b32_e32 v73, v71, v102, vcc
	v_and_b32_e32 v73, 1, v73
	v_cmp_eq_u32_e32 vcc, 1, v73
	s_nop 1
	v_cndmask_b32_e64 v73, v171, 0, vcc
	v_add_u32_e32 v73, v103, v73
	ds_read_b128 v[78:81], v86 offset:3264
	ds_read_b128 v[82:85], v73
	s_and_b64 vcc, exec, s[0:1]
	s_waitcnt vmcnt(15) lgkmcnt(0)
	v_pk_fma_f32 v[66:67], v[80:81], v[84:85], v[212:213]
	v_pk_fma_f32 v[64:65], v[78:79], v[82:83], v[210:211]
	global_store_dwordx4 v[88:89], v[64:67], off
	s_cbranch_vccnz .LBB0_698
	ds_read_b128 v[78:81], v73 offset:2048
	v_lshlrev_b64 v[76:77], 10, v[76:77]
	v_lshl_add_u64 v[76:77], v[76:77], 1, s[42:43]
	v_lshl_add_u64 v[76:77], v[98:99], 1, v[76:77]
	s_waitcnt lgkmcnt(0)
	v_pk_mul_f32 v[78:79], v[64:65], v[78:79]
	v_pk_mul_f32 v[64:65], v[64:65], v[64:65]
	v_pk_mul_f32 v[80:81], v[66:67], v[80:81]
	v_pk_mul_f32 v[66:67], v[66:67], v[66:67]
	v_add_f32_e32 v64, v64, v65
	v_add_f32_e32 v64, v66, v64
	v_add_f32_e32 v64, v67, v64
	v_cvt_pk_bf16_f32 v78, v78, v79
	v_cvt_pk_bf16_f32 v79, v80, v81
	v_add_f32_dpp v64, v64, v64 quad_perm:[1,0,3,2] row_mask:0xf bank_mask:0xf bound_ctrl:1
	global_store_dwordx2 v[76:77], v[78:79], off
	s_nop 0
	v_add_f32_dpp v64, v64, v64 quad_perm:[2,3,0,1] row_mask:0xf bank_mask:0xf bound_ctrl:1
	s_nop 1
	v_add_f32_dpp v64, v64, v64 row_half_mirror row_mask:0xf bank_mask:0xf bound_ctrl:1
	s_nop 1
	v_mov_b32_dpp v65, v64 row_mirror row_mask:0xf bank_mask:0xf bound_ctrl:1
	s_and_saveexec_b64 s[4:5], s[36:37]
	s_cbranch_execz .LBB0_697
	v_ashrrev_i32_e32 v97, 31, v96
	v_lshl_add_u64 v[66:67], s[52:53], 0, v[68:69]
	v_lshl_add_u64 v[76:77], v[96:97], 0, v[128:129]
	v_lshl_add_u64 v[66:67], v[76:77], 2, v[66:67]
	v_add_f32_e32 v64, v64, v65
	global_store_dword v[66:67], v64, off offset:48

.LBB0_698:
	v_or_b32_e32 v76, 16, v128
	v_or_b32_e32 v78, v96, v76
	v_ashrrev_i32_e32 v79, 31, v78
	v_lshlrev_b64 v[64:65], 12, v[78:79]
	v_lshl_add_u64 v[64:65], s[40:41], 0, v[64:65]
	v_lshl_add_u64 v[84:85], v[98:99], 2, v[64:65]
	s_movk_i32 s4, 0x1000
	v_cmp_gt_i32_e32 vcc, s4, v78
	s_nop 1
	v_cndmask_b32_e32 v73, v71, v102, vcc
	v_and_b32_e32 v73, 1, v73
	v_cmp_eq_u32_e32 vcc, 1, v73
	s_nop 1
	v_cndmask_b32_e64 v73, v171, 0, vcc
	v_add_u32_e32 v73, v103, v73
	ds_read_b128 v[80:83], v86 offset:4352
	ds_read_b128 v[88:91], v73
	s_and_b64 vcc, exec, s[0:1]
	s_waitcnt vmcnt(15) lgkmcnt(0)
	v_pk_fma_f32 v[66:67], v[82:83], v[90:91], v[216:217]
	v_pk_fma_f32 v[64:65], v[80:81], v[88:89], v[214:215]
	global_store_dwordx4 v[84:85], v[64:67], off
	s_cbranch_vccnz .LBB0_702
	ds_read_b128 v[80:83], v73 offset:2048
	v_lshlrev_b64 v[78:79], 10, v[78:79]
	v_lshl_add_u64 v[78:79], v[78:79], 1, s[42:43]
	v_lshl_add_u64 v[78:79], v[98:99], 1, v[78:79]
	s_waitcnt lgkmcnt(0)
	v_pk_mul_f32 v[80:81], v[64:65], v[80:81]
	v_pk_mul_f32 v[64:65], v[64:65], v[64:65]
	v_pk_mul_f32 v[82:83], v[66:67], v[82:83]
	v_pk_mul_f32 v[66:67], v[66:67], v[66:67]
	v_add_f32_e32 v64, v64, v65
	v_add_f32_e32 v64, v66, v64
	v_add_f32_e32 v64, v67, v64
	v_cvt_pk_bf16_f32 v80, v80, v81
	v_cvt_pk_bf16_f32 v81, v82, v83
	v_add_f32_dpp v64, v64, v64 quad_perm:[1,0,3,2] row_mask:0xf bank_mask:0xf bound_ctrl:1
	global_store_dwordx2 v[78:79], v[80:81], off
	s_nop 0
	v_add_f32_dpp v64, v64, v64 quad_perm:[2,3,0,1] row_mask:0xf bank_mask:0xf bound_ctrl:1
	s_nop 1
	v_add_f32_dpp v64, v64, v64 row_half_mirror row_mask:0xf bank_mask:0xf bound_ctrl:1
	s_nop 1
	v_mov_b32_dpp v65, v64 row_mirror row_mask:0xf bank_mask:0xf bound_ctrl:1
	s_and_saveexec_b64 s[4:5], s[36:37]
	s_cbranch_execz .LBB0_701
	v_ashrrev_i32_e32 v97, 31, v96
	v_lshl_add_u64 v[66:67], s[52:53], 0, v[68:69]
	v_lshl_add_u64 v[78:79], v[96:97], 0, v[128:129]
	v_lshl_add_u64 v[66:67], v[78:79], 2, v[66:67]
	v_add_f32_e32 v64, v64, v65
	global_store_dword v[66:67], v64, off offset:64

.LBB0_702:
	v_or_b32_e32 v78, 20, v128
	v_or_b32_e32 v80, v96, v78
	v_ashrrev_i32_e32 v81, 31, v80
	v_lshlrev_b64 v[64:65], 12, v[80:81]
	v_lshl_add_u64 v[64:65], s[40:41], 0, v[64:65]
	v_lshl_add_u64 v[92:93], v[98:99], 2, v[64:65]
	s_movk_i32 s4, 0x1000
	v_cmp_gt_i32_e32 vcc, s4, v80
	s_nop 1
	v_cndmask_b32_e32 v73, v71, v102, vcc
	v_and_b32_e32 v73, 1, v73
	v_cmp_eq_u32_e32 vcc, 1, v73
	s_nop 1
	v_cndmask_b32_e64 v73, v171, 0, vcc
	v_add_u32_e32 v73, v103, v73
	ds_read_b128 v[82:85], v86 offset:5440
	ds_read_b128 v[88:91], v73
	s_and_b64 vcc, exec, s[0:1]
	s_waitcnt vmcnt(15) lgkmcnt(0)
	v_pk_fma_f32 v[66:67], v[84:85], v[90:91], v[220:221]
	v_pk_fma_f32 v[64:65], v[82:83], v[88:89], v[218:219]
	global_store_dwordx4 v[92:93], v[64:67], off
	s_cbranch_vccnz .LBB0_706
	ds_read_b128 v[82:85], v73 offset:2048
	v_lshlrev_b64 v[80:81], 10, v[80:81]
	v_lshl_add_u64 v[80:81], v[80:81], 1, s[42:43]
	v_lshl_add_u64 v[80:81], v[98:99], 1, v[80:81]
	s_waitcnt lgkmcnt(0)
	v_pk_mul_f32 v[82:83], v[64:65], v[82:83]
	v_pk_mul_f32 v[64:65], v[64:65], v[64:65]
	v_pk_mul_f32 v[84:85], v[66:67], v[84:85]
	v_pk_mul_f32 v[66:67], v[66:67], v[66:67]
	v_add_f32_e32 v64, v64, v65
	v_add_f32_e32 v64, v66, v64
	v_add_f32_e32 v64, v67, v64
	v_cvt_pk_bf16_f32 v82, v82, v83
	v_cvt_pk_bf16_f32 v83, v84, v85
	v_add_f32_dpp v64, v64, v64 quad_perm:[1,0,3,2] row_mask:0xf bank_mask:0xf bound_ctrl:1
	global_store_dwordx2 v[80:81], v[82:83], off
	s_nop 0
	v_add_f32_dpp v64, v64, v64 quad_perm:[2,3,0,1] row_mask:0xf bank_mask:0xf bound_ctrl:1
	s_nop 1
	v_add_f32_dpp v64, v64, v64 row_half_mirror row_mask:0xf bank_mask:0xf bound_ctrl:1
	s_nop 1
	v_mov_b32_dpp v65, v64 row_mirror row_mask:0xf bank_mask:0xf bound_ctrl:1
	s_and_saveexec_b64 s[4:5], s[36:37]
	s_cbranch_execz .LBB0_705
	v_ashrrev_i32_e32 v97, 31, v96
	v_lshl_add_u64 v[66:67], s[52:53], 0, v[68:69]
	v_lshl_add_u64 v[80:81], v[96:97], 0, v[128:129]
	v_lshl_add_u64 v[66:67], v[80:81], 2, v[66:67]
	v_add_f32_e32 v64, v64, v65
	global_store_dword v[66:67], v64, off offset:80

.LBB0_706:
	v_or_b32_e32 v80, 24, v128
	v_or_b32_e32 v82, v96, v80
	v_ashrrev_i32_e32 v83, 31, v82
	v_lshlrev_b64 v[64:65], 12, v[82:83]
	v_lshl_add_u64 v[64:65], s[40:41], 0, v[64:65]
	v_lshl_add_u64 v[84:85], v[98:99], 2, v[64:65]
	s_movk_i32 s4, 0x1000
	v_cmp_gt_i32_e32 vcc, s4, v82
	s_nop 1
	v_cndmask_b32_e32 v73, v71, v102, vcc
	v_and_b32_e32 v73, 1, v73
	v_cmp_eq_u32_e32 vcc, 1, v73
	s_nop 1
	v_cndmask_b32_e64 v73, v171, 0, vcc
	v_add_u32_e32 v73, v103, v73
	ds_read_b128 v[88:91], v86 offset:6528
	ds_read_b128 v[92:95], v73
	s_and_b64 vcc, exec, s[0:1]
	s_waitcnt vmcnt(15) lgkmcnt(0)
	v_pk_fma_f32 v[66:67], v[90:91], v[94:95], v[224:225]
	v_pk_fma_f32 v[64:65], v[88:89], v[92:93], v[222:223]
	global_store_dwordx4 v[84:85], v[64:67], off
	s_cbranch_vccnz .LBB0_710
	ds_read_b128 v[88:91], v73 offset:2048
	v_lshlrev_b64 v[82:83], 10, v[82:83]
	v_lshl_add_u64 v[82:83], v[82:83], 1, s[42:43]
	v_lshl_add_u64 v[82:83], v[98:99], 1, v[82:83]
	s_waitcnt lgkmcnt(0)
	v_pk_mul_f32 v[88:89], v[64:65], v[88:89]
	v_pk_mul_f32 v[64:65], v[64:65], v[64:65]
	v_pk_mul_f32 v[84:85], v[66:67], v[90:91]
	v_pk_mul_f32 v[66:67], v[66:67], v[66:67]
	v_add_f32_e32 v64, v64, v65
	v_add_f32_e32 v64, v66, v64
	v_add_f32_e32 v64, v67, v64
	v_cvt_pk_bf16_f32 v88, v88, v89
	v_cvt_pk_bf16_f32 v89, v84, v85
	v_add_f32_dpp v64, v64, v64 quad_perm:[1,0,3,2] row_mask:0xf bank_mask:0xf bound_ctrl:1
	global_store_dwordx2 v[82:83], v[88:89], off
	s_nop 0
	v_add_f32_dpp v64, v64, v64 quad_perm:[2,3,0,1] row_mask:0xf bank_mask:0xf bound_ctrl:1
	s_nop 1
	v_add_f32_dpp v64, v64, v64 row_half_mirror row_mask:0xf bank_mask:0xf bound_ctrl:1
	s_nop 1
	v_mov_b32_dpp v65, v64 row_mirror row_mask:0xf bank_mask:0xf bound_ctrl:1
	s_and_saveexec_b64 s[4:5], s[36:37]
	s_cbranch_execz .LBB0_709
	v_ashrrev_i32_e32 v97, 31, v96
	v_lshl_add_u64 v[66:67], s[52:53], 0, v[68:69]
	v_lshl_add_u64 v[82:83], v[96:97], 0, v[128:129]
	v_lshl_add_u64 v[66:67], v[82:83], 2, v[66:67]
	v_add_f32_e32 v64, v64, v65
	global_store_dword v[66:67], v64, off offset:96

.LBB0_710:
	v_or_b32_e32 v82, 28, v128
	v_or_b32_e32 v84, v96, v82
	v_ashrrev_i32_e32 v85, 31, v84
	v_lshlrev_b64 v[64:65], 12, v[84:85]
	v_lshl_add_u64 v[64:65], s[40:41], 0, v[64:65]
	v_lshl_add_u64 v[100:101], v[98:99], 2, v[64:65]
	s_movk_i32 s4, 0x1000
	v_cmp_gt_i32_e32 vcc, s4, v84
	s_nop 1
	v_cndmask_b32_e32 v71, v71, v102, vcc
	v_and_b32_e32 v71, 1, v71
	v_cmp_eq_u32_e32 vcc, 1, v71
	s_nop 1
	v_cndmask_b32_e64 v71, v171, 0, vcc
	v_add_u32_e32 v71, v103, v71
	ds_read_b128 v[88:91], v86 offset:7616
	ds_read_b128 v[92:95], v71
	s_and_b64 vcc, exec, s[0:1]
	s_waitcnt vmcnt(15) lgkmcnt(0)
	v_pk_fma_f32 v[66:67], v[90:91], v[94:95], v[228:229]
	v_pk_fma_f32 v[64:65], v[88:89], v[92:93], v[226:227]
	global_store_dwordx4 v[100:101], v[64:67], off
	s_cbranch_vccnz .LBB0_714
	ds_read_b128 v[88:91], v71 offset:2048
	v_lshlrev_b64 v[84:85], 10, v[84:85]
	v_lshl_add_u64 v[84:85], v[84:85], 1, s[42:43]
	v_lshl_add_u64 v[84:85], v[98:99], 1, v[84:85]
	s_waitcnt lgkmcnt(0)
	v_pk_mul_f32 v[88:89], v[64:65], v[88:89]
	v_pk_mul_f32 v[64:65], v[64:65], v[64:65]
	v_pk_mul_f32 v[90:91], v[66:67], v[90:91]
	v_pk_mul_f32 v[66:67], v[66:67], v[66:67]
	v_add_f32_e32 v64, v64, v65
	v_add_f32_e32 v64, v66, v64
	v_add_f32_e32 v64, v67, v64
	v_cvt_pk_bf16_f32 v88, v88, v89
	v_cvt_pk_bf16_f32 v89, v90, v91
	v_add_f32_dpp v64, v64, v64 quad_perm:[1,0,3,2] row_mask:0xf bank_mask:0xf bound_ctrl:1
	global_store_dwordx2 v[84:85], v[88:89], off
	s_nop 0
	v_add_f32_dpp v64, v64, v64 quad_perm:[2,3,0,1] row_mask:0xf bank_mask:0xf bound_ctrl:1
	s_nop 1
	v_add_f32_dpp v64, v64, v64 row_half_mirror row_mask:0xf bank_mask:0xf bound_ctrl:1
	s_nop 1
	v_mov_b32_dpp v65, v64 row_mirror row_mask:0xf bank_mask:0xf bound_ctrl:1
	s_and_saveexec_b64 s[4:5], s[36:37]
	s_cbranch_execz .LBB0_713
	v_ashrrev_i32_e32 v97, 31, v96
	v_lshl_add_u64 v[66:67], s[52:53], 0, v[68:69]
	v_lshl_add_u64 v[84:85], v[96:97], 0, v[128:129]
	v_lshl_add_u64 v[66:67], v[84:85], 2, v[66:67]
	v_add_f32_e32 v64, v64, v65
	global_store_dword v[66:67], v64, off offset:112

.LBB0_714:
	s_nop 0
	v_add_u32_e32 v66, 32, v96
	v_or_b32_e32 v64, v66, v128
	v_ashrrev_i32_e32 v65, 31, v64
	v_lshlrev_b64 v[84:85], 12, v[64:65]
	v_lshl_add_u64 v[84:85], s[40:41], 0, v[84:85]
	v_lshl_add_u64 v[84:85], v[98:99], 2, v[84:85]
	v_add_co_u32_e32 v182, vcc, 0x20000, v84
	s_nop 1
	v_addc_co_u32_e32 v183, vcc, 0, v85, vcc
	global_load_dwordx4 v[198:201], v[182:183], off
	v_add_co_u32_e32 v182, vcc, 0x4000, v182
	s_nop 1
	v_addc_co_u32_e32 v183, vcc, 0, v183, vcc
	global_load_dwordx4 v[202:205], v[182:183], off
	v_add_co_u32_e32 v182, vcc, 0x4000, v182
	s_nop 1
	v_addc_co_u32_e32 v183, vcc, 0, v183, vcc
	global_load_dwordx4 v[206:209], v[182:183], off
	v_add_co_u32_e32 v182, vcc, 0x4000, v182
	s_nop 1
	v_addc_co_u32_e32 v183, vcc, 0, v183, vcc
	global_load_dwordx4 v[210:213], v[182:183], off
	v_add_co_u32_e32 v182, vcc, 0x4000, v182
	s_nop 1
	v_addc_co_u32_e32 v183, vcc, 0, v183, vcc
	global_load_dwordx4 v[214:217], v[182:183], off
	v_add_co_u32_e32 v182, vcc, 0x4000, v182
	s_nop 1
	v_addc_co_u32_e32 v183, vcc, 0, v183, vcc
	global_load_dwordx4 v[218:221], v[182:183], off
	v_add_co_u32_e32 v182, vcc, 0x4000, v182
	s_nop 1
	v_addc_co_u32_e32 v183, vcc, 0, v183, vcc
	global_load_dwordx4 v[222:225], v[182:183], off
	v_add_co_u32_e32 v182, vcc, 0x4000, v182
	s_nop 1
	v_addc_co_u32_e32 v183, vcc, 0, v183, vcc
	global_load_dwordx4 v[226:229], v[182:183], off
	ds_write_b128 v104, v[32:35]
	ds_write_b128 v104, v[36:39] offset:32
	ds_write_b128 v104, v[40:43] offset:64
	ds_write_b128 v104, v[44:47] offset:96
	ds_write_b128 v104, v[48:51] offset:128
	ds_write_b128 v104, v[52:55] offset:160
	ds_write_b128 v104, v[56:59] offset:192
	ds_write_b128 v104, v[60:63] offset:224
	v_add_u32_e32 v32, 0xfffff020, v96
	v_xor_b32_e32 v32, s7, v32
	s_movk_i32 s4, 0x400
	v_cmp_gt_u32_e32 vcc, s4, v32
	s_and_b64 s[4:5], s[2:3], vcc
	v_cndmask_b32_e64 v38, 0, 1, s[4:5]
	s_movk_i32 s4, 0x1000
	v_cmp_gt_i32_e32 vcc, s4, v64
	s_nop 1
	v_cndmask_b32_e32 v32, v38, v102, vcc
	v_and_b32_e32 v32, 1, v32
	v_cmp_eq_u32_e32 vcc, 1, v32
	s_nop 1
	v_cndmask_b32_e64 v32, v171, 0, vcc
	v_add_u32_e32 v36, v103, v32
	ds_read_b128 v[32:35], v86
	ds_read_b128 v[40:43], v36
	s_and_b64 vcc, exec, s[0:1]
	s_waitcnt vmcnt(23) lgkmcnt(0)
	v_pk_fma_f32 v[34:35], v[34:35], v[42:43], v[186:187]
	v_pk_fma_f32 v[32:33], v[32:33], v[40:41], v[184:185]
	global_store_dwordx4 v[84:85], v[32:35], off
	s_cbranch_vccnz .LBB0_718
	ds_read_b128 v[40:43], v36 offset:2048
	v_lshlrev_b64 v[36:37], 10, v[64:65]
	v_lshl_add_u64 v[36:37], v[36:37], 1, s[42:43]
	v_lshl_add_u64 v[36:37], v[98:99], 1, v[36:37]
	s_waitcnt lgkmcnt(0)
	v_pk_mul_f32 v[40:41], v[32:33], v[40:41]
	v_pk_mul_f32 v[32:33], v[32:33], v[32:33]
	v_pk_mul_f32 v[42:43], v[34:35], v[42:43]
	v_pk_mul_f32 v[34:35], v[34:35], v[34:35]
	v_add_f32_e32 v32, v32, v33
	v_add_f32_e32 v32, v34, v32
	v_add_f32_e32 v32, v35, v32
	v_cvt_pk_bf16_f32 v40, v40, v41
	v_cvt_pk_bf16_f32 v41, v42, v43
	v_add_f32_dpp v32, v32, v32 quad_perm:[1,0,3,2] row_mask:0xf bank_mask:0xf bound_ctrl:1
	global_store_dwordx2 v[36:37], v[40:41], off
	s_nop 0
	v_add_f32_dpp v32, v32, v32 quad_perm:[2,3,0,1] row_mask:0xf bank_mask:0xf bound_ctrl:1
	s_nop 1
	v_add_f32_dpp v32, v32, v32 row_half_mirror row_mask:0xf bank_mask:0xf bound_ctrl:1
	s_nop 1
	v_mov_b32_dpp v33, v32 row_mirror row_mask:0xf bank_mask:0xf bound_ctrl:1
	s_and_saveexec_b64 s[4:5], s[36:37]
	s_cbranch_execz .LBB0_717
	v_ashrrev_i32_e32 v97, 31, v96
	v_lshl_add_u64 v[34:35], s[52:53], 0, v[68:69]
	v_lshl_add_u64 v[36:37], v[96:97], 0, v[128:129]
	v_lshl_add_u64 v[34:35], v[36:37], 2, v[34:35]
	v_add_f32_e32 v32, v32, v33
	global_store_dword v[34:35], v32, off offset:128

.LBB0_718:
	v_or_b32_e32 v36, v66, v70
	v_ashrrev_i32_e32 v37, 31, v36
	v_lshlrev_b64 v[32:33], 12, v[36:37]
	v_lshl_add_u64 v[32:33], s[40:41], 0, v[32:33]
	v_lshl_add_u64 v[48:49], v[98:99], 2, v[32:33]
	s_movk_i32 s4, 0x1000
	v_cmp_gt_i32_e32 vcc, s4, v36
	s_nop 1
	v_cndmask_b32_e32 v39, v38, v102, vcc
	v_and_b32_e32 v39, 1, v39
	v_cmp_eq_u32_e32 vcc, 1, v39
	s_nop 1
	v_cndmask_b32_e64 v39, v171, 0, vcc
	v_add_u32_e32 v39, v103, v39
	ds_read_b128 v[40:43], v86 offset:1088
	ds_read_b128 v[44:47], v39
	s_and_b64 vcc, exec, s[0:1]
	s_waitcnt vmcnt(23) lgkmcnt(0)
	v_pk_fma_f32 v[34:35], v[42:43], v[46:47], v[190:191]
	v_pk_fma_f32 v[32:33], v[40:41], v[44:45], v[188:189]
	global_store_dwordx4 v[48:49], v[32:35], off
	s_cbranch_vccnz .LBB0_722
	ds_read_b128 v[40:43], v39 offset:2048
	v_lshlrev_b64 v[36:37], 10, v[36:37]
	v_lshl_add_u64 v[36:37], v[36:37], 1, s[42:43]
	v_lshl_add_u64 v[36:37], v[98:99], 1, v[36:37]
	s_waitcnt lgkmcnt(0)
	v_pk_mul_f32 v[40:41], v[32:33], v[40:41]
	v_pk_mul_f32 v[32:33], v[32:33], v[32:33]
	v_pk_mul_f32 v[42:43], v[34:35], v[42:43]
	v_pk_mul_f32 v[34:35], v[34:35], v[34:35]
	v_add_f32_e32 v32, v32, v33
	v_add_f32_e32 v32, v34, v32
	v_add_f32_e32 v32, v35, v32
	v_cvt_pk_bf16_f32 v40, v40, v41
	v_cvt_pk_bf16_f32 v41, v42, v43
	v_add_f32_dpp v32, v32, v32 quad_perm:[1,0,3,2] row_mask:0xf bank_mask:0xf bound_ctrl:1
	global_store_dwordx2 v[36:37], v[40:41], off
	s_nop 0
	v_add_f32_dpp v32, v32, v32 quad_perm:[2,3,0,1] row_mask:0xf bank_mask:0xf bound_ctrl:1
	s_nop 1
	v_add_f32_dpp v32, v32, v32 row_half_mirror row_mask:0xf bank_mask:0xf bound_ctrl:1
	s_nop 1
	v_mov_b32_dpp v33, v32 row_mirror row_mask:0xf bank_mask:0xf bound_ctrl:1
	s_and_saveexec_b64 s[4:5], s[36:37]
	s_cbranch_execz .LBB0_721
	v_mov_b32_e32 v71, v129
	v_ashrrev_i32_e32 v97, 31, v96
	v_lshl_add_u64 v[34:35], s[52:53], 0, v[68:69]
	v_lshl_add_u64 v[36:37], v[96:97], 0, v[70:71]
	v_lshl_add_u64 v[34:35], v[36:37], 2, v[34:35]
	v_add_f32_e32 v32, v32, v33
	global_store_dword v[34:35], v32, off offset:128

.LBB0_722:
	v_or_b32_e32 v36, v66, v72
	v_ashrrev_i32_e32 v37, 31, v36
	v_lshlrev_b64 v[32:33], 12, v[36:37]
	v_lshl_add_u64 v[32:33], s[40:41], 0, v[32:33]
	v_lshl_add_u64 v[48:49], v[98:99], 2, v[32:33]
	s_movk_i32 s4, 0x1000
	v_cmp_gt_i32_e32 vcc, s4, v36
	s_nop 1
	v_cndmask_b32_e32 v39, v38, v102, vcc
	v_and_b32_e32 v39, 1, v39
	v_cmp_eq_u32_e32 vcc, 1, v39
	s_nop 1
	v_cndmask_b32_e64 v39, v171, 0, vcc
	v_add_u32_e32 v39, v103, v39
	ds_read_b128 v[40:43], v86 offset:2176
	ds_read_b128 v[44:47], v39
	s_and_b64 vcc, exec, s[0:1]
	s_waitcnt vmcnt(23) lgkmcnt(0)
	v_pk_fma_f32 v[34:35], v[42:43], v[46:47], v[194:195]
	v_pk_fma_f32 v[32:33], v[40:41], v[44:45], v[192:193]
	global_store_dwordx4 v[48:49], v[32:35], off
	s_cbranch_vccnz .LBB0_726
	ds_read_b128 v[40:43], v39 offset:2048
	v_lshlrev_b64 v[36:37], 10, v[36:37]
	v_lshl_add_u64 v[36:37], v[36:37], 1, s[42:43]
	v_lshl_add_u64 v[36:37], v[98:99], 1, v[36:37]
	s_waitcnt lgkmcnt(0)
	v_pk_mul_f32 v[40:41], v[32:33], v[40:41]
	v_pk_mul_f32 v[32:33], v[32:33], v[32:33]
	v_pk_mul_f32 v[42:43], v[34:35], v[42:43]
	v_pk_mul_f32 v[34:35], v[34:35], v[34:35]
	v_add_f32_e32 v32, v32, v33
	v_add_f32_e32 v32, v34, v32
	v_add_f32_e32 v32, v35, v32
	v_cvt_pk_bf16_f32 v40, v40, v41
	v_cvt_pk_bf16_f32 v41, v42, v43
	v_add_f32_dpp v32, v32, v32 quad_perm:[1,0,3,2] row_mask:0xf bank_mask:0xf bound_ctrl:1
	global_store_dwordx2 v[36:37], v[40:41], off
	s_nop 0
	v_add_f32_dpp v32, v32, v32 quad_perm:[2,3,0,1] row_mask:0xf bank_mask:0xf bound_ctrl:1
	s_nop 1
	v_add_f32_dpp v32, v32, v32 row_half_mirror row_mask:0xf bank_mask:0xf bound_ctrl:1
	s_nop 1
	v_mov_b32_dpp v33, v32 row_mirror row_mask:0xf bank_mask:0xf bound_ctrl:1
	s_and_saveexec_b64 s[4:5], s[36:37]
	s_cbranch_execz .LBB0_725
	v_mov_b32_e32 v73, v129
	v_ashrrev_i32_e32 v97, 31, v96
	v_lshl_add_u64 v[34:35], s[52:53], 0, v[68:69]
	v_lshl_add_u64 v[36:37], v[96:97], 0, v[72:73]
	v_lshl_add_u64 v[34:35], v[36:37], 2, v[34:35]
	v_add_f32_e32 v32, v32, v33
	global_store_dword v[34:35], v32, off offset:128

.LBB0_726:
	v_or_b32_e32 v36, v66, v74
	v_ashrrev_i32_e32 v37, 31, v36
	v_lshlrev_b64 v[32:33], 12, v[36:37]
	v_lshl_add_u64 v[32:33], s[40:41], 0, v[32:33]
	v_lshl_add_u64 v[48:49], v[98:99], 2, v[32:33]
	s_movk_i32 s4, 0x1000
	v_cmp_gt_i32_e32 vcc, s4, v36
	s_nop 1
	v_cndmask_b32_e32 v39, v38, v102, vcc
	v_and_b32_e32 v39, 1, v39
	v_cmp_eq_u32_e32 vcc, 1, v39
	s_nop 1
	v_cndmask_b32_e64 v39, v171, 0, vcc
	v_add_u32_e32 v39, v103, v39
	ds_read_b128 v[40:43], v86 offset:3264
	ds_read_b128 v[44:47], v39
	s_and_b64 vcc, exec, s[0:1]
	s_waitcnt vmcnt(23) lgkmcnt(0)
	v_pk_fma_f32 v[34:35], v[42:43], v[46:47], v[118:119]
	v_pk_fma_f32 v[32:33], v[40:41], v[44:45], v[116:117]
	global_store_dwordx4 v[48:49], v[32:35], off
	s_cbranch_vccnz .LBB0_730
	ds_read_b128 v[40:43], v39 offset:2048
	v_lshlrev_b64 v[36:37], 10, v[36:37]
	v_lshl_add_u64 v[36:37], v[36:37], 1, s[42:43]
	v_lshl_add_u64 v[36:37], v[98:99], 1, v[36:37]
	s_waitcnt lgkmcnt(0)
	v_pk_mul_f32 v[40:41], v[32:33], v[40:41]
	v_pk_mul_f32 v[32:33], v[32:33], v[32:33]
	v_pk_mul_f32 v[42:43], v[34:35], v[42:43]
	v_pk_mul_f32 v[34:35], v[34:35], v[34:35]
	v_add_f32_e32 v32, v32, v33
	v_add_f32_e32 v32, v34, v32
	v_add_f32_e32 v32, v35, v32
	v_cvt_pk_bf16_f32 v40, v40, v41
	v_cvt_pk_bf16_f32 v41, v42, v43
	v_add_f32_dpp v32, v32, v32 quad_perm:[1,0,3,2] row_mask:0xf bank_mask:0xf bound_ctrl:1
	global_store_dwordx2 v[36:37], v[40:41], off
	s_nop 0
	v_add_f32_dpp v32, v32, v32 quad_perm:[2,3,0,1] row_mask:0xf bank_mask:0xf bound_ctrl:1
	s_nop 1
	v_add_f32_dpp v32, v32, v32 row_half_mirror row_mask:0xf bank_mask:0xf bound_ctrl:1
	s_nop 1
	v_mov_b32_dpp v33, v32 row_mirror row_mask:0xf bank_mask:0xf bound_ctrl:1
	s_and_saveexec_b64 s[4:5], s[36:37]
	s_cbranch_execz .LBB0_729
	v_mov_b32_e32 v75, v129
	v_ashrrev_i32_e32 v97, 31, v96
	v_lshl_add_u64 v[34:35], s[52:53], 0, v[68:69]
	v_lshl_add_u64 v[36:37], v[96:97], 0, v[74:75]
	v_lshl_add_u64 v[34:35], v[36:37], 2, v[34:35]
	v_add_f32_e32 v32, v32, v33
	global_store_dword v[34:35], v32, off offset:128

.LBB0_730:
	v_or_b32_e32 v36, v66, v76
	v_ashrrev_i32_e32 v37, 31, v36
	v_lshlrev_b64 v[32:33], 12, v[36:37]
	v_lshl_add_u64 v[32:33], s[40:41], 0, v[32:33]
	v_lshl_add_u64 v[48:49], v[98:99], 2, v[32:33]
	s_movk_i32 s4, 0x1000
	v_cmp_gt_i32_e32 vcc, s4, v36
	s_nop 1
	v_cndmask_b32_e32 v39, v38, v102, vcc
	v_and_b32_e32 v39, 1, v39
	v_cmp_eq_u32_e32 vcc, 1, v39
	s_nop 1
	v_cndmask_b32_e64 v39, v171, 0, vcc
	v_add_u32_e32 v39, v103, v39
	ds_read_b128 v[40:43], v86 offset:4352
	ds_read_b128 v[44:47], v39
	s_and_b64 vcc, exec, s[0:1]
	s_waitcnt vmcnt(23) lgkmcnt(0)
	v_pk_fma_f32 v[34:35], v[42:43], v[46:47], v[122:123]
	v_pk_fma_f32 v[32:33], v[40:41], v[44:45], v[120:121]
	global_store_dwordx4 v[48:49], v[32:35], off
	s_cbranch_vccnz .LBB0_734
	ds_read_b128 v[40:43], v39 offset:2048
	v_lshlrev_b64 v[36:37], 10, v[36:37]
	v_lshl_add_u64 v[36:37], v[36:37], 1, s[42:43]
	v_lshl_add_u64 v[36:37], v[98:99], 1, v[36:37]
	s_waitcnt lgkmcnt(0)
	v_pk_mul_f32 v[40:41], v[32:33], v[40:41]
	v_pk_mul_f32 v[32:33], v[32:33], v[32:33]
	v_pk_mul_f32 v[42:43], v[34:35], v[42:43]
	v_pk_mul_f32 v[34:35], v[34:35], v[34:35]
	v_add_f32_e32 v32, v32, v33
	v_add_f32_e32 v32, v34, v32
	v_add_f32_e32 v32, v35, v32
	v_cvt_pk_bf16_f32 v40, v40, v41
	v_cvt_pk_bf16_f32 v41, v42, v43
	v_add_f32_dpp v32, v32, v32 quad_perm:[1,0,3,2] row_mask:0xf bank_mask:0xf bound_ctrl:1
	global_store_dwordx2 v[36:37], v[40:41], off
	s_nop 0
	v_add_f32_dpp v32, v32, v32 quad_perm:[2,3,0,1] row_mask:0xf bank_mask:0xf bound_ctrl:1
	s_nop 1
	v_add_f32_dpp v32, v32, v32 row_half_mirror row_mask:0xf bank_mask:0xf bound_ctrl:1
	s_nop 1
	v_mov_b32_dpp v33, v32 row_mirror row_mask:0xf bank_mask:0xf bound_ctrl:1
	s_and_saveexec_b64 s[4:5], s[36:37]
	s_cbranch_execz .LBB0_733
	v_mov_b32_e32 v77, v129
	v_ashrrev_i32_e32 v97, 31, v96
	v_lshl_add_u64 v[34:35], s[52:53], 0, v[68:69]
	v_lshl_add_u64 v[36:37], v[96:97], 0, v[76:77]
	v_lshl_add_u64 v[34:35], v[36:37], 2, v[34:35]
	v_add_f32_e32 v32, v32, v33
	global_store_dword v[34:35], v32, off offset:128

.LBB0_734:
	v_or_b32_e32 v36, v66, v78
	v_ashrrev_i32_e32 v37, 31, v36
	v_lshlrev_b64 v[32:33], 12, v[36:37]
	v_lshl_add_u64 v[32:33], s[40:41], 0, v[32:33]
	v_lshl_add_u64 v[48:49], v[98:99], 2, v[32:33]
	s_movk_i32 s4, 0x1000
	v_cmp_gt_i32_e32 vcc, s4, v36
	s_nop 1
	v_cndmask_b32_e32 v39, v38, v102, vcc
	v_and_b32_e32 v39, 1, v39
	v_cmp_eq_u32_e32 vcc, 1, v39
	s_nop 1
	v_cndmask_b32_e64 v39, v171, 0, vcc
	v_add_u32_e32 v39, v103, v39
	ds_read_b128 v[40:43], v86 offset:5440
	ds_read_b128 v[44:47], v39
	s_and_b64 vcc, exec, s[0:1]
	s_waitcnt vmcnt(23) lgkmcnt(0)
	v_pk_fma_f32 v[34:35], v[42:43], v[46:47], v[126:127]
	v_pk_fma_f32 v[32:33], v[40:41], v[44:45], v[124:125]
	global_store_dwordx4 v[48:49], v[32:35], off
	s_cbranch_vccnz .LBB0_738
	ds_read_b128 v[40:43], v39 offset:2048
	v_lshlrev_b64 v[36:37], 10, v[36:37]
	v_lshl_add_u64 v[36:37], v[36:37], 1, s[42:43]
	v_lshl_add_u64 v[36:37], v[98:99], 1, v[36:37]
	s_waitcnt lgkmcnt(0)
	v_pk_mul_f32 v[40:41], v[32:33], v[40:41]
	v_pk_mul_f32 v[32:33], v[32:33], v[32:33]
	v_pk_mul_f32 v[42:43], v[34:35], v[42:43]
	v_pk_mul_f32 v[34:35], v[34:35], v[34:35]
	v_add_f32_e32 v32, v32, v33
	v_add_f32_e32 v32, v34, v32
	v_add_f32_e32 v32, v35, v32
	v_cvt_pk_bf16_f32 v40, v40, v41
	v_cvt_pk_bf16_f32 v41, v42, v43
	v_add_f32_dpp v32, v32, v32 quad_perm:[1,0,3,2] row_mask:0xf bank_mask:0xf bound_ctrl:1
	global_store_dwordx2 v[36:37], v[40:41], off
	s_nop 0
	v_add_f32_dpp v32, v32, v32 quad_perm:[2,3,0,1] row_mask:0xf bank_mask:0xf bound_ctrl:1
	s_nop 1
	v_add_f32_dpp v32, v32, v32 row_half_mirror row_mask:0xf bank_mask:0xf bound_ctrl:1
	s_nop 1
	v_mov_b32_dpp v33, v32 row_mirror row_mask:0xf bank_mask:0xf bound_ctrl:1
	s_and_saveexec_b64 s[4:5], s[36:37]
	s_cbranch_execz .LBB0_737
	v_mov_b32_e32 v79, v129
	v_ashrrev_i32_e32 v97, 31, v96
	v_lshl_add_u64 v[34:35], s[52:53], 0, v[68:69]
	v_lshl_add_u64 v[36:37], v[96:97], 0, v[78:79]
	v_lshl_add_u64 v[34:35], v[36:37], 2, v[34:35]
	v_add_f32_e32 v32, v32, v33
	global_store_dword v[34:35], v32, off offset:128

.LBB0_738:
	v_or_b32_e32 v36, v66, v80
	v_ashrrev_i32_e32 v37, 31, v36
	v_lshlrev_b64 v[32:33], 12, v[36:37]
	v_lshl_add_u64 v[32:33], s[40:41], 0, v[32:33]
	v_lshl_add_u64 v[48:49], v[98:99], 2, v[32:33]
	s_movk_i32 s4, 0x1000
	v_cmp_gt_i32_e32 vcc, s4, v36
	s_nop 1
	v_cndmask_b32_e32 v39, v38, v102, vcc
	v_and_b32_e32 v39, 1, v39
	v_cmp_eq_u32_e32 vcc, 1, v39
	s_nop 1
	v_cndmask_b32_e64 v39, v171, 0, vcc
	v_add_u32_e32 v39, v103, v39
	ds_read_b128 v[40:43], v86 offset:6528
	ds_read_b128 v[44:47], v39
	s_and_b64 vcc, exec, s[0:1]
	s_waitcnt vmcnt(23) lgkmcnt(0)
	v_pk_fma_f32 v[34:35], v[42:43], v[46:47], v[132:133]
	v_pk_fma_f32 v[32:33], v[40:41], v[44:45], v[130:131]
	global_store_dwordx4 v[48:49], v[32:35], off
	s_cbranch_vccnz .LBB0_742
	ds_read_b128 v[40:43], v39 offset:2048
	v_lshlrev_b64 v[36:37], 10, v[36:37]
	v_lshl_add_u64 v[36:37], v[36:37], 1, s[42:43]
	v_lshl_add_u64 v[36:37], v[98:99], 1, v[36:37]
	s_waitcnt lgkmcnt(0)
	v_pk_mul_f32 v[40:41], v[32:33], v[40:41]
	v_pk_mul_f32 v[32:33], v[32:33], v[32:33]
	v_pk_mul_f32 v[42:43], v[34:35], v[42:43]
	v_pk_mul_f32 v[34:35], v[34:35], v[34:35]
	v_add_f32_e32 v32, v32, v33
	v_add_f32_e32 v32, v34, v32
	v_add_f32_e32 v32, v35, v32
	v_cvt_pk_bf16_f32 v40, v40, v41
	v_cvt_pk_bf16_f32 v41, v42, v43
	v_add_f32_dpp v32, v32, v32 quad_perm:[1,0,3,2] row_mask:0xf bank_mask:0xf bound_ctrl:1
	global_store_dwordx2 v[36:37], v[40:41], off
	s_nop 0
	v_add_f32_dpp v32, v32, v32 quad_perm:[2,3,0,1] row_mask:0xf bank_mask:0xf bound_ctrl:1
	s_nop 1
	v_add_f32_dpp v32, v32, v32 row_half_mirror row_mask:0xf bank_mask:0xf bound_ctrl:1
	s_nop 1
	v_mov_b32_dpp v33, v32 row_mirror row_mask:0xf bank_mask:0xf bound_ctrl:1
	s_and_saveexec_b64 s[4:5], s[36:37]
	s_cbranch_execz .LBB0_741
	v_mov_b32_e32 v81, v129
	v_ashrrev_i32_e32 v97, 31, v96
	v_lshl_add_u64 v[34:35], s[52:53], 0, v[68:69]
	v_lshl_add_u64 v[36:37], v[96:97], 0, v[80:81]
	v_lshl_add_u64 v[34:35], v[36:37], 2, v[34:35]
	v_add_f32_e32 v32, v32, v33
	global_store_dword v[34:35], v32, off offset:128

.LBB0_742:
	v_or_b32_e32 v36, v66, v82
	v_ashrrev_i32_e32 v37, 31, v36
	v_lshlrev_b64 v[32:33], 12, v[36:37]
	v_lshl_add_u64 v[32:33], s[40:41], 0, v[32:33]
	v_lshl_add_u64 v[48:49], v[98:99], 2, v[32:33]
	s_movk_i32 s4, 0x1000
	v_cmp_gt_i32_e32 vcc, s4, v36
	s_nop 1
	v_cndmask_b32_e32 v38, v38, v102, vcc
	v_and_b32_e32 v38, 1, v38
	v_cmp_eq_u32_e32 vcc, 1, v38
	s_nop 1
	v_cndmask_b32_e64 v38, v171, 0, vcc
	v_add_u32_e32 v38, v103, v38
	ds_read_b128 v[40:43], v86 offset:7616
	ds_read_b128 v[44:47], v38
	s_and_b64 vcc, exec, s[0:1]
	s_waitcnt vmcnt(23) lgkmcnt(0)
	v_pk_fma_f32 v[34:35], v[42:43], v[46:47], v[136:137]
	v_pk_fma_f32 v[32:33], v[40:41], v[44:45], v[134:135]
	global_store_dwordx4 v[48:49], v[32:35], off
	s_cbranch_vccnz .LBB0_746
	ds_read_b128 v[38:41], v38 offset:2048
	v_lshlrev_b64 v[36:37], 10, v[36:37]
	v_lshl_add_u64 v[36:37], v[36:37], 1, s[42:43]
	v_lshl_add_u64 v[36:37], v[98:99], 1, v[36:37]
	s_waitcnt lgkmcnt(0)
	v_pk_mul_f32 v[38:39], v[32:33], v[38:39]
	v_pk_mul_f32 v[32:33], v[32:33], v[32:33]
	v_pk_mul_f32 v[40:41], v[34:35], v[40:41]
	v_pk_mul_f32 v[34:35], v[34:35], v[34:35]
	v_add_f32_e32 v32, v32, v33
	v_add_f32_e32 v32, v34, v32
	v_add_f32_e32 v32, v35, v32
	v_cvt_pk_bf16_f32 v38, v38, v39
	v_cvt_pk_bf16_f32 v39, v40, v41
	v_add_f32_dpp v32, v32, v32 quad_perm:[1,0,3,2] row_mask:0xf bank_mask:0xf bound_ctrl:1
	global_store_dwordx2 v[36:37], v[38:39], off
	s_nop 0
	v_add_f32_dpp v32, v32, v32 quad_perm:[2,3,0,1] row_mask:0xf bank_mask:0xf bound_ctrl:1
	s_nop 1
	v_add_f32_dpp v32, v32, v32 row_half_mirror row_mask:0xf bank_mask:0xf bound_ctrl:1
	s_nop 1
	v_mov_b32_dpp v33, v32 row_mirror row_mask:0xf bank_mask:0xf bound_ctrl:1
	s_and_saveexec_b64 s[4:5], s[36:37]
	s_cbranch_execz .LBB0_745
	v_mov_b32_e32 v83, v129
	v_ashrrev_i32_e32 v97, 31, v96
	v_lshl_add_u64 v[34:35], s[52:53], 0, v[68:69]
	v_lshl_add_u64 v[36:37], v[96:97], 0, v[82:83]
	v_lshl_add_u64 v[34:35], v[36:37], 2, v[34:35]
	v_add_f32_e32 v32, v32, v33
	global_store_dword v[34:35], v32, off offset:128

.LBB0_746:
	s_nop 0
	v_add_u32_e32 v34, 64, v96
	v_or_b32_e32 v32, v34, v128
	v_ashrrev_i32_e32 v33, 31, v32
	v_lshlrev_b64 v[36:37], 12, v[32:33]
	v_lshl_add_u64 v[36:37], s[40:41], 0, v[36:37]
	v_lshl_add_u64 v[40:41], v[98:99], 2, v[36:37]
	ds_write_b128 v104, v[0:3]
	ds_write_b128 v104, v[4:7] offset:32
	ds_write_b128 v104, v[8:11] offset:64
	ds_write_b128 v104, v[12:15] offset:96
	ds_write_b128 v104, v[16:19] offset:128
	ds_write_b128 v104, v[20:23] offset:160
	ds_write_b128 v104, v[24:27] offset:192
	ds_write_b128 v104, v[28:31] offset:224
	v_add_u32_e32 v0, 0xfffff040, v96
	v_xor_b32_e32 v0, s7, v0
	s_movk_i32 s4, 0x400
	v_cmp_gt_u32_e32 vcc, s4, v0
	s_and_b64 s[2:3], s[2:3], vcc
	v_cndmask_b32_e64 v6, 0, 1, s[2:3]
	s_movk_i32 s2, 0x1000
	v_cmp_gt_i32_e32 vcc, s2, v32
	s_nop 1
	v_cndmask_b32_e32 v0, v6, v102, vcc
	v_and_b32_e32 v0, 1, v0
	v_cmp_eq_u32_e32 vcc, 1, v0
	s_nop 1
	v_cndmask_b32_e64 v0, v171, 0, vcc
	v_add_u32_e32 v4, v103, v0
	ds_read_b128 v[0:3], v86
	ds_read_b128 v[8:11], v4
	s_and_b64 vcc, exec, s[0:1]
	s_waitcnt vmcnt(15) lgkmcnt(0)
	v_pk_fma_f32 v[2:3], v[2:3], v[10:11], v[200:201]
	v_pk_fma_f32 v[0:1], v[0:1], v[8:9], v[198:199]
	global_store_dwordx4 v[40:41], v[0:3], off
	s_cbranch_vccnz .LBB0_750
	ds_read_b128 v[8:11], v4 offset:2048
	v_lshlrev_b64 v[4:5], 10, v[32:33]
	v_lshl_add_u64 v[4:5], v[4:5], 1, s[42:43]
	v_lshl_add_u64 v[4:5], v[98:99], 1, v[4:5]
	s_waitcnt lgkmcnt(0)
	v_pk_mul_f32 v[8:9], v[0:1], v[8:9]
	v_pk_mul_f32 v[0:1], v[0:1], v[0:1]
	v_pk_mul_f32 v[10:11], v[2:3], v[10:11]
	v_pk_mul_f32 v[2:3], v[2:3], v[2:3]
	v_add_f32_e32 v0, v0, v1
	v_add_f32_e32 v0, v2, v0
	v_add_f32_e32 v0, v3, v0
	v_cvt_pk_bf16_f32 v8, v8, v9
	v_cvt_pk_bf16_f32 v9, v10, v11
	v_add_f32_dpp v0, v0, v0 quad_perm:[1,0,3,2] row_mask:0xf bank_mask:0xf bound_ctrl:1
	global_store_dwordx2 v[4:5], v[8:9], off
	s_nop 0
	v_add_f32_dpp v0, v0, v0 quad_perm:[2,3,0,1] row_mask:0xf bank_mask:0xf bound_ctrl:1
	s_nop 1
	v_add_f32_dpp v0, v0, v0 row_half_mirror row_mask:0xf bank_mask:0xf bound_ctrl:1
	s_nop 1
	v_mov_b32_dpp v1, v0 row_mirror row_mask:0xf bank_mask:0xf bound_ctrl:1
	s_and_saveexec_b64 s[2:3], s[36:37]
	s_cbranch_execz .LBB0_749
	v_ashrrev_i32_e32 v97, 31, v96
	v_lshl_add_u64 v[2:3], s[52:53], 0, v[68:69]
	v_lshl_add_u64 v[4:5], v[96:97], 0, v[128:129]
	v_lshl_add_u64 v[2:3], v[4:5], 2, v[2:3]
	v_add_f32_e32 v0, v0, v1
	global_store_dword v[2:3], v0, off offset:256

.LBB0_750:
	v_or_b32_e32 v4, v34, v70
	v_ashrrev_i32_e32 v5, 31, v4
	v_lshlrev_b64 v[0:1], 12, v[4:5]
	v_lshl_add_u64 v[0:1], s[40:41], 0, v[0:1]
	v_lshl_add_u64 v[16:17], v[98:99], 2, v[0:1]
	s_movk_i32 s2, 0x1000
	v_cmp_gt_i32_e32 vcc, s2, v4
	s_nop 1
	v_cndmask_b32_e32 v7, v6, v102, vcc
	v_and_b32_e32 v7, 1, v7
	v_cmp_eq_u32_e32 vcc, 1, v7
	s_nop 1
	v_cndmask_b32_e64 v7, v171, 0, vcc
	v_add_u32_e32 v7, v103, v7
	ds_read_b128 v[8:11], v86 offset:1088
	ds_read_b128 v[12:15], v7
	s_and_b64 vcc, exec, s[0:1]
	s_waitcnt vmcnt(15) lgkmcnt(0)
	v_pk_fma_f32 v[2:3], v[10:11], v[14:15], v[204:205]
	v_pk_fma_f32 v[0:1], v[8:9], v[12:13], v[202:203]
	global_store_dwordx4 v[16:17], v[0:3], off
	s_cbranch_vccnz .LBB0_754
	ds_read_b128 v[8:11], v7 offset:2048
	v_lshlrev_b64 v[4:5], 10, v[4:5]
	v_lshl_add_u64 v[4:5], v[4:5], 1, s[42:43]
	v_lshl_add_u64 v[4:5], v[98:99], 1, v[4:5]
	s_waitcnt lgkmcnt(0)
	v_pk_mul_f32 v[8:9], v[0:1], v[8:9]
	v_pk_mul_f32 v[0:1], v[0:1], v[0:1]
	v_pk_mul_f32 v[10:11], v[2:3], v[10:11]
	v_pk_mul_f32 v[2:3], v[2:3], v[2:3]
	v_add_f32_e32 v0, v0, v1
	v_add_f32_e32 v0, v2, v0
	v_add_f32_e32 v0, v3, v0
	v_cvt_pk_bf16_f32 v8, v8, v9
	v_cvt_pk_bf16_f32 v9, v10, v11
	v_add_f32_dpp v0, v0, v0 quad_perm:[1,0,3,2] row_mask:0xf bank_mask:0xf bound_ctrl:1
	global_store_dwordx2 v[4:5], v[8:9], off
	s_nop 0
	v_add_f32_dpp v0, v0, v0 quad_perm:[2,3,0,1] row_mask:0xf bank_mask:0xf bound_ctrl:1
	s_nop 1
	v_add_f32_dpp v0, v0, v0 row_half_mirror row_mask:0xf bank_mask:0xf bound_ctrl:1
	s_nop 1
	v_mov_b32_dpp v1, v0 row_mirror row_mask:0xf bank_mask:0xf bound_ctrl:1
	s_and_saveexec_b64 s[2:3], s[36:37]
	s_cbranch_execz .LBB0_753
	v_mov_b32_e32 v71, v129
	v_ashrrev_i32_e32 v97, 31, v96
	v_lshl_add_u64 v[2:3], s[52:53], 0, v[68:69]
	v_lshl_add_u64 v[4:5], v[96:97], 0, v[70:71]
	v_lshl_add_u64 v[2:3], v[4:5], 2, v[2:3]
	v_add_f32_e32 v0, v0, v1
	global_store_dword v[2:3], v0, off offset:256

.LBB0_754:
	v_or_b32_e32 v4, v34, v72
	v_ashrrev_i32_e32 v5, 31, v4
	v_lshlrev_b64 v[0:1], 12, v[4:5]
	v_lshl_add_u64 v[0:1], s[40:41], 0, v[0:1]
	v_lshl_add_u64 v[16:17], v[98:99], 2, v[0:1]
	s_movk_i32 s2, 0x1000
	v_cmp_gt_i32_e32 vcc, s2, v4
	s_nop 1
	v_cndmask_b32_e32 v7, v6, v102, vcc
	v_and_b32_e32 v7, 1, v7
	v_cmp_eq_u32_e32 vcc, 1, v7
	s_nop 1
	v_cndmask_b32_e64 v7, v171, 0, vcc
	v_add_u32_e32 v7, v103, v7
	ds_read_b128 v[8:11], v86 offset:2176
	ds_read_b128 v[12:15], v7
	s_and_b64 vcc, exec, s[0:1]
	s_waitcnt vmcnt(15) lgkmcnt(0)
	v_pk_fma_f32 v[2:3], v[10:11], v[14:15], v[208:209]
	v_pk_fma_f32 v[0:1], v[8:9], v[12:13], v[206:207]
	global_store_dwordx4 v[16:17], v[0:3], off
	s_cbranch_vccnz .LBB0_758
	ds_read_b128 v[8:11], v7 offset:2048
	v_lshlrev_b64 v[4:5], 10, v[4:5]
	v_lshl_add_u64 v[4:5], v[4:5], 1, s[42:43]
	v_lshl_add_u64 v[4:5], v[98:99], 1, v[4:5]
	s_waitcnt lgkmcnt(0)
	v_pk_mul_f32 v[8:9], v[0:1], v[8:9]
	v_pk_mul_f32 v[0:1], v[0:1], v[0:1]
	v_pk_mul_f32 v[10:11], v[2:3], v[10:11]
	v_pk_mul_f32 v[2:3], v[2:3], v[2:3]
	v_add_f32_e32 v0, v0, v1
	v_add_f32_e32 v0, v2, v0
	v_add_f32_e32 v0, v3, v0
	v_cvt_pk_bf16_f32 v8, v8, v9
	v_cvt_pk_bf16_f32 v9, v10, v11
	v_add_f32_dpp v0, v0, v0 quad_perm:[1,0,3,2] row_mask:0xf bank_mask:0xf bound_ctrl:1
	global_store_dwordx2 v[4:5], v[8:9], off
	s_nop 0
	v_add_f32_dpp v0, v0, v0 quad_perm:[2,3,0,1] row_mask:0xf bank_mask:0xf bound_ctrl:1
	s_nop 1
	v_add_f32_dpp v0, v0, v0 row_half_mirror row_mask:0xf bank_mask:0xf bound_ctrl:1
	s_nop 1
	v_mov_b32_dpp v1, v0 row_mirror row_mask:0xf bank_mask:0xf bound_ctrl:1
	s_and_saveexec_b64 s[2:3], s[36:37]
	s_cbranch_execz .LBB0_757
	v_mov_b32_e32 v73, v129
	v_ashrrev_i32_e32 v97, 31, v96
	v_lshl_add_u64 v[2:3], s[52:53], 0, v[68:69]
	v_lshl_add_u64 v[4:5], v[96:97], 0, v[72:73]
	v_lshl_add_u64 v[2:3], v[4:5], 2, v[2:3]
	v_add_f32_e32 v0, v0, v1
	global_store_dword v[2:3], v0, off offset:256

.LBB0_758:
	v_or_b32_e32 v4, v34, v74
	v_ashrrev_i32_e32 v5, 31, v4
	v_lshlrev_b64 v[0:1], 12, v[4:5]
	v_lshl_add_u64 v[0:1], s[40:41], 0, v[0:1]
	v_lshl_add_u64 v[16:17], v[98:99], 2, v[0:1]
	s_movk_i32 s2, 0x1000
	v_cmp_gt_i32_e32 vcc, s2, v4
	s_nop 1
	v_cndmask_b32_e32 v7, v6, v102, vcc
	v_and_b32_e32 v7, 1, v7
	v_cmp_eq_u32_e32 vcc, 1, v7
	s_nop 1
	v_cndmask_b32_e64 v7, v171, 0, vcc
	v_add_u32_e32 v7, v103, v7
	ds_read_b128 v[8:11], v86 offset:3264
	ds_read_b128 v[12:15], v7
	s_and_b64 vcc, exec, s[0:1]
	s_waitcnt vmcnt(15) lgkmcnt(0)
	v_pk_fma_f32 v[2:3], v[10:11], v[14:15], v[212:213]
	v_pk_fma_f32 v[0:1], v[8:9], v[12:13], v[210:211]
	global_store_dwordx4 v[16:17], v[0:3], off
	s_cbranch_vccnz .LBB0_762
	ds_read_b128 v[8:11], v7 offset:2048
	v_lshlrev_b64 v[4:5], 10, v[4:5]
	v_lshl_add_u64 v[4:5], v[4:5], 1, s[42:43]
	v_lshl_add_u64 v[4:5], v[98:99], 1, v[4:5]
	s_waitcnt lgkmcnt(0)
	v_pk_mul_f32 v[8:9], v[0:1], v[8:9]
	v_pk_mul_f32 v[0:1], v[0:1], v[0:1]
	v_pk_mul_f32 v[10:11], v[2:3], v[10:11]
	v_pk_mul_f32 v[2:3], v[2:3], v[2:3]
	v_add_f32_e32 v0, v0, v1
	v_add_f32_e32 v0, v2, v0
	v_add_f32_e32 v0, v3, v0
	v_cvt_pk_bf16_f32 v8, v8, v9
	v_cvt_pk_bf16_f32 v9, v10, v11
	v_add_f32_dpp v0, v0, v0 quad_perm:[1,0,3,2] row_mask:0xf bank_mask:0xf bound_ctrl:1
	global_store_dwordx2 v[4:5], v[8:9], off
	s_nop 0
	v_add_f32_dpp v0, v0, v0 quad_perm:[2,3,0,1] row_mask:0xf bank_mask:0xf bound_ctrl:1
	s_nop 1
	v_add_f32_dpp v0, v0, v0 row_half_mirror row_mask:0xf bank_mask:0xf bound_ctrl:1
	s_nop 1
	v_mov_b32_dpp v1, v0 row_mirror row_mask:0xf bank_mask:0xf bound_ctrl:1
	s_and_saveexec_b64 s[2:3], s[36:37]
	s_cbranch_execz .LBB0_761
	v_mov_b32_e32 v75, v129
	v_ashrrev_i32_e32 v97, 31, v96
	v_lshl_add_u64 v[2:3], s[52:53], 0, v[68:69]
	v_lshl_add_u64 v[4:5], v[96:97], 0, v[74:75]
	v_lshl_add_u64 v[2:3], v[4:5], 2, v[2:3]
	v_add_f32_e32 v0, v0, v1
	global_store_dword v[2:3], v0, off offset:256

.LBB0_762:
	v_or_b32_e32 v4, v34, v76
	v_ashrrev_i32_e32 v5, 31, v4
	v_lshlrev_b64 v[0:1], 12, v[4:5]
	v_lshl_add_u64 v[0:1], s[40:41], 0, v[0:1]
	v_lshl_add_u64 v[16:17], v[98:99], 2, v[0:1]
	s_movk_i32 s2, 0x1000
	v_cmp_gt_i32_e32 vcc, s2, v4
	s_nop 1
	v_cndmask_b32_e32 v7, v6, v102, vcc
	v_and_b32_e32 v7, 1, v7
	v_cmp_eq_u32_e32 vcc, 1, v7
	s_nop 1
	v_cndmask_b32_e64 v7, v171, 0, vcc
	v_add_u32_e32 v7, v103, v7
	ds_read_b128 v[8:11], v86 offset:4352
	ds_read_b128 v[12:15], v7
	s_and_b64 vcc, exec, s[0:1]
	s_waitcnt vmcnt(15) lgkmcnt(0)
	v_pk_fma_f32 v[2:3], v[10:11], v[14:15], v[216:217]
	v_pk_fma_f32 v[0:1], v[8:9], v[12:13], v[214:215]
	global_store_dwordx4 v[16:17], v[0:3], off
	s_cbranch_vccnz .LBB0_766
	ds_read_b128 v[8:11], v7 offset:2048
	v_lshlrev_b64 v[4:5], 10, v[4:5]
	v_lshl_add_u64 v[4:5], v[4:5], 1, s[42:43]
	v_lshl_add_u64 v[4:5], v[98:99], 1, v[4:5]
	s_waitcnt lgkmcnt(0)
	v_pk_mul_f32 v[8:9], v[0:1], v[8:9]
	v_pk_mul_f32 v[0:1], v[0:1], v[0:1]
	v_pk_mul_f32 v[10:11], v[2:3], v[10:11]
	v_pk_mul_f32 v[2:3], v[2:3], v[2:3]
	v_add_f32_e32 v0, v0, v1
	v_add_f32_e32 v0, v2, v0
	v_add_f32_e32 v0, v3, v0
	v_cvt_pk_bf16_f32 v8, v8, v9
	v_cvt_pk_bf16_f32 v9, v10, v11
	v_add_f32_dpp v0, v0, v0 quad_perm:[1,0,3,2] row_mask:0xf bank_mask:0xf bound_ctrl:1
	global_store_dwordx2 v[4:5], v[8:9], off
	s_nop 0
	v_add_f32_dpp v0, v0, v0 quad_perm:[2,3,0,1] row_mask:0xf bank_mask:0xf bound_ctrl:1
	s_nop 1
	v_add_f32_dpp v0, v0, v0 row_half_mirror row_mask:0xf bank_mask:0xf bound_ctrl:1
	s_nop 1
	v_mov_b32_dpp v1, v0 row_mirror row_mask:0xf bank_mask:0xf bound_ctrl:1
	s_and_saveexec_b64 s[2:3], s[36:37]
	s_cbranch_execz .LBB0_765
	v_mov_b32_e32 v77, v129
	v_ashrrev_i32_e32 v97, 31, v96
	v_lshl_add_u64 v[2:3], s[52:53], 0, v[68:69]
	v_lshl_add_u64 v[4:5], v[96:97], 0, v[76:77]
	v_lshl_add_u64 v[2:3], v[4:5], 2, v[2:3]
	v_add_f32_e32 v0, v0, v1
	global_store_dword v[2:3], v0, off offset:256

.LBB0_766:
	v_or_b32_e32 v4, v34, v78
	v_ashrrev_i32_e32 v5, 31, v4
	v_lshlrev_b64 v[0:1], 12, v[4:5]
	v_lshl_add_u64 v[0:1], s[40:41], 0, v[0:1]
	v_lshl_add_u64 v[16:17], v[98:99], 2, v[0:1]
	s_movk_i32 s2, 0x1000
	v_cmp_gt_i32_e32 vcc, s2, v4
	s_nop 1
	v_cndmask_b32_e32 v7, v6, v102, vcc
	v_and_b32_e32 v7, 1, v7
	v_cmp_eq_u32_e32 vcc, 1, v7
	s_nop 1
	v_cndmask_b32_e64 v7, v171, 0, vcc
	v_add_u32_e32 v7, v103, v7
	ds_read_b128 v[8:11], v86 offset:5440
	ds_read_b128 v[12:15], v7
	s_and_b64 vcc, exec, s[0:1]
	s_waitcnt vmcnt(15) lgkmcnt(0)
	v_pk_fma_f32 v[2:3], v[10:11], v[14:15], v[220:221]
	v_pk_fma_f32 v[0:1], v[8:9], v[12:13], v[218:219]
	global_store_dwordx4 v[16:17], v[0:3], off
	s_cbranch_vccnz .LBB0_770
	ds_read_b128 v[8:11], v7 offset:2048
	v_lshlrev_b64 v[4:5], 10, v[4:5]
	v_lshl_add_u64 v[4:5], v[4:5], 1, s[42:43]
	v_lshl_add_u64 v[4:5], v[98:99], 1, v[4:5]
	s_waitcnt lgkmcnt(0)
	v_pk_mul_f32 v[8:9], v[0:1], v[8:9]
	v_pk_mul_f32 v[0:1], v[0:1], v[0:1]
	v_pk_mul_f32 v[10:11], v[2:3], v[10:11]
	v_pk_mul_f32 v[2:3], v[2:3], v[2:3]
	v_add_f32_e32 v0, v0, v1
	v_add_f32_e32 v0, v2, v0
	v_add_f32_e32 v0, v3, v0
	v_cvt_pk_bf16_f32 v8, v8, v9
	v_cvt_pk_bf16_f32 v9, v10, v11
	v_add_f32_dpp v0, v0, v0 quad_perm:[1,0,3,2] row_mask:0xf bank_mask:0xf bound_ctrl:1
	global_store_dwordx2 v[4:5], v[8:9], off
	s_nop 0
	v_add_f32_dpp v0, v0, v0 quad_perm:[2,3,0,1] row_mask:0xf bank_mask:0xf bound_ctrl:1
	s_nop 1
	v_add_f32_dpp v0, v0, v0 row_half_mirror row_mask:0xf bank_mask:0xf bound_ctrl:1
	s_nop 1
	v_mov_b32_dpp v1, v0 row_mirror row_mask:0xf bank_mask:0xf bound_ctrl:1
	s_and_saveexec_b64 s[2:3], s[36:37]
	s_cbranch_execz .LBB0_769
	v_mov_b32_e32 v79, v129
	v_ashrrev_i32_e32 v97, 31, v96
	v_lshl_add_u64 v[2:3], s[52:53], 0, v[68:69]
	v_lshl_add_u64 v[4:5], v[96:97], 0, v[78:79]
	v_lshl_add_u64 v[2:3], v[4:5], 2, v[2:3]
	v_add_f32_e32 v0, v0, v1
	global_store_dword v[2:3], v0, off offset:256

.LBB0_770:
	v_or_b32_e32 v4, v34, v80
	v_ashrrev_i32_e32 v5, 31, v4
	v_lshlrev_b64 v[0:1], 12, v[4:5]
	v_lshl_add_u64 v[0:1], s[40:41], 0, v[0:1]
	v_lshl_add_u64 v[16:17], v[98:99], 2, v[0:1]
	s_movk_i32 s2, 0x1000
	v_cmp_gt_i32_e32 vcc, s2, v4
	s_nop 1
	v_cndmask_b32_e32 v7, v6, v102, vcc
	v_and_b32_e32 v7, 1, v7
	v_cmp_eq_u32_e32 vcc, 1, v7
	s_nop 1
	v_cndmask_b32_e64 v7, v171, 0, vcc
	v_add_u32_e32 v7, v103, v7
	ds_read_b128 v[8:11], v86 offset:6528
	ds_read_b128 v[12:15], v7
	s_and_b64 vcc, exec, s[0:1]
	s_waitcnt vmcnt(15) lgkmcnt(0)
	v_pk_fma_f32 v[2:3], v[10:11], v[14:15], v[224:225]
	v_pk_fma_f32 v[0:1], v[8:9], v[12:13], v[222:223]
	global_store_dwordx4 v[16:17], v[0:3], off
	s_cbranch_vccnz .LBB0_774
	ds_read_b128 v[8:11], v7 offset:2048
	v_lshlrev_b64 v[4:5], 10, v[4:5]
	v_lshl_add_u64 v[4:5], v[4:5], 1, s[42:43]
	v_lshl_add_u64 v[4:5], v[98:99], 1, v[4:5]
	s_waitcnt lgkmcnt(0)
	v_pk_mul_f32 v[8:9], v[0:1], v[8:9]
	v_pk_mul_f32 v[0:1], v[0:1], v[0:1]
	v_pk_mul_f32 v[10:11], v[2:3], v[10:11]
	v_pk_mul_f32 v[2:3], v[2:3], v[2:3]
	v_add_f32_e32 v0, v0, v1
	v_add_f32_e32 v0, v2, v0
	v_add_f32_e32 v0, v3, v0
	v_cvt_pk_bf16_f32 v8, v8, v9
	v_cvt_pk_bf16_f32 v9, v10, v11
	v_add_f32_dpp v0, v0, v0 quad_perm:[1,0,3,2] row_mask:0xf bank_mask:0xf bound_ctrl:1
	global_store_dwordx2 v[4:5], v[8:9], off
	s_nop 0
	v_add_f32_dpp v0, v0, v0 quad_perm:[2,3,0,1] row_mask:0xf bank_mask:0xf bound_ctrl:1
	s_nop 1
	v_add_f32_dpp v0, v0, v0 row_half_mirror row_mask:0xf bank_mask:0xf bound_ctrl:1
	s_nop 1
	v_mov_b32_dpp v1, v0 row_mirror row_mask:0xf bank_mask:0xf bound_ctrl:1
	s_and_saveexec_b64 s[2:3], s[36:37]
	s_cbranch_execz .LBB0_773
	v_mov_b32_e32 v81, v129
	v_ashrrev_i32_e32 v97, 31, v96
	v_lshl_add_u64 v[2:3], s[52:53], 0, v[68:69]
	v_lshl_add_u64 v[4:5], v[96:97], 0, v[80:81]
	v_lshl_add_u64 v[2:3], v[4:5], 2, v[2:3]
	v_add_f32_e32 v0, v0, v1
	global_store_dword v[2:3], v0, off offset:256

.LBB0_774:
	v_or_b32_e32 v4, v34, v82
	v_ashrrev_i32_e32 v5, 31, v4
	v_lshlrev_b64 v[0:1], 12, v[4:5]
	v_lshl_add_u64 v[0:1], s[40:41], 0, v[0:1]
	v_lshl_add_u64 v[16:17], v[98:99], 2, v[0:1]
	s_movk_i32 s2, 0x1000
	v_cmp_gt_i32_e32 vcc, s2, v4
	s_nop 1
	v_cndmask_b32_e32 v6, v6, v102, vcc
	v_and_b32_e32 v6, 1, v6
	v_cmp_eq_u32_e32 vcc, 1, v6
	s_nop 1
	v_cndmask_b32_e64 v6, v171, 0, vcc
	v_add_u32_e32 v6, v103, v6
	ds_read_b128 v[8:11], v86 offset:7616
	ds_read_b128 v[12:15], v6
	s_and_b64 vcc, exec, s[0:1]
	s_waitcnt vmcnt(15) lgkmcnt(0)
	v_pk_fma_f32 v[2:3], v[10:11], v[14:15], v[228:229]
	v_pk_fma_f32 v[0:1], v[8:9], v[12:13], v[226:227]
	global_store_dwordx4 v[16:17], v[0:3], off
	s_cbranch_vccnz .LBB0_677
	ds_read_b128 v[6:9], v6 offset:2048
	v_lshlrev_b64 v[4:5], 10, v[4:5]
	v_lshl_add_u64 v[4:5], v[4:5], 1, s[42:43]
	v_lshl_add_u64 v[4:5], v[98:99], 1, v[4:5]
	s_waitcnt lgkmcnt(0)
	v_pk_mul_f32 v[6:7], v[0:1], v[6:7]
	v_pk_mul_f32 v[0:1], v[0:1], v[0:1]
	v_pk_mul_f32 v[8:9], v[2:3], v[8:9]
	v_pk_mul_f32 v[2:3], v[2:3], v[2:3]
	v_add_f32_e32 v0, v0, v1
	v_add_f32_e32 v0, v2, v0
	v_add_f32_e32 v0, v3, v0
	v_cvt_pk_bf16_f32 v6, v6, v7
	v_cvt_pk_bf16_f32 v7, v8, v9
	v_add_f32_dpp v0, v0, v0 quad_perm:[1,0,3,2] row_mask:0xf bank_mask:0xf bound_ctrl:1
	global_store_dwordx2 v[4:5], v[6:7], off
	s_nop 0
	v_add_f32_dpp v0, v0, v0 quad_perm:[2,3,0,1] row_mask:0xf bank_mask:0xf bound_ctrl:1
	s_nop 1
	v_add_f32_dpp v0, v0, v0 row_half_mirror row_mask:0xf bank_mask:0xf bound_ctrl:1
	s_nop 1
	v_mov_b32_dpp v1, v0 row_mirror row_mask:0xf bank_mask:0xf bound_ctrl:1
	s_and_saveexec_b64 s[0:1], s[36:37]
	s_cbranch_execz .LBB0_676
	v_mov_b32_e32 v83, v129
	v_ashrrev_i32_e32 v97, 31, v96
	v_lshl_add_u64 v[2:3], s[52:53], 0, v[68:69]
	v_lshl_add_u64 v[4:5], v[96:97], 0, v[82:83]
	v_lshl_add_u64 v[2:3], v[4:5], 2, v[2:3]
	v_add_f32_e32 v0, v0, v1
	global_store_dword v[2:3], v0, off offset:256
	s_branch .LBB0_676

.LBB0_1223:
	s_add_i32 s9, s7, 1
	s_bitcmp1_b32 s9, 0
	s_cselect_b32 s10, 0xe000, 0
	v_add_u32_e32 v115, s10, v109
	v_lshl_add_u64 v[116:117], v[98:99], 0, s[2:3]
	v_readfirstlane_b32 s10, v115
	v_add_u32_e32 v120, 0x2000, v115
	v_lshl_add_u64 v[118:119], v[116:117], 0, s[12:13]
	s_mov_b32 m0, s10
	v_readfirstlane_b32 s10, v120
	s_waitcnt vmcnt(0)
	s_waitcnt vmcnt(0) lgkmcnt(0)
	s_barrier
	global_load_lds_dwordx4 v[118:119], off
	v_lshl_add_u64 v[118:119], v[116:117], 0, s[16:17]
	s_mov_b32 m0, s10
	v_lshl_add_u64 v[116:117], v[116:117], 0, s[18:19]
	global_load_lds_dwordx4 v[118:119], off
	v_add_u32_e32 v118, 0x4000, v115
	v_add_u32_e32 v120, 0x6000, v115
	v_readfirstlane_b32 s10, v118
	s_mov_b32 m0, s10
	s_mov_b64 s[10:11], 0x5f14080
	global_load_lds_dwordx4 v[116:117], off
	v_lshl_add_u64 v[116:117], v[96:97], 0, s[2:3]
	v_lshl_add_u64 v[118:119], v[116:117], 0, s[10:11]
	v_readfirstlane_b32 s10, v120
	s_mov_b32 m0, s10
	s_mov_b64 s[10:11], 0x5f34080
	v_add_u32_e32 v120, 0x8000, v115
	global_load_lds_dwordx4 v[118:119], off
	v_lshl_add_u64 v[118:119], v[116:117], 0, s[10:11]
	v_readfirstlane_b32 s10, v120
	s_mov_b32 m0, s10
	s_mov_b64 s[10:11], 0x5f54080
	v_add_u32_e32 v120, 0xa000, v115
	global_load_lds_dwordx4 v[118:119], off
	v_lshl_add_u64 v[118:119], v[116:117], 0, s[10:11]
	v_readfirstlane_b32 s10, v120
	s_mov_b32 m0, s10
	s_mov_b64 s[10:11], 0x5f74080
	v_add_u32_e32 v115, 0xc000, v115
	v_lshl_add_u64 v[116:117], v[116:117], 0, s[10:11]
	v_readfirstlane_b32 s10, v115
	global_load_lds_dwordx4 v[118:119], off
	s_mov_b32 m0, s10
	s_nop 0
	global_load_lds_dwordx4 v[116:117], off
	s_bitcmp1_b32 s7, 0
	s_cselect_b32 s7, 0xe000, 0
	v_add_u32_e32 v115, s7, v114
	v_add_u32_e32 v120, v115, v111
	ds_read_b128 v[116:119], v120 offset:0
	v_add_u32_e32 v128, s7, v113
	ds_read_b128 v[120:123], v120 offset:0x1000
	v_add_u32_e32 v134, v128, v111
	ds_read_b128 v[124:127], v134 offset:0
	ds_read_b128 v[130:133], v134 offset:0x1000
	ds_read_b128 v[134:137], v134 offset:0x2000
	v_add_u32_e32 v148, v115, v110
	ds_read_b128 v[144:147], v148 offset:0
	ds_read_b128 v[148:151], v148 offset:0x1000
	v_add_u32_e32 v152, v128, v110
	ds_read_b128 v[182:185], v152 offset:0
	ds_read_b128 v[186:189], v152 offset:0x1000
	ds_read_b128 v[190:193], v152 offset:0x2000
	s_waitcnt lgkmcnt(5)
	s_nop 0
	v_mfma_f32_32x32x16_bf16 v[64:79], v[116:119], v[124:127], v[64:79]
	v_mfma_f32_32x32x16_bf16 v[32:47], v[116:119], v[130:133], v[32:47]
	v_mfma_f32_32x32x16_bf16 v[0:15], v[116:119], v[134:137], v[0:15]
	v_mfma_f32_32x32x16_bf16 v[80:95], v[120:123], v[124:127], v[80:95]
	v_mfma_f32_32x32x16_bf16 v[48:63], v[120:123], v[130:133], v[48:63]
	v_mfma_f32_32x32x16_bf16 v[16:31], v[120:123], v[134:137], v[16:31]
	v_add_u32_e32 v120, v115, v108
	ds_read_b128 v[116:119], v120 offset:0
	ds_read_b128 v[120:123], v120 offset:0x1000
	v_add_u32_e32 v134, v128, v108
	ds_read_b128 v[124:127], v134 offset:0
	ds_read_b128 v[130:133], v134 offset:0x1000
	ds_read_b128 v[134:137], v134 offset:0x2000
	s_waitcnt lgkmcnt(5)
	s_nop 0
	v_mfma_f32_32x32x16_bf16 v[64:79], v[144:147], v[182:185], v[64:79]
	v_mfma_f32_32x32x16_bf16 v[32:47], v[144:147], v[186:189], v[32:47]
	v_mfma_f32_32x32x16_bf16 v[0:15], v[144:147], v[190:193], v[0:15]
	v_mfma_f32_32x32x16_bf16 v[80:95], v[148:151], v[182:185], v[80:95]
	v_mfma_f32_32x32x16_bf16 v[48:63], v[148:151], v[186:189], v[48:63]
	v_mfma_f32_32x32x16_bf16 v[16:31], v[148:151], v[190:193], v[16:31]
	v_add_u32_e32 v115, v115, v107
	ds_read_b128 v[144:147], v115 offset:0
	ds_read_b128 v[148:151], v115 offset:0x1000
	v_add_u32_e32 v115, v128, v107
	ds_read_b128 v[182:185], v115 offset:0
	ds_read_b128 v[186:189], v115 offset:0x1000
	ds_read_b128 v[190:193], v115 offset:0x2000
	s_waitcnt lgkmcnt(5)
	s_nop 0
	v_mfma_f32_32x32x16_bf16 v[64:79], v[116:119], v[124:127], v[64:79]
	v_mfma_f32_32x32x16_bf16 v[32:47], v[116:119], v[130:133], v[32:47]
	v_mfma_f32_32x32x16_bf16 v[0:15], v[116:119], v[134:137], v[0:15]
	v_mfma_f32_32x32x16_bf16 v[80:95], v[120:123], v[124:127], v[80:95]
	v_mfma_f32_32x32x16_bf16 v[48:63], v[120:123], v[130:133], v[48:63]
	v_mfma_f32_32x32x16_bf16 v[16:31], v[120:123], v[134:137], v[16:31]
	s_waitcnt lgkmcnt(0)
	s_nop 0
	v_mfma_f32_32x32x16_bf16 v[64:79], v[144:147], v[182:185], v[64:79]
	v_mfma_f32_32x32x16_bf16 v[32:47], v[144:147], v[186:189], v[32:47]
	v_mfma_f32_32x32x16_bf16 v[0:15], v[144:147], v[190:193], v[0:15]
	v_mfma_f32_32x32x16_bf16 v[80:95], v[148:151], v[182:185], v[80:95]
	v_mfma_f32_32x32x16_bf16 v[48:63], v[148:151], v[186:189], v[48:63]
	v_mfma_f32_32x32x16_bf16 v[16:31], v[148:151], v[190:193], v[16:31]
	s_add_u32 s2, s2, 0x80
	s_addc_u32 s3, s3, 0
	s_cmpk_eq_i32 s2, 0x780
	s_mov_b32 s7, s9
	s_cbranch_scc0 .LBB0_1223
	s_waitcnt vmcnt(0)
	s_waitcnt vmcnt(0) lgkmcnt(0)
	s_barrier
	v_add_u32_e32 v109, 0x14000, v112
	v_add_u32_e32 v112, v109, v111
	ds_read_b128 v[96:99], v112 offset:0
	v_add_u32_e32 v128, 0xe000, v113
	ds_read_b128 v[112:115], v112 offset:0x1000
	v_add_u32_e32 v111, v128, v111
	ds_read_b128 v[116:119], v111 offset:0
	ds_read_b128 v[120:123], v111 offset:0x1000
	ds_read_b128 v[124:127], v111 offset:0x2000
	v_add_u32_e32 v111, v109, v110
	ds_read_b128 v[130:133], v111 offset:0
	ds_read_b128 v[134:137], v111 offset:0x1000
	v_add_u32_e32 v110, v128, v110
	ds_read_b128 v[144:147], v110 offset:0
	ds_read_b128 v[148:151], v110 offset:0x1000
	ds_read_b128 v[182:185], v110 offset:0x2000
	s_waitcnt lgkmcnt(5)
	s_nop 0
	v_mfma_f32_32x32x16_bf16 v[64:79], v[96:99], v[116:119], v[64:79]
	v_mfma_f32_32x32x16_bf16 v[32:47], v[96:99], v[120:123], v[32:47]
	v_mfma_f32_32x32x16_bf16 v[0:15], v[96:99], v[124:127], v[0:15]
	v_mfma_f32_32x32x16_bf16 v[48:63], v[112:115], v[120:123], v[48:63]
	v_mfma_f32_32x32x16_bf16 v[16:31], v[112:115], v[124:127], v[16:31]
	v_mfma_f32_32x32x16_bf16 v[80:95], v[112:115], v[116:119], v[80:95]
	v_add_u32_e32 v110, v109, v108
	ds_read_b128 v[96:99], v110 offset:0
	ds_read_b128 v[110:113], v110 offset:0x1000
	v_add_u32_e32 v108, v128, v108
	ds_read_b128 v[114:117], v108 offset:0
	ds_read_b128 v[118:121], v108 offset:0x1000
	ds_read_b128 v[122:125], v108 offset:0x2000
	s_waitcnt lgkmcnt(5)
	s_nop 0
	v_mfma_f32_32x32x16_bf16 v[64:79], v[130:133], v[144:147], v[64:79]
	v_mfma_f32_32x32x16_bf16 v[32:47], v[130:133], v[148:151], v[32:47]
	v_mfma_f32_32x32x16_bf16 v[0:15], v[130:133], v[182:185], v[0:15]
	v_mfma_f32_32x32x16_bf16 v[48:63], v[134:137], v[148:151], v[48:63]
	v_mfma_f32_32x32x16_bf16 v[16:31], v[134:137], v[182:185], v[16:31]
	v_mfma_f32_32x32x16_bf16 v[80:95], v[134:137], v[144:147], v[80:95]
	v_add_u32_e32 v108, v109, v107
	ds_read_b128 v[130:133], v108 offset:0
	ds_read_b128 v[134:137], v108 offset:0x1000
	v_add_u32_e32 v107, v128, v107
	ds_read_b128 v[144:147], v107 offset:0
	ds_read_b128 v[148:151], v107 offset:0x1000
	ds_read_b128 v[182:185], v107 offset:0x2000
	s_waitcnt lgkmcnt(5)
	s_nop 0
	v_mfma_f32_32x32x16_bf16 v[64:79], v[96:99], v[114:117], v[64:79]
	v_mfma_f32_32x32x16_bf16 v[32:47], v[96:99], v[118:121], v[32:47]
	v_mfma_f32_32x32x16_bf16 v[0:15], v[96:99], v[122:125], v[0:15]
	v_mfma_f32_32x32x16_bf16 v[48:63], v[110:113], v[118:121], v[48:63]
	v_mfma_f32_32x32x16_bf16 v[16:31], v[110:113], v[122:125], v[16:31]
	v_mfma_f32_32x32x16_bf16 v[80:95], v[110:113], v[114:117], v[80:95]
	s_waitcnt lgkmcnt(0)
	s_nop 0
	v_mfma_f32_32x32x16_bf16 v[64:79], v[130:133], v[144:147], v[64:79]
	v_mfma_f32_32x32x16_bf16 v[32:47], v[130:133], v[148:151], v[32:47]
	v_mfma_f32_32x32x16_bf16 v[0:15], v[130:133], v[182:185], v[0:15]
	v_mfma_f32_32x32x16_bf16 v[48:63], v[134:137], v[148:151], v[48:63]
	v_mfma_f32_32x32x16_bf16 v[16:31], v[134:137], v[182:185], v[16:31]
	v_mfma_f32_32x32x16_bf16 v[80:95], v[134:137], v[144:147], v[80:95]
	v_add_u32_e32 v96, s4, v106
	v_lshrrev_b32_e32 v128, 4, v101
	v_and_b32_e32 v112, 15, v100
	v_or_b32_e32 v100, v96, v128
	v_add_u32_e32 v105, s8, v105
	v_ashrrev_i32_e32 v101, 31, v100
	v_lshl_or_b32 v98, v112, 2, v105
	v_lshlrev_b64 v[106:107], 12, v[100:101]
	v_ashrrev_i32_e32 v99, 31, v98
	v_lshl_add_u64 v[106:107], s[42:43], 0, v[106:107]
	v_lshl_add_u64 v[110:111], v[98:99], 2, v[106:107]
	s_barrier
	global_load_dwordx4 v[198:201], v[110:111], off
	v_add_co_u32_e32 v182, vcc, 0x4000, v110
	s_nop 1
	v_addc_co_u32_e32 v183, vcc, 0, v111, vcc
	global_load_dwordx4 v[202:205], v[182:183], off
	v_add_co_u32_e32 v182, vcc, 0x4000, v182
	s_nop 1
	v_addc_co_u32_e32 v183, vcc, 0, v183, vcc
	global_load_dwordx4 v[206:209], v[182:183], off
	v_add_co_u32_e32 v182, vcc, 0x4000, v182
	s_nop 1
	v_addc_co_u32_e32 v183, vcc, 0, v183, vcc
	global_load_dwordx4 v[210:213], v[182:183], off
	v_add_co_u32_e32 v182, vcc, 0x4000, v182
	s_nop 1
	v_addc_co_u32_e32 v183, vcc, 0, v183, vcc
	global_load_dwordx4 v[214:217], v[182:183], off
	v_add_co_u32_e32 v182, vcc, 0x4000, v182
	s_nop 1
	v_addc_co_u32_e32 v183, vcc, 0, v183, vcc
	global_load_dwordx4 v[218:221], v[182:183], off
	v_add_co_u32_e32 v182, vcc, 0x4000, v182
	s_nop 1
	v_addc_co_u32_e32 v183, vcc, 0, v183, vcc
	global_load_dwordx4 v[222:225], v[182:183], off
	v_add_co_u32_e32 v182, vcc, 0x4000, v182
	s_nop 1
	v_addc_co_u32_e32 v183, vcc, 0, v183, vcc
	global_load_dwordx4 v[226:229], v[182:183], off
	v_add_co_u32_e32 v182, vcc, 0x4000, v182
	s_nop 1
	v_addc_co_u32_e32 v183, vcc, 0, v183, vcc
	global_load_dwordx4 v[184:187], v[182:183], off
	v_add_co_u32_e32 v182, vcc, 0x4000, v182
	s_nop 1
	v_addc_co_u32_e32 v183, vcc, 0, v183, vcc
	global_load_dwordx4 v[188:191], v[182:183], off
	v_add_co_u32_e32 v182, vcc, 0x4000, v182
	s_nop 1
	v_addc_co_u32_e32 v183, vcc, 0, v183, vcc
	global_load_dwordx4 v[192:195], v[182:183], off
	v_add_co_u32_e32 v182, vcc, 0x4000, v182
	s_nop 1
	v_addc_co_u32_e32 v183, vcc, 0, v183, vcc
	global_load_dwordx4 v[116:119], v[182:183], off
	v_add_co_u32_e32 v182, vcc, 0x4000, v182
	s_nop 1
	v_addc_co_u32_e32 v183, vcc, 0, v183, vcc
	global_load_dwordx4 v[120:123], v[182:183], off
	v_add_co_u32_e32 v182, vcc, 0x4000, v182
	s_nop 1
	v_addc_co_u32_e32 v183, vcc, 0, v183, vcc
	global_load_dwordx4 v[124:127], v[182:183], off
	v_add_co_u32_e32 v182, vcc, 0x4000, v182
	s_nop 1
	v_addc_co_u32_e32 v183, vcc, 0, v183, vcc
	global_load_dwordx4 v[130:133], v[182:183], off
	v_add_co_u32_e32 v182, vcc, 0x4000, v182
	s_nop 1
	v_addc_co_u32_e32 v183, vcc, 0, v183, vcc
	global_load_dwordx4 v[134:137], v[182:183], off
	s_movk_i32 s2, 0x2400
	s_cmp_lt_i32 s5, 22
	v_mul_lo_u32 v97, v103, s2
	s_cselect_b64 s[2:3], -1, 0
	s_cmp_gt_i32 s5, 21
	s_movk_i32 s5, 0x110
	v_and_b32_e32 v103, 16, v104
	v_mad_u32_u24 v104, v102, s5, v97
	v_add_u32_e32 v113, 0xfffff000, v96
	v_cndmask_b32_e64 v102, 0, 1, s[2:3]
	s_cselect_b64 s[2:3], -1, 0
	s_add_i32 s7, s4, 0xfffff000
	v_add_u32_e32 v104, v104, v103
	ds_write_b128 v104, v[64:67]
	ds_write_b128 v104, v[68:71] offset:32
	ds_write_b128 v104, v[72:75] offset:64
	ds_write_b128 v104, v[76:79] offset:96
	ds_write_b128 v104, v[80:83] offset:128
	ds_write_b128 v104, v[84:87] offset:160
	ds_write_b128 v104, v[88:91] offset:192
	ds_write_b128 v104, v[92:95] offset:224
	v_xor_b32_e32 v64, s7, v113
	s_movk_i32 s4, 0x400
	v_lshl_or_b32 v97, v112, 4, v97
	v_cmp_gt_u32_e32 vcc, s4, v64
	v_mad_u32_u24 v115, v128, s5, v97
	s_and_b64 s[4:5], s[2:3], vcc
	v_cndmask_b32_e64 v71, 0, 1, s[4:5]
	s_movk_i32 s4, 0x1000
	v_cmp_gt_i32_e32 vcc, s4, v100
	v_subrev_u32_e32 v114, s8, v98
	v_lshl_add_u32 v103, v114, 2, v167
	v_cndmask_b32_e32 v64, v71, v102, vcc
	v_and_b32_e32 v64, 1, v64
	v_cmp_eq_u32_e32 vcc, 1, v64
	v_ashrrev_i32_e32 v68, 6, v105
	s_mov_b32 s4, 0xc000
	v_cndmask_b32_e64 v64, v171, 0, vcc
	v_add_u32_e32 v70, v103, v64
	ds_read_b128 v[64:67], v115
	ds_read_b128 v[72:75], v70
	v_cmp_eq_u32_e64 s[40:41], 0, v112
	v_mad_i64_i32 v[68:69], s[4:5], v68, s4, 0
	s_and_b64 vcc, exec, s[0:1]
	s_waitcnt vmcnt(15) lgkmcnt(0)
	v_pk_fma_f32 v[66:67], v[66:67], v[74:75], v[200:201]
	v_pk_fma_f32 v[64:65], v[64:65], v[72:73], v[198:199]
	global_store_dwordx4 v[110:111], v[64:67], off
	s_cbranch_vccnz .LBB0_1228
	ds_read_b128 v[72:75], v70 offset:2048
	v_lshlrev_b64 v[76:77], 10, v[100:101]
	v_lshl_add_u64 v[76:77], v[76:77], 1, s[44:45]
	v_lshl_add_u64 v[76:77], v[98:99], 1, v[76:77]
	s_waitcnt lgkmcnt(0)
	v_pk_mul_f32 v[72:73], v[64:65], v[72:73]
	v_pk_mul_f32 v[64:65], v[64:65], v[64:65]
	v_pk_mul_f32 v[74:75], v[66:67], v[74:75]
	v_pk_mul_f32 v[66:67], v[66:67], v[66:67]
	v_add_f32_e32 v64, v64, v65
	v_add_f32_e32 v64, v66, v64
	v_add_f32_e32 v64, v67, v64
	v_cvt_pk_bf16_f32 v72, v72, v73
	v_cvt_pk_bf16_f32 v73, v74, v75
	v_add_f32_dpp v64, v64, v64 quad_perm:[1,0,3,2] row_mask:0xf bank_mask:0xf bound_ctrl:1
	global_store_dwordx2 v[76:77], v[72:73], off
	s_nop 0
	v_add_f32_dpp v64, v64, v64 quad_perm:[2,3,0,1] row_mask:0xf bank_mask:0xf bound_ctrl:1
	s_nop 1
	v_add_f32_dpp v64, v64, v64 row_half_mirror row_mask:0xf bank_mask:0xf bound_ctrl:1
	s_nop 1
	v_mov_b32_dpp v65, v64 row_mirror row_mask:0xf bank_mask:0xf bound_ctrl:1
	s_and_saveexec_b64 s[4:5], s[40:41]
	s_cbranch_execz .LBB0_1227
	v_lshl_add_u64 v[66:67], s[48:49], 0, v[68:69]
	v_lshl_add_u64 v[66:67], v[100:101], 2, v[66:67]
	v_add_f32_e32 v64, v64, v65
	global_store_dword v[66:67], v64, off

.LBB0_1228:
	v_or_b32_e32 v70, 4, v128
	v_or_b32_e32 v72, v96, v70
	v_ashrrev_i32_e32 v73, 31, v72
	v_lshlrev_b64 v[64:65], 12, v[72:73]
	v_lshl_add_u64 v[64:65], s[42:43], 0, v[64:65]
	v_lshl_add_u64 v[84:85], v[98:99], 2, v[64:65]
	s_movk_i32 s4, 0x1000
	v_mul_u32_u24_e32 v74, 0x110, v128
	v_cmp_gt_i32_e32 vcc, s4, v72
	v_add_u32_e32 v86, v74, v97
	s_nop 0
	v_cndmask_b32_e32 v74, v71, v102, vcc
	v_and_b32_e32 v74, 1, v74
	v_cmp_eq_u32_e32 vcc, 1, v74
	s_nop 1
	v_cndmask_b32_e64 v74, v171, 0, vcc
	v_add_u32_e32 v74, v103, v74
	ds_read_b128 v[76:79], v86 offset:1088
	ds_read_b128 v[80:83], v74
	s_and_b64 vcc, exec, s[0:1]
	s_waitcnt vmcnt(15) lgkmcnt(0)
	v_pk_fma_f32 v[66:67], v[78:79], v[82:83], v[204:205]
	v_pk_fma_f32 v[64:65], v[76:77], v[80:81], v[202:203]
	global_store_dwordx4 v[84:85], v[64:67], off
	s_cbranch_vccnz .LBB0_1232
	ds_read_b128 v[74:77], v74 offset:2048
	v_lshlrev_b64 v[72:73], 10, v[72:73]
	v_lshl_add_u64 v[72:73], v[72:73], 1, s[44:45]
	v_lshl_add_u64 v[72:73], v[98:99], 1, v[72:73]
	s_waitcnt lgkmcnt(0)
	v_pk_mul_f32 v[74:75], v[64:65], v[74:75]
	v_pk_mul_f32 v[64:65], v[64:65], v[64:65]
	v_pk_mul_f32 v[76:77], v[66:67], v[76:77]
	v_pk_mul_f32 v[66:67], v[66:67], v[66:67]
	v_add_f32_e32 v64, v64, v65
	v_add_f32_e32 v64, v66, v64
	v_add_f32_e32 v64, v67, v64
	v_cvt_pk_bf16_f32 v74, v74, v75
	v_cvt_pk_bf16_f32 v75, v76, v77
	v_add_f32_dpp v64, v64, v64 quad_perm:[1,0,3,2] row_mask:0xf bank_mask:0xf bound_ctrl:1
	global_store_dwordx2 v[72:73], v[74:75], off
	s_nop 0
	v_add_f32_dpp v64, v64, v64 quad_perm:[2,3,0,1] row_mask:0xf bank_mask:0xf bound_ctrl:1
	s_nop 1
	v_add_f32_dpp v64, v64, v64 row_half_mirror row_mask:0xf bank_mask:0xf bound_ctrl:1
	s_nop 1
	v_mov_b32_dpp v65, v64 row_mirror row_mask:0xf bank_mask:0xf bound_ctrl:1
	s_and_saveexec_b64 s[4:5], s[40:41]
	s_cbranch_execz .LBB0_1231
	v_ashrrev_i32_e32 v97, 31, v96
	v_lshl_add_u64 v[66:67], s[48:49], 0, v[68:69]
	v_lshl_add_u64 v[72:73], v[96:97], 0, v[128:129]
	v_lshl_add_u64 v[66:67], v[72:73], 2, v[66:67]
	v_add_f32_e32 v64, v64, v65
	global_store_dword v[66:67], v64, off offset:16

.LBB0_1232:
	v_or_b32_e32 v72, 8, v128
	v_or_b32_e32 v74, v96, v72
	v_ashrrev_i32_e32 v75, 31, v74
	v_lshlrev_b64 v[64:65], 12, v[74:75]
	v_lshl_add_u64 v[64:65], s[42:43], 0, v[64:65]
	v_lshl_add_u64 v[84:85], v[98:99], 2, v[64:65]
	s_movk_i32 s4, 0x1000
	v_cmp_gt_i32_e32 vcc, s4, v74
	s_nop 1
	v_cndmask_b32_e32 v73, v71, v102, vcc
	v_and_b32_e32 v73, 1, v73
	v_cmp_eq_u32_e32 vcc, 1, v73
	s_nop 1
	v_cndmask_b32_e64 v73, v171, 0, vcc
	v_add_u32_e32 v73, v103, v73
	ds_read_b128 v[76:79], v86 offset:2176
	ds_read_b128 v[80:83], v73
	s_and_b64 vcc, exec, s[0:1]
	s_waitcnt vmcnt(15) lgkmcnt(0)
	v_pk_fma_f32 v[66:67], v[78:79], v[82:83], v[208:209]
	v_pk_fma_f32 v[64:65], v[76:77], v[80:81], v[206:207]
	global_store_dwordx4 v[84:85], v[64:67], off
	s_cbranch_vccnz .LBB0_1236
	ds_read_b128 v[76:79], v73 offset:2048
	v_lshlrev_b64 v[74:75], 10, v[74:75]
	v_lshl_add_u64 v[74:75], v[74:75], 1, s[44:45]
	v_lshl_add_u64 v[74:75], v[98:99], 1, v[74:75]
	s_waitcnt lgkmcnt(0)
	v_pk_mul_f32 v[76:77], v[64:65], v[76:77]
	v_pk_mul_f32 v[64:65], v[64:65], v[64:65]
	v_pk_mul_f32 v[78:79], v[66:67], v[78:79]
	v_pk_mul_f32 v[66:67], v[66:67], v[66:67]
	v_add_f32_e32 v64, v64, v65
	v_add_f32_e32 v64, v66, v64
	v_add_f32_e32 v64, v67, v64
	v_cvt_pk_bf16_f32 v76, v76, v77
	v_cvt_pk_bf16_f32 v77, v78, v79
	v_add_f32_dpp v64, v64, v64 quad_perm:[1,0,3,2] row_mask:0xf bank_mask:0xf bound_ctrl:1
	global_store_dwordx2 v[74:75], v[76:77], off
	s_nop 0
	v_add_f32_dpp v64, v64, v64 quad_perm:[2,3,0,1] row_mask:0xf bank_mask:0xf bound_ctrl:1
	s_nop 1
	v_add_f32_dpp v64, v64, v64 row_half_mirror row_mask:0xf bank_mask:0xf bound_ctrl:1
	s_nop 1
	v_mov_b32_dpp v65, v64 row_mirror row_mask:0xf bank_mask:0xf bound_ctrl:1
	s_and_saveexec_b64 s[4:5], s[40:41]
	s_cbranch_execz .LBB0_1235
	v_ashrrev_i32_e32 v97, 31, v96
	v_lshl_add_u64 v[66:67], s[48:49], 0, v[68:69]
	v_lshl_add_u64 v[74:75], v[96:97], 0, v[128:129]
	v_lshl_add_u64 v[66:67], v[74:75], 2, v[66:67]
	v_add_f32_e32 v64, v64, v65
	global_store_dword v[66:67], v64, off offset:32

.LBB0_1236:
	v_or_b32_e32 v74, 12, v128
	v_or_b32_e32 v76, v96, v74
	v_ashrrev_i32_e32 v77, 31, v76
	v_lshlrev_b64 v[64:65], 12, v[76:77]
	v_lshl_add_u64 v[64:65], s[42:43], 0, v[64:65]
	v_lshl_add_u64 v[88:89], v[98:99], 2, v[64:65]
	s_movk_i32 s4, 0x1000
	v_cmp_gt_i32_e32 vcc, s4, v76
	s_nop 1
	v_cndmask_b32_e32 v73, v71, v102, vcc
	v_and_b32_e32 v73, 1, v73
	v_cmp_eq_u32_e32 vcc, 1, v73
	s_nop 1
	v_cndmask_b32_e64 v73, v171, 0, vcc
	v_add_u32_e32 v73, v103, v73
	ds_read_b128 v[78:81], v86 offset:3264
	ds_read_b128 v[82:85], v73
	s_and_b64 vcc, exec, s[0:1]
	s_waitcnt vmcnt(15) lgkmcnt(0)
	v_pk_fma_f32 v[66:67], v[80:81], v[84:85], v[212:213]
	v_pk_fma_f32 v[64:65], v[78:79], v[82:83], v[210:211]
	global_store_dwordx4 v[88:89], v[64:67], off
	s_cbranch_vccnz .LBB0_1240
	ds_read_b128 v[78:81], v73 offset:2048
	v_lshlrev_b64 v[76:77], 10, v[76:77]
	v_lshl_add_u64 v[76:77], v[76:77], 1, s[44:45]
	v_lshl_add_u64 v[76:77], v[98:99], 1, v[76:77]
	s_waitcnt lgkmcnt(0)
	v_pk_mul_f32 v[78:79], v[64:65], v[78:79]
	v_pk_mul_f32 v[64:65], v[64:65], v[64:65]
	v_pk_mul_f32 v[80:81], v[66:67], v[80:81]
	v_pk_mul_f32 v[66:67], v[66:67], v[66:67]
	v_add_f32_e32 v64, v64, v65
	v_add_f32_e32 v64, v66, v64
	v_add_f32_e32 v64, v67, v64
	v_cvt_pk_bf16_f32 v78, v78, v79
	v_cvt_pk_bf16_f32 v79, v80, v81
	v_add_f32_dpp v64, v64, v64 quad_perm:[1,0,3,2] row_mask:0xf bank_mask:0xf bound_ctrl:1
	global_store_dwordx2 v[76:77], v[78:79], off
	s_nop 0
	v_add_f32_dpp v64, v64, v64 quad_perm:[2,3,0,1] row_mask:0xf bank_mask:0xf bound_ctrl:1
	s_nop 1
	v_add_f32_dpp v64, v64, v64 row_half_mirror row_mask:0xf bank_mask:0xf bound_ctrl:1
	s_nop 1
	v_mov_b32_dpp v65, v64 row_mirror row_mask:0xf bank_mask:0xf bound_ctrl:1
	s_and_saveexec_b64 s[4:5], s[40:41]
	s_cbranch_execz .LBB0_1239
	v_ashrrev_i32_e32 v97, 31, v96
	v_lshl_add_u64 v[66:67], s[48:49], 0, v[68:69]
	v_lshl_add_u64 v[76:77], v[96:97], 0, v[128:129]
	v_lshl_add_u64 v[66:67], v[76:77], 2, v[66:67]
	v_add_f32_e32 v64, v64, v65
	global_store_dword v[66:67], v64, off offset:48

.LBB0_1240:
	v_or_b32_e32 v76, 16, v128
	v_or_b32_e32 v78, v96, v76
	v_ashrrev_i32_e32 v79, 31, v78
	v_lshlrev_b64 v[64:65], 12, v[78:79]
	v_lshl_add_u64 v[64:65], s[42:43], 0, v[64:65]
	v_lshl_add_u64 v[84:85], v[98:99], 2, v[64:65]
	s_movk_i32 s4, 0x1000
	v_cmp_gt_i32_e32 vcc, s4, v78
	s_nop 1
	v_cndmask_b32_e32 v73, v71, v102, vcc
	v_and_b32_e32 v73, 1, v73
	v_cmp_eq_u32_e32 vcc, 1, v73
	s_nop 1
	v_cndmask_b32_e64 v73, v171, 0, vcc
	v_add_u32_e32 v73, v103, v73
	ds_read_b128 v[80:83], v86 offset:4352
	ds_read_b128 v[88:91], v73
	s_and_b64 vcc, exec, s[0:1]
	s_waitcnt vmcnt(15) lgkmcnt(0)
	v_pk_fma_f32 v[66:67], v[82:83], v[90:91], v[216:217]
	v_pk_fma_f32 v[64:65], v[80:81], v[88:89], v[214:215]
	global_store_dwordx4 v[84:85], v[64:67], off
	s_cbranch_vccnz .LBB0_1244
	ds_read_b128 v[80:83], v73 offset:2048
	v_lshlrev_b64 v[78:79], 10, v[78:79]
	v_lshl_add_u64 v[78:79], v[78:79], 1, s[44:45]
	v_lshl_add_u64 v[78:79], v[98:99], 1, v[78:79]
	s_waitcnt lgkmcnt(0)
	v_pk_mul_f32 v[80:81], v[64:65], v[80:81]
	v_pk_mul_f32 v[64:65], v[64:65], v[64:65]
	v_pk_mul_f32 v[82:83], v[66:67], v[82:83]
	v_pk_mul_f32 v[66:67], v[66:67], v[66:67]
	v_add_f32_e32 v64, v64, v65
	v_add_f32_e32 v64, v66, v64
	v_add_f32_e32 v64, v67, v64
	v_cvt_pk_bf16_f32 v80, v80, v81
	v_cvt_pk_bf16_f32 v81, v82, v83
	v_add_f32_dpp v64, v64, v64 quad_perm:[1,0,3,2] row_mask:0xf bank_mask:0xf bound_ctrl:1
	global_store_dwordx2 v[78:79], v[80:81], off
	s_nop 0
	v_add_f32_dpp v64, v64, v64 quad_perm:[2,3,0,1] row_mask:0xf bank_mask:0xf bound_ctrl:1
	s_nop 1
	v_add_f32_dpp v64, v64, v64 row_half_mirror row_mask:0xf bank_mask:0xf bound_ctrl:1
	s_nop 1
	v_mov_b32_dpp v65, v64 row_mirror row_mask:0xf bank_mask:0xf bound_ctrl:1
	s_and_saveexec_b64 s[4:5], s[40:41]
	s_cbranch_execz .LBB0_1243
	v_ashrrev_i32_e32 v97, 31, v96
	v_lshl_add_u64 v[66:67], s[48:49], 0, v[68:69]
	v_lshl_add_u64 v[78:79], v[96:97], 0, v[128:129]
	v_lshl_add_u64 v[66:67], v[78:79], 2, v[66:67]
	v_add_f32_e32 v64, v64, v65
	global_store_dword v[66:67], v64, off offset:64

.LBB0_1244:
	v_or_b32_e32 v78, 20, v128
	v_or_b32_e32 v80, v96, v78
	v_ashrrev_i32_e32 v81, 31, v80
	v_lshlrev_b64 v[64:65], 12, v[80:81]
	v_lshl_add_u64 v[64:65], s[42:43], 0, v[64:65]
	v_lshl_add_u64 v[92:93], v[98:99], 2, v[64:65]
	s_movk_i32 s4, 0x1000
	v_cmp_gt_i32_e32 vcc, s4, v80
	s_nop 1
	v_cndmask_b32_e32 v73, v71, v102, vcc
	v_and_b32_e32 v73, 1, v73
	v_cmp_eq_u32_e32 vcc, 1, v73
	s_nop 1
	v_cndmask_b32_e64 v73, v171, 0, vcc
	v_add_u32_e32 v73, v103, v73
	ds_read_b128 v[82:85], v86 offset:5440
	ds_read_b128 v[88:91], v73
	s_and_b64 vcc, exec, s[0:1]
	s_waitcnt vmcnt(15) lgkmcnt(0)
	v_pk_fma_f32 v[66:67], v[84:85], v[90:91], v[220:221]
	v_pk_fma_f32 v[64:65], v[82:83], v[88:89], v[218:219]
	global_store_dwordx4 v[92:93], v[64:67], off
	s_cbranch_vccnz .LBB0_1248
	ds_read_b128 v[82:85], v73 offset:2048
	v_lshlrev_b64 v[80:81], 10, v[80:81]
	v_lshl_add_u64 v[80:81], v[80:81], 1, s[44:45]
	v_lshl_add_u64 v[80:81], v[98:99], 1, v[80:81]
	s_waitcnt lgkmcnt(0)
	v_pk_mul_f32 v[82:83], v[64:65], v[82:83]
	v_pk_mul_f32 v[64:65], v[64:65], v[64:65]
	v_pk_mul_f32 v[84:85], v[66:67], v[84:85]
	v_pk_mul_f32 v[66:67], v[66:67], v[66:67]
	v_add_f32_e32 v64, v64, v65
	v_add_f32_e32 v64, v66, v64
	v_add_f32_e32 v64, v67, v64
	v_cvt_pk_bf16_f32 v82, v82, v83
	v_cvt_pk_bf16_f32 v83, v84, v85
	v_add_f32_dpp v64, v64, v64 quad_perm:[1,0,3,2] row_mask:0xf bank_mask:0xf bound_ctrl:1
	global_store_dwordx2 v[80:81], v[82:83], off
	s_nop 0
	v_add_f32_dpp v64, v64, v64 quad_perm:[2,3,0,1] row_mask:0xf bank_mask:0xf bound_ctrl:1
	s_nop 1
	v_add_f32_dpp v64, v64, v64 row_half_mirror row_mask:0xf bank_mask:0xf bound_ctrl:1
	s_nop 1
	v_mov_b32_dpp v65, v64 row_mirror row_mask:0xf bank_mask:0xf bound_ctrl:1
	s_and_saveexec_b64 s[4:5], s[40:41]
	s_cbranch_execz .LBB0_1247
	v_ashrrev_i32_e32 v97, 31, v96
	v_lshl_add_u64 v[66:67], s[48:49], 0, v[68:69]
	v_lshl_add_u64 v[80:81], v[96:97], 0, v[128:129]
	v_lshl_add_u64 v[66:67], v[80:81], 2, v[66:67]
	v_add_f32_e32 v64, v64, v65
	global_store_dword v[66:67], v64, off offset:80

.LBB0_1248:
	v_or_b32_e32 v80, 24, v128
	v_or_b32_e32 v82, v96, v80
	v_ashrrev_i32_e32 v83, 31, v82
	v_lshlrev_b64 v[64:65], 12, v[82:83]
	v_lshl_add_u64 v[64:65], s[42:43], 0, v[64:65]
	v_lshl_add_u64 v[84:85], v[98:99], 2, v[64:65]
	s_movk_i32 s4, 0x1000
	v_cmp_gt_i32_e32 vcc, s4, v82
	s_nop 1
	v_cndmask_b32_e32 v73, v71, v102, vcc
	v_and_b32_e32 v73, 1, v73
	v_cmp_eq_u32_e32 vcc, 1, v73
	s_nop 1
	v_cndmask_b32_e64 v73, v171, 0, vcc
	v_add_u32_e32 v73, v103, v73
	ds_read_b128 v[88:91], v86 offset:6528
	ds_read_b128 v[92:95], v73
	s_and_b64 vcc, exec, s[0:1]
	s_waitcnt vmcnt(15) lgkmcnt(0)
	v_pk_fma_f32 v[66:67], v[90:91], v[94:95], v[224:225]
	v_pk_fma_f32 v[64:65], v[88:89], v[92:93], v[222:223]
	global_store_dwordx4 v[84:85], v[64:67], off
	s_cbranch_vccnz .LBB0_1252
	ds_read_b128 v[88:91], v73 offset:2048
	v_lshlrev_b64 v[82:83], 10, v[82:83]
	v_lshl_add_u64 v[82:83], v[82:83], 1, s[44:45]
	v_lshl_add_u64 v[82:83], v[98:99], 1, v[82:83]
	s_waitcnt lgkmcnt(0)
	v_pk_mul_f32 v[88:89], v[64:65], v[88:89]
	v_pk_mul_f32 v[64:65], v[64:65], v[64:65]
	v_pk_mul_f32 v[84:85], v[66:67], v[90:91]
	v_pk_mul_f32 v[66:67], v[66:67], v[66:67]
	v_add_f32_e32 v64, v64, v65
	v_add_f32_e32 v64, v66, v64
	v_add_f32_e32 v64, v67, v64
	v_cvt_pk_bf16_f32 v88, v88, v89
	v_cvt_pk_bf16_f32 v89, v84, v85
	v_add_f32_dpp v64, v64, v64 quad_perm:[1,0,3,2] row_mask:0xf bank_mask:0xf bound_ctrl:1
	global_store_dwordx2 v[82:83], v[88:89], off
	s_nop 0
	v_add_f32_dpp v64, v64, v64 quad_perm:[2,3,0,1] row_mask:0xf bank_mask:0xf bound_ctrl:1
	s_nop 1
	v_add_f32_dpp v64, v64, v64 row_half_mirror row_mask:0xf bank_mask:0xf bound_ctrl:1
	s_nop 1
	v_mov_b32_dpp v65, v64 row_mirror row_mask:0xf bank_mask:0xf bound_ctrl:1
	s_and_saveexec_b64 s[4:5], s[40:41]
	s_cbranch_execz .LBB0_1251
	v_ashrrev_i32_e32 v97, 31, v96
	v_lshl_add_u64 v[66:67], s[48:49], 0, v[68:69]
	v_lshl_add_u64 v[82:83], v[96:97], 0, v[128:129]
	v_lshl_add_u64 v[66:67], v[82:83], 2, v[66:67]
	v_add_f32_e32 v64, v64, v65
	global_store_dword v[66:67], v64, off offset:96

.LBB0_1252:
	v_or_b32_e32 v82, 28, v128
	v_or_b32_e32 v84, v96, v82
	v_ashrrev_i32_e32 v85, 31, v84
	v_lshlrev_b64 v[64:65], 12, v[84:85]
	v_lshl_add_u64 v[64:65], s[42:43], 0, v[64:65]
	v_lshl_add_u64 v[100:101], v[98:99], 2, v[64:65]
	s_movk_i32 s4, 0x1000
	v_cmp_gt_i32_e32 vcc, s4, v84
	s_nop 1
	v_cndmask_b32_e32 v71, v71, v102, vcc
	v_and_b32_e32 v71, 1, v71
	v_cmp_eq_u32_e32 vcc, 1, v71
	s_nop 1
	v_cndmask_b32_e64 v71, v171, 0, vcc
	v_add_u32_e32 v71, v103, v71
	ds_read_b128 v[88:91], v86 offset:7616
	ds_read_b128 v[92:95], v71
	s_and_b64 vcc, exec, s[0:1]
	s_waitcnt vmcnt(15) lgkmcnt(0)
	v_pk_fma_f32 v[66:67], v[90:91], v[94:95], v[228:229]
	v_pk_fma_f32 v[64:65], v[88:89], v[92:93], v[226:227]
	global_store_dwordx4 v[100:101], v[64:67], off
	s_cbranch_vccnz .LBB0_1256
	ds_read_b128 v[88:91], v71 offset:2048
	v_lshlrev_b64 v[84:85], 10, v[84:85]
	v_lshl_add_u64 v[84:85], v[84:85], 1, s[44:45]
	v_lshl_add_u64 v[84:85], v[98:99], 1, v[84:85]
	s_waitcnt lgkmcnt(0)
	v_pk_mul_f32 v[88:89], v[64:65], v[88:89]
	v_pk_mul_f32 v[64:65], v[64:65], v[64:65]
	v_pk_mul_f32 v[90:91], v[66:67], v[90:91]
	v_pk_mul_f32 v[66:67], v[66:67], v[66:67]
	v_add_f32_e32 v64, v64, v65
	v_add_f32_e32 v64, v66, v64
	v_add_f32_e32 v64, v67, v64
	v_cvt_pk_bf16_f32 v88, v88, v89
	v_cvt_pk_bf16_f32 v89, v90, v91
	v_add_f32_dpp v64, v64, v64 quad_perm:[1,0,3,2] row_mask:0xf bank_mask:0xf bound_ctrl:1
	global_store_dwordx2 v[84:85], v[88:89], off
	s_nop 0
	v_add_f32_dpp v64, v64, v64 quad_perm:[2,3,0,1] row_mask:0xf bank_mask:0xf bound_ctrl:1
	s_nop 1
	v_add_f32_dpp v64, v64, v64 row_half_mirror row_mask:0xf bank_mask:0xf bound_ctrl:1
	s_nop 1
	v_mov_b32_dpp v65, v64 row_mirror row_mask:0xf bank_mask:0xf bound_ctrl:1
	s_and_saveexec_b64 s[4:5], s[40:41]
	s_cbranch_execz .LBB0_1255
	v_ashrrev_i32_e32 v97, 31, v96
	v_lshl_add_u64 v[66:67], s[48:49], 0, v[68:69]
	v_lshl_add_u64 v[84:85], v[96:97], 0, v[128:129]
	v_lshl_add_u64 v[66:67], v[84:85], 2, v[66:67]
	v_add_f32_e32 v64, v64, v65
	global_store_dword v[66:67], v64, off offset:112

.LBB0_1256:
	s_nop 0
	v_add_u32_e32 v66, 32, v96
	v_or_b32_e32 v64, v66, v128
	v_ashrrev_i32_e32 v65, 31, v64
	v_lshlrev_b64 v[84:85], 12, v[64:65]
	v_lshl_add_u64 v[84:85], s[42:43], 0, v[84:85]
	v_lshl_add_u64 v[84:85], v[98:99], 2, v[84:85]
	v_add_co_u32_e32 v182, vcc, 0x20000, v84
	s_nop 1
	v_addc_co_u32_e32 v183, vcc, 0, v85, vcc
	global_load_dwordx4 v[198:201], v[182:183], off
	v_add_co_u32_e32 v182, vcc, 0x4000, v182
	s_nop 1
	v_addc_co_u32_e32 v183, vcc, 0, v183, vcc
	global_load_dwordx4 v[202:205], v[182:183], off
	v_add_co_u32_e32 v182, vcc, 0x4000, v182
	s_nop 1
	v_addc_co_u32_e32 v183, vcc, 0, v183, vcc
	global_load_dwordx4 v[206:209], v[182:183], off
	v_add_co_u32_e32 v182, vcc, 0x4000, v182
	s_nop 1
	v_addc_co_u32_e32 v183, vcc, 0, v183, vcc
	global_load_dwordx4 v[210:213], v[182:183], off
	v_add_co_u32_e32 v182, vcc, 0x4000, v182
	s_nop 1
	v_addc_co_u32_e32 v183, vcc, 0, v183, vcc
	global_load_dwordx4 v[214:217], v[182:183], off
	v_add_co_u32_e32 v182, vcc, 0x4000, v182
	s_nop 1
	v_addc_co_u32_e32 v183, vcc, 0, v183, vcc
	global_load_dwordx4 v[218:221], v[182:183], off
	v_add_co_u32_e32 v182, vcc, 0x4000, v182
	s_nop 1
	v_addc_co_u32_e32 v183, vcc, 0, v183, vcc
	global_load_dwordx4 v[222:225], v[182:183], off
	v_add_co_u32_e32 v182, vcc, 0x4000, v182
	s_nop 1
	v_addc_co_u32_e32 v183, vcc, 0, v183, vcc
	global_load_dwordx4 v[226:229], v[182:183], off
	ds_write_b128 v104, v[32:35]
	ds_write_b128 v104, v[36:39] offset:32
	ds_write_b128 v104, v[40:43] offset:64
	ds_write_b128 v104, v[44:47] offset:96
	ds_write_b128 v104, v[48:51] offset:128
	ds_write_b128 v104, v[52:55] offset:160
	ds_write_b128 v104, v[56:59] offset:192
	ds_write_b128 v104, v[60:63] offset:224
	v_add_u32_e32 v32, 0xfffff020, v96
	v_xor_b32_e32 v32, s7, v32
	s_movk_i32 s4, 0x400
	v_cmp_gt_u32_e32 vcc, s4, v32
	s_and_b64 s[4:5], s[2:3], vcc
	v_cndmask_b32_e64 v38, 0, 1, s[4:5]
	s_movk_i32 s4, 0x1000
	v_cmp_gt_i32_e32 vcc, s4, v64
	s_nop 1
	v_cndmask_b32_e32 v32, v38, v102, vcc
	v_and_b32_e32 v32, 1, v32
	v_cmp_eq_u32_e32 vcc, 1, v32
	s_nop 1
	v_cndmask_b32_e64 v32, v171, 0, vcc
	v_add_u32_e32 v36, v103, v32
	ds_read_b128 v[32:35], v86
	ds_read_b128 v[40:43], v36
	s_and_b64 vcc, exec, s[0:1]
	s_waitcnt vmcnt(23) lgkmcnt(0)
	v_pk_fma_f32 v[34:35], v[34:35], v[42:43], v[186:187]
	v_pk_fma_f32 v[32:33], v[32:33], v[40:41], v[184:185]
	global_store_dwordx4 v[84:85], v[32:35], off
	s_cbranch_vccnz .LBB0_1260
	ds_read_b128 v[40:43], v36 offset:2048
	v_lshlrev_b64 v[36:37], 10, v[64:65]
	v_lshl_add_u64 v[36:37], v[36:37], 1, s[44:45]
	v_lshl_add_u64 v[36:37], v[98:99], 1, v[36:37]
	s_waitcnt lgkmcnt(0)
	v_pk_mul_f32 v[40:41], v[32:33], v[40:41]
	v_pk_mul_f32 v[32:33], v[32:33], v[32:33]
	v_pk_mul_f32 v[42:43], v[34:35], v[42:43]
	v_pk_mul_f32 v[34:35], v[34:35], v[34:35]
	v_add_f32_e32 v32, v32, v33
	v_add_f32_e32 v32, v34, v32
	v_add_f32_e32 v32, v35, v32
	v_cvt_pk_bf16_f32 v40, v40, v41
	v_cvt_pk_bf16_f32 v41, v42, v43
	v_add_f32_dpp v32, v32, v32 quad_perm:[1,0,3,2] row_mask:0xf bank_mask:0xf bound_ctrl:1
	global_store_dwordx2 v[36:37], v[40:41], off
	s_nop 0
	v_add_f32_dpp v32, v32, v32 quad_perm:[2,3,0,1] row_mask:0xf bank_mask:0xf bound_ctrl:1
	s_nop 1
	v_add_f32_dpp v32, v32, v32 row_half_mirror row_mask:0xf bank_mask:0xf bound_ctrl:1
	s_nop 1
	v_mov_b32_dpp v33, v32 row_mirror row_mask:0xf bank_mask:0xf bound_ctrl:1
	s_and_saveexec_b64 s[4:5], s[40:41]
	s_cbranch_execz .LBB0_1259
	v_ashrrev_i32_e32 v97, 31, v96
	v_lshl_add_u64 v[34:35], s[48:49], 0, v[68:69]
	v_lshl_add_u64 v[36:37], v[96:97], 0, v[128:129]
	v_lshl_add_u64 v[34:35], v[36:37], 2, v[34:35]
	v_add_f32_e32 v32, v32, v33
	global_store_dword v[34:35], v32, off offset:128

.LBB0_1260:
	v_or_b32_e32 v36, v66, v70
	v_ashrrev_i32_e32 v37, 31, v36
	v_lshlrev_b64 v[32:33], 12, v[36:37]
	v_lshl_add_u64 v[32:33], s[42:43], 0, v[32:33]
	v_lshl_add_u64 v[48:49], v[98:99], 2, v[32:33]
	s_movk_i32 s4, 0x1000
	v_cmp_gt_i32_e32 vcc, s4, v36
	s_nop 1
	v_cndmask_b32_e32 v39, v38, v102, vcc
	v_and_b32_e32 v39, 1, v39
	v_cmp_eq_u32_e32 vcc, 1, v39
	s_nop 1
	v_cndmask_b32_e64 v39, v171, 0, vcc
	v_add_u32_e32 v39, v103, v39
	ds_read_b128 v[40:43], v86 offset:1088
	ds_read_b128 v[44:47], v39
	s_and_b64 vcc, exec, s[0:1]
	s_waitcnt vmcnt(23) lgkmcnt(0)
	v_pk_fma_f32 v[34:35], v[42:43], v[46:47], v[190:191]
	v_pk_fma_f32 v[32:33], v[40:41], v[44:45], v[188:189]
	global_store_dwordx4 v[48:49], v[32:35], off
	s_cbranch_vccnz .LBB0_1264
	ds_read_b128 v[40:43], v39 offset:2048
	v_lshlrev_b64 v[36:37], 10, v[36:37]
	v_lshl_add_u64 v[36:37], v[36:37], 1, s[44:45]
	v_lshl_add_u64 v[36:37], v[98:99], 1, v[36:37]
	s_waitcnt lgkmcnt(0)
	v_pk_mul_f32 v[40:41], v[32:33], v[40:41]
	v_pk_mul_f32 v[32:33], v[32:33], v[32:33]
	v_pk_mul_f32 v[42:43], v[34:35], v[42:43]
	v_pk_mul_f32 v[34:35], v[34:35], v[34:35]
	v_add_f32_e32 v32, v32, v33
	v_add_f32_e32 v32, v34, v32
	v_add_f32_e32 v32, v35, v32
	v_cvt_pk_bf16_f32 v40, v40, v41
	v_cvt_pk_bf16_f32 v41, v42, v43
	v_add_f32_dpp v32, v32, v32 quad_perm:[1,0,3,2] row_mask:0xf bank_mask:0xf bound_ctrl:1
	global_store_dwordx2 v[36:37], v[40:41], off
	s_nop 0
	v_add_f32_dpp v32, v32, v32 quad_perm:[2,3,0,1] row_mask:0xf bank_mask:0xf bound_ctrl:1
	s_nop 1
	v_add_f32_dpp v32, v32, v32 row_half_mirror row_mask:0xf bank_mask:0xf bound_ctrl:1
	s_nop 1
	v_mov_b32_dpp v33, v32 row_mirror row_mask:0xf bank_mask:0xf bound_ctrl:1
	s_and_saveexec_b64 s[4:5], s[40:41]
	s_cbranch_execz .LBB0_1263
	v_mov_b32_e32 v71, v129
	v_ashrrev_i32_e32 v97, 31, v96
	v_lshl_add_u64 v[34:35], s[48:49], 0, v[68:69]
	v_lshl_add_u64 v[36:37], v[96:97], 0, v[70:71]
	v_lshl_add_u64 v[34:35], v[36:37], 2, v[34:35]
	v_add_f32_e32 v32, v32, v33
	global_store_dword v[34:35], v32, off offset:128

.LBB0_1264:
	v_or_b32_e32 v36, v66, v72
	v_ashrrev_i32_e32 v37, 31, v36
	v_lshlrev_b64 v[32:33], 12, v[36:37]
	v_lshl_add_u64 v[32:33], s[42:43], 0, v[32:33]
	v_lshl_add_u64 v[48:49], v[98:99], 2, v[32:33]
	s_movk_i32 s4, 0x1000
	v_cmp_gt_i32_e32 vcc, s4, v36
	s_nop 1
	v_cndmask_b32_e32 v39, v38, v102, vcc
	v_and_b32_e32 v39, 1, v39
	v_cmp_eq_u32_e32 vcc, 1, v39
	s_nop 1
	v_cndmask_b32_e64 v39, v171, 0, vcc
	v_add_u32_e32 v39, v103, v39
	ds_read_b128 v[40:43], v86 offset:2176
	ds_read_b128 v[44:47], v39
	s_and_b64 vcc, exec, s[0:1]
	s_waitcnt vmcnt(23) lgkmcnt(0)
	v_pk_fma_f32 v[34:35], v[42:43], v[46:47], v[194:195]
	v_pk_fma_f32 v[32:33], v[40:41], v[44:45], v[192:193]
	global_store_dwordx4 v[48:49], v[32:35], off
	s_cbranch_vccnz .LBB0_1268
	ds_read_b128 v[40:43], v39 offset:2048
	v_lshlrev_b64 v[36:37], 10, v[36:37]
	v_lshl_add_u64 v[36:37], v[36:37], 1, s[44:45]
	v_lshl_add_u64 v[36:37], v[98:99], 1, v[36:37]
	s_waitcnt lgkmcnt(0)
	v_pk_mul_f32 v[40:41], v[32:33], v[40:41]
	v_pk_mul_f32 v[32:33], v[32:33], v[32:33]
	v_pk_mul_f32 v[42:43], v[34:35], v[42:43]
	v_pk_mul_f32 v[34:35], v[34:35], v[34:35]
	v_add_f32_e32 v32, v32, v33
	v_add_f32_e32 v32, v34, v32
	v_add_f32_e32 v32, v35, v32
	v_cvt_pk_bf16_f32 v40, v40, v41
	v_cvt_pk_bf16_f32 v41, v42, v43
	v_add_f32_dpp v32, v32, v32 quad_perm:[1,0,3,2] row_mask:0xf bank_mask:0xf bound_ctrl:1
	global_store_dwordx2 v[36:37], v[40:41], off
	s_nop 0
	v_add_f32_dpp v32, v32, v32 quad_perm:[2,3,0,1] row_mask:0xf bank_mask:0xf bound_ctrl:1
	s_nop 1
	v_add_f32_dpp v32, v32, v32 row_half_mirror row_mask:0xf bank_mask:0xf bound_ctrl:1
	s_nop 1
	v_mov_b32_dpp v33, v32 row_mirror row_mask:0xf bank_mask:0xf bound_ctrl:1
	s_and_saveexec_b64 s[4:5], s[40:41]
	s_cbranch_execz .LBB0_1267
	v_mov_b32_e32 v73, v129
	v_ashrrev_i32_e32 v97, 31, v96
	v_lshl_add_u64 v[34:35], s[48:49], 0, v[68:69]
	v_lshl_add_u64 v[36:37], v[96:97], 0, v[72:73]
	v_lshl_add_u64 v[34:35], v[36:37], 2, v[34:35]
	v_add_f32_e32 v32, v32, v33
	global_store_dword v[34:35], v32, off offset:128

.LBB0_1268:
	v_or_b32_e32 v36, v66, v74
	v_ashrrev_i32_e32 v37, 31, v36
	v_lshlrev_b64 v[32:33], 12, v[36:37]
	v_lshl_add_u64 v[32:33], s[42:43], 0, v[32:33]
	v_lshl_add_u64 v[48:49], v[98:99], 2, v[32:33]
	s_movk_i32 s4, 0x1000
	v_cmp_gt_i32_e32 vcc, s4, v36
	s_nop 1
	v_cndmask_b32_e32 v39, v38, v102, vcc
	v_and_b32_e32 v39, 1, v39
	v_cmp_eq_u32_e32 vcc, 1, v39
	s_nop 1
	v_cndmask_b32_e64 v39, v171, 0, vcc
	v_add_u32_e32 v39, v103, v39
	ds_read_b128 v[40:43], v86 offset:3264
	ds_read_b128 v[44:47], v39
	s_and_b64 vcc, exec, s[0:1]
	s_waitcnt vmcnt(23) lgkmcnt(0)
	v_pk_fma_f32 v[34:35], v[42:43], v[46:47], v[118:119]
	v_pk_fma_f32 v[32:33], v[40:41], v[44:45], v[116:117]
	global_store_dwordx4 v[48:49], v[32:35], off
	s_cbranch_vccnz .LBB0_1272
	ds_read_b128 v[40:43], v39 offset:2048
	v_lshlrev_b64 v[36:37], 10, v[36:37]
	v_lshl_add_u64 v[36:37], v[36:37], 1, s[44:45]
	v_lshl_add_u64 v[36:37], v[98:99], 1, v[36:37]
	s_waitcnt lgkmcnt(0)
	v_pk_mul_f32 v[40:41], v[32:33], v[40:41]
	v_pk_mul_f32 v[32:33], v[32:33], v[32:33]
	v_pk_mul_f32 v[42:43], v[34:35], v[42:43]
	v_pk_mul_f32 v[34:35], v[34:35], v[34:35]
	v_add_f32_e32 v32, v32, v33
	v_add_f32_e32 v32, v34, v32
	v_add_f32_e32 v32, v35, v32
	v_cvt_pk_bf16_f32 v40, v40, v41
	v_cvt_pk_bf16_f32 v41, v42, v43
	v_add_f32_dpp v32, v32, v32 quad_perm:[1,0,3,2] row_mask:0xf bank_mask:0xf bound_ctrl:1
	global_store_dwordx2 v[36:37], v[40:41], off
	s_nop 0
	v_add_f32_dpp v32, v32, v32 quad_perm:[2,3,0,1] row_mask:0xf bank_mask:0xf bound_ctrl:1
	s_nop 1
	v_add_f32_dpp v32, v32, v32 row_half_mirror row_mask:0xf bank_mask:0xf bound_ctrl:1
	s_nop 1
	v_mov_b32_dpp v33, v32 row_mirror row_mask:0xf bank_mask:0xf bound_ctrl:1
	s_and_saveexec_b64 s[4:5], s[40:41]
	s_cbranch_execz .LBB0_1271
	v_mov_b32_e32 v75, v129
	v_ashrrev_i32_e32 v97, 31, v96
	v_lshl_add_u64 v[34:35], s[48:49], 0, v[68:69]
	v_lshl_add_u64 v[36:37], v[96:97], 0, v[74:75]
	v_lshl_add_u64 v[34:35], v[36:37], 2, v[34:35]
	v_add_f32_e32 v32, v32, v33
	global_store_dword v[34:35], v32, off offset:128

.LBB0_1272:
	v_or_b32_e32 v36, v66, v76
	v_ashrrev_i32_e32 v37, 31, v36
	v_lshlrev_b64 v[32:33], 12, v[36:37]
	v_lshl_add_u64 v[32:33], s[42:43], 0, v[32:33]
	v_lshl_add_u64 v[48:49], v[98:99], 2, v[32:33]
	s_movk_i32 s4, 0x1000
	v_cmp_gt_i32_e32 vcc, s4, v36
	s_nop 1
	v_cndmask_b32_e32 v39, v38, v102, vcc
	v_and_b32_e32 v39, 1, v39
	v_cmp_eq_u32_e32 vcc, 1, v39
	s_nop 1
	v_cndmask_b32_e64 v39, v171, 0, vcc
	v_add_u32_e32 v39, v103, v39
	ds_read_b128 v[40:43], v86 offset:4352
	ds_read_b128 v[44:47], v39
	s_and_b64 vcc, exec, s[0:1]
	s_waitcnt vmcnt(23) lgkmcnt(0)
	v_pk_fma_f32 v[34:35], v[42:43], v[46:47], v[122:123]
	v_pk_fma_f32 v[32:33], v[40:41], v[44:45], v[120:121]
	global_store_dwordx4 v[48:49], v[32:35], off
	s_cbranch_vccnz .LBB0_1276
	ds_read_b128 v[40:43], v39 offset:2048
	v_lshlrev_b64 v[36:37], 10, v[36:37]
	v_lshl_add_u64 v[36:37], v[36:37], 1, s[44:45]
	v_lshl_add_u64 v[36:37], v[98:99], 1, v[36:37]
	s_waitcnt lgkmcnt(0)
	v_pk_mul_f32 v[40:41], v[32:33], v[40:41]
	v_pk_mul_f32 v[32:33], v[32:33], v[32:33]
	v_pk_mul_f32 v[42:43], v[34:35], v[42:43]
	v_pk_mul_f32 v[34:35], v[34:35], v[34:35]
	v_add_f32_e32 v32, v32, v33
	v_add_f32_e32 v32, v34, v32
	v_add_f32_e32 v32, v35, v32
	v_cvt_pk_bf16_f32 v40, v40, v41
	v_cvt_pk_bf16_f32 v41, v42, v43
	v_add_f32_dpp v32, v32, v32 quad_perm:[1,0,3,2] row_mask:0xf bank_mask:0xf bound_ctrl:1
	global_store_dwordx2 v[36:37], v[40:41], off
	s_nop 0
	v_add_f32_dpp v32, v32, v32 quad_perm:[2,3,0,1] row_mask:0xf bank_mask:0xf bound_ctrl:1
	s_nop 1
	v_add_f32_dpp v32, v32, v32 row_half_mirror row_mask:0xf bank_mask:0xf bound_ctrl:1
	s_nop 1
	v_mov_b32_dpp v33, v32 row_mirror row_mask:0xf bank_mask:0xf bound_ctrl:1
	s_and_saveexec_b64 s[4:5], s[40:41]
	s_cbranch_execz .LBB0_1275
	v_mov_b32_e32 v77, v129
	v_ashrrev_i32_e32 v97, 31, v96
	v_lshl_add_u64 v[34:35], s[48:49], 0, v[68:69]
	v_lshl_add_u64 v[36:37], v[96:97], 0, v[76:77]
	v_lshl_add_u64 v[34:35], v[36:37], 2, v[34:35]
	v_add_f32_e32 v32, v32, v33
	global_store_dword v[34:35], v32, off offset:128

.LBB0_1276:
	v_or_b32_e32 v36, v66, v78
	v_ashrrev_i32_e32 v37, 31, v36
	v_lshlrev_b64 v[32:33], 12, v[36:37]
	v_lshl_add_u64 v[32:33], s[42:43], 0, v[32:33]
	v_lshl_add_u64 v[48:49], v[98:99], 2, v[32:33]
	s_movk_i32 s4, 0x1000
	v_cmp_gt_i32_e32 vcc, s4, v36
	s_nop 1
	v_cndmask_b32_e32 v39, v38, v102, vcc
	v_and_b32_e32 v39, 1, v39
	v_cmp_eq_u32_e32 vcc, 1, v39
	s_nop 1
	v_cndmask_b32_e64 v39, v171, 0, vcc
	v_add_u32_e32 v39, v103, v39
	ds_read_b128 v[40:43], v86 offset:5440
	ds_read_b128 v[44:47], v39
	s_and_b64 vcc, exec, s[0:1]
	s_waitcnt vmcnt(23) lgkmcnt(0)
	v_pk_fma_f32 v[34:35], v[42:43], v[46:47], v[126:127]
	v_pk_fma_f32 v[32:33], v[40:41], v[44:45], v[124:125]
	global_store_dwordx4 v[48:49], v[32:35], off
	s_cbranch_vccnz .LBB0_1280
	ds_read_b128 v[40:43], v39 offset:2048
	v_lshlrev_b64 v[36:37], 10, v[36:37]
	v_lshl_add_u64 v[36:37], v[36:37], 1, s[44:45]
	v_lshl_add_u64 v[36:37], v[98:99], 1, v[36:37]
	s_waitcnt lgkmcnt(0)
	v_pk_mul_f32 v[40:41], v[32:33], v[40:41]
	v_pk_mul_f32 v[32:33], v[32:33], v[32:33]
	v_pk_mul_f32 v[42:43], v[34:35], v[42:43]
	v_pk_mul_f32 v[34:35], v[34:35], v[34:35]
	v_add_f32_e32 v32, v32, v33
	v_add_f32_e32 v32, v34, v32
	v_add_f32_e32 v32, v35, v32
	v_cvt_pk_bf16_f32 v40, v40, v41
	v_cvt_pk_bf16_f32 v41, v42, v43
	v_add_f32_dpp v32, v32, v32 quad_perm:[1,0,3,2] row_mask:0xf bank_mask:0xf bound_ctrl:1
	global_store_dwordx2 v[36:37], v[40:41], off
	s_nop 0
	v_add_f32_dpp v32, v32, v32 quad_perm:[2,3,0,1] row_mask:0xf bank_mask:0xf bound_ctrl:1
	s_nop 1
	v_add_f32_dpp v32, v32, v32 row_half_mirror row_mask:0xf bank_mask:0xf bound_ctrl:1
	s_nop 1
	v_mov_b32_dpp v33, v32 row_mirror row_mask:0xf bank_mask:0xf bound_ctrl:1
	s_and_saveexec_b64 s[4:5], s[40:41]
	s_cbranch_execz .LBB0_1279
	v_mov_b32_e32 v79, v129
	v_ashrrev_i32_e32 v97, 31, v96
	v_lshl_add_u64 v[34:35], s[48:49], 0, v[68:69]
	v_lshl_add_u64 v[36:37], v[96:97], 0, v[78:79]
	v_lshl_add_u64 v[34:35], v[36:37], 2, v[34:35]
	v_add_f32_e32 v32, v32, v33
	global_store_dword v[34:35], v32, off offset:128

.LBB0_1280:
	v_or_b32_e32 v36, v66, v80
	v_ashrrev_i32_e32 v37, 31, v36
	v_lshlrev_b64 v[32:33], 12, v[36:37]
	v_lshl_add_u64 v[32:33], s[42:43], 0, v[32:33]
	v_lshl_add_u64 v[48:49], v[98:99], 2, v[32:33]
	s_movk_i32 s4, 0x1000
	v_cmp_gt_i32_e32 vcc, s4, v36
	s_nop 1
	v_cndmask_b32_e32 v39, v38, v102, vcc
	v_and_b32_e32 v39, 1, v39
	v_cmp_eq_u32_e32 vcc, 1, v39
	s_nop 1
	v_cndmask_b32_e64 v39, v171, 0, vcc
	v_add_u32_e32 v39, v103, v39
	ds_read_b128 v[40:43], v86 offset:6528
	ds_read_b128 v[44:47], v39
	s_and_b64 vcc, exec, s[0:1]
	s_waitcnt vmcnt(23) lgkmcnt(0)
	v_pk_fma_f32 v[34:35], v[42:43], v[46:47], v[132:133]
	v_pk_fma_f32 v[32:33], v[40:41], v[44:45], v[130:131]
	global_store_dwordx4 v[48:49], v[32:35], off
	s_cbranch_vccnz .LBB0_1284
	ds_read_b128 v[40:43], v39 offset:2048
	v_lshlrev_b64 v[36:37], 10, v[36:37]
	v_lshl_add_u64 v[36:37], v[36:37], 1, s[44:45]
	v_lshl_add_u64 v[36:37], v[98:99], 1, v[36:37]
	s_waitcnt lgkmcnt(0)
	v_pk_mul_f32 v[40:41], v[32:33], v[40:41]
	v_pk_mul_f32 v[32:33], v[32:33], v[32:33]
	v_pk_mul_f32 v[42:43], v[34:35], v[42:43]
	v_pk_mul_f32 v[34:35], v[34:35], v[34:35]
	v_add_f32_e32 v32, v32, v33
	v_add_f32_e32 v32, v34, v32
	v_add_f32_e32 v32, v35, v32
	v_cvt_pk_bf16_f32 v40, v40, v41
	v_cvt_pk_bf16_f32 v41, v42, v43
	v_add_f32_dpp v32, v32, v32 quad_perm:[1,0,3,2] row_mask:0xf bank_mask:0xf bound_ctrl:1
	global_store_dwordx2 v[36:37], v[40:41], off
	s_nop 0
	v_add_f32_dpp v32, v32, v32 quad_perm:[2,3,0,1] row_mask:0xf bank_mask:0xf bound_ctrl:1
	s_nop 1
	v_add_f32_dpp v32, v32, v32 row_half_mirror row_mask:0xf bank_mask:0xf bound_ctrl:1
	s_nop 1
	v_mov_b32_dpp v33, v32 row_mirror row_mask:0xf bank_mask:0xf bound_ctrl:1
	s_and_saveexec_b64 s[4:5], s[40:41]
	s_cbranch_execz .LBB0_1283
	v_mov_b32_e32 v81, v129
	v_ashrrev_i32_e32 v97, 31, v96
	v_lshl_add_u64 v[34:35], s[48:49], 0, v[68:69]
	v_lshl_add_u64 v[36:37], v[96:97], 0, v[80:81]
	v_lshl_add_u64 v[34:35], v[36:37], 2, v[34:35]
	v_add_f32_e32 v32, v32, v33
	global_store_dword v[34:35], v32, off offset:128

.LBB0_1284:
	v_or_b32_e32 v36, v66, v82
	v_ashrrev_i32_e32 v37, 31, v36
	v_lshlrev_b64 v[32:33], 12, v[36:37]
	v_lshl_add_u64 v[32:33], s[42:43], 0, v[32:33]
	v_lshl_add_u64 v[48:49], v[98:99], 2, v[32:33]
	s_movk_i32 s4, 0x1000
	v_cmp_gt_i32_e32 vcc, s4, v36
	s_nop 1
	v_cndmask_b32_e32 v38, v38, v102, vcc
	v_and_b32_e32 v38, 1, v38
	v_cmp_eq_u32_e32 vcc, 1, v38
	s_nop 1
	v_cndmask_b32_e64 v38, v171, 0, vcc
	v_add_u32_e32 v38, v103, v38
	ds_read_b128 v[40:43], v86 offset:7616
	ds_read_b128 v[44:47], v38
	s_and_b64 vcc, exec, s[0:1]
	s_waitcnt vmcnt(23) lgkmcnt(0)
	v_pk_fma_f32 v[34:35], v[42:43], v[46:47], v[136:137]
	v_pk_fma_f32 v[32:33], v[40:41], v[44:45], v[134:135]
	global_store_dwordx4 v[48:49], v[32:35], off
	s_cbranch_vccnz .LBB0_1288
	ds_read_b128 v[38:41], v38 offset:2048
	v_lshlrev_b64 v[36:37], 10, v[36:37]
	v_lshl_add_u64 v[36:37], v[36:37], 1, s[44:45]
	v_lshl_add_u64 v[36:37], v[98:99], 1, v[36:37]
	s_waitcnt lgkmcnt(0)
	v_pk_mul_f32 v[38:39], v[32:33], v[38:39]
	v_pk_mul_f32 v[32:33], v[32:33], v[32:33]
	v_pk_mul_f32 v[40:41], v[34:35], v[40:41]
	v_pk_mul_f32 v[34:35], v[34:35], v[34:35]
	v_add_f32_e32 v32, v32, v33
	v_add_f32_e32 v32, v34, v32
	v_add_f32_e32 v32, v35, v32
	v_cvt_pk_bf16_f32 v38, v38, v39
	v_cvt_pk_bf16_f32 v39, v40, v41
	v_add_f32_dpp v32, v32, v32 quad_perm:[1,0,3,2] row_mask:0xf bank_mask:0xf bound_ctrl:1
	global_store_dwordx2 v[36:37], v[38:39], off
	s_nop 0
	v_add_f32_dpp v32, v32, v32 quad_perm:[2,3,0,1] row_mask:0xf bank_mask:0xf bound_ctrl:1
	s_nop 1
	v_add_f32_dpp v32, v32, v32 row_half_mirror row_mask:0xf bank_mask:0xf bound_ctrl:1
	s_nop 1
	v_mov_b32_dpp v33, v32 row_mirror row_mask:0xf bank_mask:0xf bound_ctrl:1
	s_and_saveexec_b64 s[4:5], s[40:41]
	s_cbranch_execz .LBB0_1287
	v_mov_b32_e32 v83, v129
	v_ashrrev_i32_e32 v97, 31, v96
	v_lshl_add_u64 v[34:35], s[48:49], 0, v[68:69]
	v_lshl_add_u64 v[36:37], v[96:97], 0, v[82:83]
	v_lshl_add_u64 v[34:35], v[36:37], 2, v[34:35]
	v_add_f32_e32 v32, v32, v33
	global_store_dword v[34:35], v32, off offset:128

.LBB0_1288:
	s_nop 0
	v_add_u32_e32 v34, 64, v96
	v_or_b32_e32 v32, v34, v128
	v_ashrrev_i32_e32 v33, 31, v32
	v_lshlrev_b64 v[36:37], 12, v[32:33]
	v_lshl_add_u64 v[36:37], s[42:43], 0, v[36:37]
	v_lshl_add_u64 v[40:41], v[98:99], 2, v[36:37]
	ds_write_b128 v104, v[0:3]
	ds_write_b128 v104, v[4:7] offset:32
	ds_write_b128 v104, v[8:11] offset:64
	ds_write_b128 v104, v[12:15] offset:96
	ds_write_b128 v104, v[16:19] offset:128
	ds_write_b128 v104, v[20:23] offset:160
	ds_write_b128 v104, v[24:27] offset:192
	ds_write_b128 v104, v[28:31] offset:224
	v_add_u32_e32 v0, 0xfffff040, v96
	v_xor_b32_e32 v0, s7, v0
	s_movk_i32 s4, 0x400
	v_cmp_gt_u32_e32 vcc, s4, v0
	s_and_b64 s[2:3], s[2:3], vcc
	v_cndmask_b32_e64 v6, 0, 1, s[2:3]
	s_movk_i32 s2, 0x1000
	v_cmp_gt_i32_e32 vcc, s2, v32
	s_nop 1
	v_cndmask_b32_e32 v0, v6, v102, vcc
	v_and_b32_e32 v0, 1, v0
	v_cmp_eq_u32_e32 vcc, 1, v0
	s_nop 1
	v_cndmask_b32_e64 v0, v171, 0, vcc
	v_add_u32_e32 v4, v103, v0
	ds_read_b128 v[0:3], v86
	ds_read_b128 v[8:11], v4
	s_and_b64 vcc, exec, s[0:1]
	s_waitcnt vmcnt(15) lgkmcnt(0)
	v_pk_fma_f32 v[2:3], v[2:3], v[10:11], v[200:201]
	v_pk_fma_f32 v[0:1], v[0:1], v[8:9], v[198:199]
	global_store_dwordx4 v[40:41], v[0:3], off
	s_cbranch_vccnz .LBB0_1292
	ds_read_b128 v[8:11], v4 offset:2048
	v_lshlrev_b64 v[4:5], 10, v[32:33]
	v_lshl_add_u64 v[4:5], v[4:5], 1, s[44:45]
	v_lshl_add_u64 v[4:5], v[98:99], 1, v[4:5]
	s_waitcnt lgkmcnt(0)
	v_pk_mul_f32 v[8:9], v[0:1], v[8:9]
	v_pk_mul_f32 v[0:1], v[0:1], v[0:1]
	v_pk_mul_f32 v[10:11], v[2:3], v[10:11]
	v_pk_mul_f32 v[2:3], v[2:3], v[2:3]
	v_add_f32_e32 v0, v0, v1
	v_add_f32_e32 v0, v2, v0
	v_add_f32_e32 v0, v3, v0
	v_cvt_pk_bf16_f32 v8, v8, v9
	v_cvt_pk_bf16_f32 v9, v10, v11
	v_add_f32_dpp v0, v0, v0 quad_perm:[1,0,3,2] row_mask:0xf bank_mask:0xf bound_ctrl:1
	global_store_dwordx2 v[4:5], v[8:9], off
	s_nop 0
	v_add_f32_dpp v0, v0, v0 quad_perm:[2,3,0,1] row_mask:0xf bank_mask:0xf bound_ctrl:1
	s_nop 1
	v_add_f32_dpp v0, v0, v0 row_half_mirror row_mask:0xf bank_mask:0xf bound_ctrl:1
	s_nop 1
	v_mov_b32_dpp v1, v0 row_mirror row_mask:0xf bank_mask:0xf bound_ctrl:1
	s_and_saveexec_b64 s[2:3], s[40:41]
	s_cbranch_execz .LBB0_1291
	v_ashrrev_i32_e32 v97, 31, v96
	v_lshl_add_u64 v[2:3], s[48:49], 0, v[68:69]
	v_lshl_add_u64 v[4:5], v[96:97], 0, v[128:129]
	v_lshl_add_u64 v[2:3], v[4:5], 2, v[2:3]
	v_add_f32_e32 v0, v0, v1
	global_store_dword v[2:3], v0, off offset:256

.LBB0_1292:
	v_or_b32_e32 v4, v34, v70
	v_ashrrev_i32_e32 v5, 31, v4
	v_lshlrev_b64 v[0:1], 12, v[4:5]
	v_lshl_add_u64 v[0:1], s[42:43], 0, v[0:1]
	v_lshl_add_u64 v[16:17], v[98:99], 2, v[0:1]
	s_movk_i32 s2, 0x1000
	v_cmp_gt_i32_e32 vcc, s2, v4
	s_nop 1
	v_cndmask_b32_e32 v7, v6, v102, vcc
	v_and_b32_e32 v7, 1, v7
	v_cmp_eq_u32_e32 vcc, 1, v7
	s_nop 1
	v_cndmask_b32_e64 v7, v171, 0, vcc
	v_add_u32_e32 v7, v103, v7
	ds_read_b128 v[8:11], v86 offset:1088
	ds_read_b128 v[12:15], v7
	s_and_b64 vcc, exec, s[0:1]
	s_waitcnt vmcnt(15) lgkmcnt(0)
	v_pk_fma_f32 v[2:3], v[10:11], v[14:15], v[204:205]
	v_pk_fma_f32 v[0:1], v[8:9], v[12:13], v[202:203]
	global_store_dwordx4 v[16:17], v[0:3], off
	s_cbranch_vccnz .LBB0_1296
	ds_read_b128 v[8:11], v7 offset:2048
	v_lshlrev_b64 v[4:5], 10, v[4:5]
	v_lshl_add_u64 v[4:5], v[4:5], 1, s[44:45]
	v_lshl_add_u64 v[4:5], v[98:99], 1, v[4:5]
	s_waitcnt lgkmcnt(0)
	v_pk_mul_f32 v[8:9], v[0:1], v[8:9]
	v_pk_mul_f32 v[0:1], v[0:1], v[0:1]
	v_pk_mul_f32 v[10:11], v[2:3], v[10:11]
	v_pk_mul_f32 v[2:3], v[2:3], v[2:3]
	v_add_f32_e32 v0, v0, v1
	v_add_f32_e32 v0, v2, v0
	v_add_f32_e32 v0, v3, v0
	v_cvt_pk_bf16_f32 v8, v8, v9
	v_cvt_pk_bf16_f32 v9, v10, v11
	v_add_f32_dpp v0, v0, v0 quad_perm:[1,0,3,2] row_mask:0xf bank_mask:0xf bound_ctrl:1
	global_store_dwordx2 v[4:5], v[8:9], off
	s_nop 0
	v_add_f32_dpp v0, v0, v0 quad_perm:[2,3,0,1] row_mask:0xf bank_mask:0xf bound_ctrl:1
	s_nop 1
	v_add_f32_dpp v0, v0, v0 row_half_mirror row_mask:0xf bank_mask:0xf bound_ctrl:1
	s_nop 1
	v_mov_b32_dpp v1, v0 row_mirror row_mask:0xf bank_mask:0xf bound_ctrl:1
	s_and_saveexec_b64 s[2:3], s[40:41]
	s_cbranch_execz .LBB0_1295
	v_mov_b32_e32 v71, v129
	v_ashrrev_i32_e32 v97, 31, v96
	v_lshl_add_u64 v[2:3], s[48:49], 0, v[68:69]
	v_lshl_add_u64 v[4:5], v[96:97], 0, v[70:71]
	v_lshl_add_u64 v[2:3], v[4:5], 2, v[2:3]
	v_add_f32_e32 v0, v0, v1
	global_store_dword v[2:3], v0, off offset:256

.LBB0_1296:
	v_or_b32_e32 v4, v34, v72
	v_ashrrev_i32_e32 v5, 31, v4
	v_lshlrev_b64 v[0:1], 12, v[4:5]
	v_lshl_add_u64 v[0:1], s[42:43], 0, v[0:1]
	v_lshl_add_u64 v[16:17], v[98:99], 2, v[0:1]
	s_movk_i32 s2, 0x1000
	v_cmp_gt_i32_e32 vcc, s2, v4
	s_nop 1
	v_cndmask_b32_e32 v7, v6, v102, vcc
	v_and_b32_e32 v7, 1, v7
	v_cmp_eq_u32_e32 vcc, 1, v7
	s_nop 1
	v_cndmask_b32_e64 v7, v171, 0, vcc
	v_add_u32_e32 v7, v103, v7
	ds_read_b128 v[8:11], v86 offset:2176
	ds_read_b128 v[12:15], v7
	s_and_b64 vcc, exec, s[0:1]
	s_waitcnt vmcnt(15) lgkmcnt(0)
	v_pk_fma_f32 v[2:3], v[10:11], v[14:15], v[208:209]
	v_pk_fma_f32 v[0:1], v[8:9], v[12:13], v[206:207]
	global_store_dwordx4 v[16:17], v[0:3], off
	s_cbranch_vccnz .LBB0_1300
	ds_read_b128 v[8:11], v7 offset:2048
	v_lshlrev_b64 v[4:5], 10, v[4:5]
	v_lshl_add_u64 v[4:5], v[4:5], 1, s[44:45]
	v_lshl_add_u64 v[4:5], v[98:99], 1, v[4:5]
	s_waitcnt lgkmcnt(0)
	v_pk_mul_f32 v[8:9], v[0:1], v[8:9]
	v_pk_mul_f32 v[0:1], v[0:1], v[0:1]
	v_pk_mul_f32 v[10:11], v[2:3], v[10:11]
	v_pk_mul_f32 v[2:3], v[2:3], v[2:3]
	v_add_f32_e32 v0, v0, v1
	v_add_f32_e32 v0, v2, v0
	v_add_f32_e32 v0, v3, v0
	v_cvt_pk_bf16_f32 v8, v8, v9
	v_cvt_pk_bf16_f32 v9, v10, v11
	v_add_f32_dpp v0, v0, v0 quad_perm:[1,0,3,2] row_mask:0xf bank_mask:0xf bound_ctrl:1
	global_store_dwordx2 v[4:5], v[8:9], off
	s_nop 0
	v_add_f32_dpp v0, v0, v0 quad_perm:[2,3,0,1] row_mask:0xf bank_mask:0xf bound_ctrl:1
	s_nop 1
	v_add_f32_dpp v0, v0, v0 row_half_mirror row_mask:0xf bank_mask:0xf bound_ctrl:1
	s_nop 1
	v_mov_b32_dpp v1, v0 row_mirror row_mask:0xf bank_mask:0xf bound_ctrl:1
	s_and_saveexec_b64 s[2:3], s[40:41]
	s_cbranch_execz .LBB0_1299
	v_mov_b32_e32 v73, v129
	v_ashrrev_i32_e32 v97, 31, v96
	v_lshl_add_u64 v[2:3], s[48:49], 0, v[68:69]
	v_lshl_add_u64 v[4:5], v[96:97], 0, v[72:73]
	v_lshl_add_u64 v[2:3], v[4:5], 2, v[2:3]
	v_add_f32_e32 v0, v0, v1
	global_store_dword v[2:3], v0, off offset:256

.LBB0_1300:
	v_or_b32_e32 v4, v34, v74
	v_ashrrev_i32_e32 v5, 31, v4
	v_lshlrev_b64 v[0:1], 12, v[4:5]
	v_lshl_add_u64 v[0:1], s[42:43], 0, v[0:1]
	v_lshl_add_u64 v[16:17], v[98:99], 2, v[0:1]
	s_movk_i32 s2, 0x1000
	v_cmp_gt_i32_e32 vcc, s2, v4
	s_nop 1
	v_cndmask_b32_e32 v7, v6, v102, vcc
	v_and_b32_e32 v7, 1, v7
	v_cmp_eq_u32_e32 vcc, 1, v7
	s_nop 1
	v_cndmask_b32_e64 v7, v171, 0, vcc
	v_add_u32_e32 v7, v103, v7
	ds_read_b128 v[8:11], v86 offset:3264
	ds_read_b128 v[12:15], v7
	s_and_b64 vcc, exec, s[0:1]
	s_waitcnt vmcnt(15) lgkmcnt(0)
	v_pk_fma_f32 v[2:3], v[10:11], v[14:15], v[212:213]
	v_pk_fma_f32 v[0:1], v[8:9], v[12:13], v[210:211]
	global_store_dwordx4 v[16:17], v[0:3], off
	s_cbranch_vccnz .LBB0_1304
	ds_read_b128 v[8:11], v7 offset:2048
	v_lshlrev_b64 v[4:5], 10, v[4:5]
	v_lshl_add_u64 v[4:5], v[4:5], 1, s[44:45]
	v_lshl_add_u64 v[4:5], v[98:99], 1, v[4:5]
	s_waitcnt lgkmcnt(0)
	v_pk_mul_f32 v[8:9], v[0:1], v[8:9]
	v_pk_mul_f32 v[0:1], v[0:1], v[0:1]
	v_pk_mul_f32 v[10:11], v[2:3], v[10:11]
	v_pk_mul_f32 v[2:3], v[2:3], v[2:3]
	v_add_f32_e32 v0, v0, v1
	v_add_f32_e32 v0, v2, v0
	v_add_f32_e32 v0, v3, v0
	v_cvt_pk_bf16_f32 v8, v8, v9
	v_cvt_pk_bf16_f32 v9, v10, v11
	v_add_f32_dpp v0, v0, v0 quad_perm:[1,0,3,2] row_mask:0xf bank_mask:0xf bound_ctrl:1
	global_store_dwordx2 v[4:5], v[8:9], off
	s_nop 0
	v_add_f32_dpp v0, v0, v0 quad_perm:[2,3,0,1] row_mask:0xf bank_mask:0xf bound_ctrl:1
	s_nop 1
	v_add_f32_dpp v0, v0, v0 row_half_mirror row_mask:0xf bank_mask:0xf bound_ctrl:1
	s_nop 1
	v_mov_b32_dpp v1, v0 row_mirror row_mask:0xf bank_mask:0xf bound_ctrl:1
	s_and_saveexec_b64 s[2:3], s[40:41]
	s_cbranch_execz .LBB0_1303
	v_mov_b32_e32 v75, v129
	v_ashrrev_i32_e32 v97, 31, v96
	v_lshl_add_u64 v[2:3], s[48:49], 0, v[68:69]
	v_lshl_add_u64 v[4:5], v[96:97], 0, v[74:75]
	v_lshl_add_u64 v[2:3], v[4:5], 2, v[2:3]
	v_add_f32_e32 v0, v0, v1
	global_store_dword v[2:3], v0, off offset:256

.LBB0_1304:
	v_or_b32_e32 v4, v34, v76
	v_ashrrev_i32_e32 v5, 31, v4
	v_lshlrev_b64 v[0:1], 12, v[4:5]
	v_lshl_add_u64 v[0:1], s[42:43], 0, v[0:1]
	v_lshl_add_u64 v[16:17], v[98:99], 2, v[0:1]
	s_movk_i32 s2, 0x1000
	v_cmp_gt_i32_e32 vcc, s2, v4
	s_nop 1
	v_cndmask_b32_e32 v7, v6, v102, vcc
	v_and_b32_e32 v7, 1, v7
	v_cmp_eq_u32_e32 vcc, 1, v7
	s_nop 1
	v_cndmask_b32_e64 v7, v171, 0, vcc
	v_add_u32_e32 v7, v103, v7
	ds_read_b128 v[8:11], v86 offset:4352
	ds_read_b128 v[12:15], v7
	s_and_b64 vcc, exec, s[0:1]
	s_waitcnt vmcnt(15) lgkmcnt(0)
	v_pk_fma_f32 v[2:3], v[10:11], v[14:15], v[216:217]
	v_pk_fma_f32 v[0:1], v[8:9], v[12:13], v[214:215]
	global_store_dwordx4 v[16:17], v[0:3], off
	s_cbranch_vccnz .LBB0_1308
	ds_read_b128 v[8:11], v7 offset:2048
	v_lshlrev_b64 v[4:5], 10, v[4:5]
	v_lshl_add_u64 v[4:5], v[4:5], 1, s[44:45]
	v_lshl_add_u64 v[4:5], v[98:99], 1, v[4:5]
	s_waitcnt lgkmcnt(0)
	v_pk_mul_f32 v[8:9], v[0:1], v[8:9]
	v_pk_mul_f32 v[0:1], v[0:1], v[0:1]
	v_pk_mul_f32 v[10:11], v[2:3], v[10:11]
	v_pk_mul_f32 v[2:3], v[2:3], v[2:3]
	v_add_f32_e32 v0, v0, v1
	v_add_f32_e32 v0, v2, v0
	v_add_f32_e32 v0, v3, v0
	v_cvt_pk_bf16_f32 v8, v8, v9
	v_cvt_pk_bf16_f32 v9, v10, v11
	v_add_f32_dpp v0, v0, v0 quad_perm:[1,0,3,2] row_mask:0xf bank_mask:0xf bound_ctrl:1
	global_store_dwordx2 v[4:5], v[8:9], off
	s_nop 0
	v_add_f32_dpp v0, v0, v0 quad_perm:[2,3,0,1] row_mask:0xf bank_mask:0xf bound_ctrl:1
	s_nop 1
	v_add_f32_dpp v0, v0, v0 row_half_mirror row_mask:0xf bank_mask:0xf bound_ctrl:1
	s_nop 1
	v_mov_b32_dpp v1, v0 row_mirror row_mask:0xf bank_mask:0xf bound_ctrl:1
	s_and_saveexec_b64 s[2:3], s[40:41]
	s_cbranch_execz .LBB0_1307
	v_mov_b32_e32 v77, v129
	v_ashrrev_i32_e32 v97, 31, v96
	v_lshl_add_u64 v[2:3], s[48:49], 0, v[68:69]
	v_lshl_add_u64 v[4:5], v[96:97], 0, v[76:77]
	v_lshl_add_u64 v[2:3], v[4:5], 2, v[2:3]
	v_add_f32_e32 v0, v0, v1
	global_store_dword v[2:3], v0, off offset:256

.LBB0_1308:
	v_or_b32_e32 v4, v34, v78
	v_ashrrev_i32_e32 v5, 31, v4
	v_lshlrev_b64 v[0:1], 12, v[4:5]
	v_lshl_add_u64 v[0:1], s[42:43], 0, v[0:1]
	v_lshl_add_u64 v[16:17], v[98:99], 2, v[0:1]
	s_movk_i32 s2, 0x1000
	v_cmp_gt_i32_e32 vcc, s2, v4
	s_nop 1
	v_cndmask_b32_e32 v7, v6, v102, vcc
	v_and_b32_e32 v7, 1, v7
	v_cmp_eq_u32_e32 vcc, 1, v7
	s_nop 1
	v_cndmask_b32_e64 v7, v171, 0, vcc
	v_add_u32_e32 v7, v103, v7
	ds_read_b128 v[8:11], v86 offset:5440
	ds_read_b128 v[12:15], v7
	s_and_b64 vcc, exec, s[0:1]
	s_waitcnt vmcnt(15) lgkmcnt(0)
	v_pk_fma_f32 v[2:3], v[10:11], v[14:15], v[220:221]
	v_pk_fma_f32 v[0:1], v[8:9], v[12:13], v[218:219]
	global_store_dwordx4 v[16:17], v[0:3], off
	s_cbranch_vccnz .LBB0_1312
	ds_read_b128 v[8:11], v7 offset:2048
	v_lshlrev_b64 v[4:5], 10, v[4:5]
	v_lshl_add_u64 v[4:5], v[4:5], 1, s[44:45]
	v_lshl_add_u64 v[4:5], v[98:99], 1, v[4:5]
	s_waitcnt lgkmcnt(0)
	v_pk_mul_f32 v[8:9], v[0:1], v[8:9]
	v_pk_mul_f32 v[0:1], v[0:1], v[0:1]
	v_pk_mul_f32 v[10:11], v[2:3], v[10:11]
	v_pk_mul_f32 v[2:3], v[2:3], v[2:3]
	v_add_f32_e32 v0, v0, v1
	v_add_f32_e32 v0, v2, v0
	v_add_f32_e32 v0, v3, v0
	v_cvt_pk_bf16_f32 v8, v8, v9
	v_cvt_pk_bf16_f32 v9, v10, v11
	v_add_f32_dpp v0, v0, v0 quad_perm:[1,0,3,2] row_mask:0xf bank_mask:0xf bound_ctrl:1
	global_store_dwordx2 v[4:5], v[8:9], off
	s_nop 0
	v_add_f32_dpp v0, v0, v0 quad_perm:[2,3,0,1] row_mask:0xf bank_mask:0xf bound_ctrl:1
	s_nop 1
	v_add_f32_dpp v0, v0, v0 row_half_mirror row_mask:0xf bank_mask:0xf bound_ctrl:1
	s_nop 1
	v_mov_b32_dpp v1, v0 row_mirror row_mask:0xf bank_mask:0xf bound_ctrl:1
	s_and_saveexec_b64 s[2:3], s[40:41]
	s_cbranch_execz .LBB0_1311
	v_mov_b32_e32 v79, v129
	v_ashrrev_i32_e32 v97, 31, v96
	v_lshl_add_u64 v[2:3], s[48:49], 0, v[68:69]
	v_lshl_add_u64 v[4:5], v[96:97], 0, v[78:79]
	v_lshl_add_u64 v[2:3], v[4:5], 2, v[2:3]
	v_add_f32_e32 v0, v0, v1
	global_store_dword v[2:3], v0, off offset:256

.LBB0_1312:
	v_or_b32_e32 v4, v34, v80
	v_ashrrev_i32_e32 v5, 31, v4
	v_lshlrev_b64 v[0:1], 12, v[4:5]
	v_lshl_add_u64 v[0:1], s[42:43], 0, v[0:1]
	v_lshl_add_u64 v[16:17], v[98:99], 2, v[0:1]
	s_movk_i32 s2, 0x1000
	v_cmp_gt_i32_e32 vcc, s2, v4
	s_nop 1
	v_cndmask_b32_e32 v7, v6, v102, vcc
	v_and_b32_e32 v7, 1, v7
	v_cmp_eq_u32_e32 vcc, 1, v7
	s_nop 1
	v_cndmask_b32_e64 v7, v171, 0, vcc
	v_add_u32_e32 v7, v103, v7
	ds_read_b128 v[8:11], v86 offset:6528
	ds_read_b128 v[12:15], v7
	s_and_b64 vcc, exec, s[0:1]
	s_waitcnt vmcnt(15) lgkmcnt(0)
	v_pk_fma_f32 v[2:3], v[10:11], v[14:15], v[224:225]
	v_pk_fma_f32 v[0:1], v[8:9], v[12:13], v[222:223]
	global_store_dwordx4 v[16:17], v[0:3], off
	s_cbranch_vccnz .LBB0_1316
	ds_read_b128 v[8:11], v7 offset:2048
	v_lshlrev_b64 v[4:5], 10, v[4:5]
	v_lshl_add_u64 v[4:5], v[4:5], 1, s[44:45]
	v_lshl_add_u64 v[4:5], v[98:99], 1, v[4:5]
	s_waitcnt lgkmcnt(0)
	v_pk_mul_f32 v[8:9], v[0:1], v[8:9]
	v_pk_mul_f32 v[0:1], v[0:1], v[0:1]
	v_pk_mul_f32 v[10:11], v[2:3], v[10:11]
	v_pk_mul_f32 v[2:3], v[2:3], v[2:3]
	v_add_f32_e32 v0, v0, v1
	v_add_f32_e32 v0, v2, v0
	v_add_f32_e32 v0, v3, v0
	v_cvt_pk_bf16_f32 v8, v8, v9
	v_cvt_pk_bf16_f32 v9, v10, v11
	v_add_f32_dpp v0, v0, v0 quad_perm:[1,0,3,2] row_mask:0xf bank_mask:0xf bound_ctrl:1
	global_store_dwordx2 v[4:5], v[8:9], off
	s_nop 0
	v_add_f32_dpp v0, v0, v0 quad_perm:[2,3,0,1] row_mask:0xf bank_mask:0xf bound_ctrl:1
	s_nop 1
	v_add_f32_dpp v0, v0, v0 row_half_mirror row_mask:0xf bank_mask:0xf bound_ctrl:1
	s_nop 1
	v_mov_b32_dpp v1, v0 row_mirror row_mask:0xf bank_mask:0xf bound_ctrl:1
	s_and_saveexec_b64 s[2:3], s[40:41]
	s_cbranch_execz .LBB0_1315
	v_mov_b32_e32 v81, v129
	v_ashrrev_i32_e32 v97, 31, v96
	v_lshl_add_u64 v[2:3], s[48:49], 0, v[68:69]
	v_lshl_add_u64 v[4:5], v[96:97], 0, v[80:81]
	v_lshl_add_u64 v[2:3], v[4:5], 2, v[2:3]
	v_add_f32_e32 v0, v0, v1
	global_store_dword v[2:3], v0, off offset:256

.LBB0_1316:
	v_or_b32_e32 v4, v34, v82
	v_ashrrev_i32_e32 v5, 31, v4
	v_lshlrev_b64 v[0:1], 12, v[4:5]
	v_lshl_add_u64 v[0:1], s[42:43], 0, v[0:1]
	v_lshl_add_u64 v[16:17], v[98:99], 2, v[0:1]
	s_movk_i32 s2, 0x1000
	v_cmp_gt_i32_e32 vcc, s2, v4
	s_nop 1
	v_cndmask_b32_e32 v6, v6, v102, vcc
	v_and_b32_e32 v6, 1, v6
	v_cmp_eq_u32_e32 vcc, 1, v6
	s_nop 1
	v_cndmask_b32_e64 v6, v171, 0, vcc
	v_add_u32_e32 v6, v103, v6
	ds_read_b128 v[8:11], v86 offset:7616
	ds_read_b128 v[12:15], v6
	s_and_b64 vcc, exec, s[0:1]
	s_waitcnt vmcnt(15) lgkmcnt(0)
	v_pk_fma_f32 v[2:3], v[10:11], v[14:15], v[228:229]
	v_pk_fma_f32 v[0:1], v[8:9], v[12:13], v[226:227]
	global_store_dwordx4 v[16:17], v[0:3], off
	s_cbranch_vccnz .LBB0_1219
	ds_read_b128 v[6:9], v6 offset:2048
	v_lshlrev_b64 v[4:5], 10, v[4:5]
	v_lshl_add_u64 v[4:5], v[4:5], 1, s[44:45]
	v_lshl_add_u64 v[4:5], v[98:99], 1, v[4:5]
	s_waitcnt lgkmcnt(0)
	v_pk_mul_f32 v[6:7], v[0:1], v[6:7]
	v_pk_mul_f32 v[0:1], v[0:1], v[0:1]
	v_pk_mul_f32 v[8:9], v[2:3], v[8:9]
	v_pk_mul_f32 v[2:3], v[2:3], v[2:3]
	v_add_f32_e32 v0, v0, v1
	v_add_f32_e32 v0, v2, v0
	v_add_f32_e32 v0, v3, v0
	v_cvt_pk_bf16_f32 v6, v6, v7
	v_cvt_pk_bf16_f32 v7, v8, v9
	v_add_f32_dpp v0, v0, v0 quad_perm:[1,0,3,2] row_mask:0xf bank_mask:0xf bound_ctrl:1
	global_store_dwordx2 v[4:5], v[6:7], off
	s_nop 0
	v_add_f32_dpp v0, v0, v0 quad_perm:[2,3,0,1] row_mask:0xf bank_mask:0xf bound_ctrl:1
	s_nop 1
	v_add_f32_dpp v0, v0, v0 row_half_mirror row_mask:0xf bank_mask:0xf bound_ctrl:1
	s_nop 1
	v_mov_b32_dpp v1, v0 row_mirror row_mask:0xf bank_mask:0xf bound_ctrl:1
	s_and_saveexec_b64 s[0:1], s[40:41]
	s_cbranch_execz .LBB0_1218
	v_mov_b32_e32 v83, v129
	v_ashrrev_i32_e32 v97, 31, v96
	v_lshl_add_u64 v[2:3], s[48:49], 0, v[68:69]
	v_lshl_add_u64 v[4:5], v[96:97], 0, v[82:83]
	v_lshl_add_u64 v[2:3], v[4:5], 2, v[2:3]
	v_add_f32_e32 v0, v0, v1
	global_store_dword v[2:3], v0, off offset:256
	s_branch .LBB0_1218

.LBB0_1434:
	s_add_i32 s9, s7, 1
	s_bitcmp1_b32 s9, 0
	s_cselect_b32 s10, 0xe000, 0
	v_add_u32_e32 v115, s10, v109
	v_lshl_add_u64 v[116:117], v[98:99], 0, s[2:3]
	s_mov_b64 s[10:11], 0x9f94080
	v_lshl_add_u64 v[118:119], v[116:117], 0, s[10:11]
	v_readfirstlane_b32 s10, v115
	s_mov_b32 m0, s10
	s_mov_b64 s[10:11], 0xa014080
	v_add_u32_e32 v120, 0x2000, v115
	s_waitcnt vmcnt(0)
	s_waitcnt vmcnt(0) lgkmcnt(0)
	s_barrier
	global_load_lds_dwordx4 v[118:119], off
	v_lshl_add_u64 v[118:119], v[116:117], 0, s[10:11]
	v_readfirstlane_b32 s10, v120
	s_mov_b32 m0, s10
	s_mov_b64 s[10:11], 0xa094080
	global_load_lds_dwordx4 v[118:119], off
	v_add_u32_e32 v118, 0x4000, v115
	v_lshl_add_u64 v[116:117], v[116:117], 0, s[10:11]
	v_readfirstlane_b32 s10, v118
	s_mov_b32 m0, s10
	s_mov_b64 s[10:11], 0x3314080
	global_load_lds_dwordx4 v[116:117], off
	v_lshl_add_u64 v[116:117], v[96:97], 0, s[2:3]
	v_add_u32_e32 v120, 0x6000, v115
	v_lshl_add_u64 v[118:119], v[116:117], 0, s[10:11]
	v_readfirstlane_b32 s10, v120
	s_mov_b32 m0, s10
	s_mov_b64 s[10:11], 0x3394080
	v_add_u32_e32 v120, 0x8000, v115
	global_load_lds_dwordx4 v[118:119], off
	v_lshl_add_u64 v[118:119], v[116:117], 0, s[10:11]
	v_readfirstlane_b32 s10, v120
	s_mov_b32 m0, s10
	s_mov_b64 s[10:11], 0x3414080
	v_add_u32_e32 v120, 0xa000, v115
	global_load_lds_dwordx4 v[118:119], off
	v_lshl_add_u64 v[118:119], v[116:117], 0, s[10:11]
	v_readfirstlane_b32 s10, v120
	s_mov_b32 m0, s10
	s_mov_b64 s[10:11], 0x3494080
	v_add_u32_e32 v115, 0xc000, v115
	v_lshl_add_u64 v[116:117], v[116:117], 0, s[10:11]
	v_readfirstlane_b32 s10, v115
	global_load_lds_dwordx4 v[118:119], off
	s_mov_b32 m0, s10
	s_nop 0
	global_load_lds_dwordx4 v[116:117], off
	s_bitcmp1_b32 s7, 0
	s_cselect_b32 s7, 0xe000, 0
	v_add_u32_e32 v115, s7, v114
	v_add_u32_e32 v120, v115, v111
	ds_read_b128 v[116:119], v120 offset:0
	v_add_u32_e32 v128, s7, v113
	ds_read_b128 v[120:123], v120 offset:0x1000
	v_add_u32_e32 v134, v128, v111
	ds_read_b128 v[124:127], v134 offset:0
	ds_read_b128 v[130:133], v134 offset:0x1000
	ds_read_b128 v[134:137], v134 offset:0x2000
	v_add_u32_e32 v148, v115, v110
	ds_read_b128 v[144:147], v148 offset:0
	ds_read_b128 v[148:151], v148 offset:0x1000
	v_add_u32_e32 v152, v128, v110
	ds_read_b128 v[182:185], v152 offset:0
	ds_read_b128 v[186:189], v152 offset:0x1000
	ds_read_b128 v[190:193], v152 offset:0x2000
	s_waitcnt lgkmcnt(5)
	s_nop 0
	v_mfma_f32_32x32x16_bf16 v[64:79], v[116:119], v[124:127], v[64:79]
	v_mfma_f32_32x32x16_bf16 v[32:47], v[116:119], v[130:133], v[32:47]
	v_mfma_f32_32x32x16_bf16 v[0:15], v[116:119], v[134:137], v[0:15]
	v_mfma_f32_32x32x16_bf16 v[80:95], v[120:123], v[124:127], v[80:95]
	v_mfma_f32_32x32x16_bf16 v[48:63], v[120:123], v[130:133], v[48:63]
	v_mfma_f32_32x32x16_bf16 v[16:31], v[120:123], v[134:137], v[16:31]
	v_add_u32_e32 v120, v115, v108
	ds_read_b128 v[116:119], v120 offset:0
	ds_read_b128 v[120:123], v120 offset:0x1000
	v_add_u32_e32 v134, v128, v108
	ds_read_b128 v[124:127], v134 offset:0
	ds_read_b128 v[130:133], v134 offset:0x1000
	ds_read_b128 v[134:137], v134 offset:0x2000
	s_waitcnt lgkmcnt(5)
	s_nop 0
	v_mfma_f32_32x32x16_bf16 v[64:79], v[144:147], v[182:185], v[64:79]
	v_mfma_f32_32x32x16_bf16 v[32:47], v[144:147], v[186:189], v[32:47]
	v_mfma_f32_32x32x16_bf16 v[0:15], v[144:147], v[190:193], v[0:15]
	v_mfma_f32_32x32x16_bf16 v[80:95], v[148:151], v[182:185], v[80:95]
	v_mfma_f32_32x32x16_bf16 v[48:63], v[148:151], v[186:189], v[48:63]
	v_mfma_f32_32x32x16_bf16 v[16:31], v[148:151], v[190:193], v[16:31]
	v_add_u32_e32 v115, v115, v107
	ds_read_b128 v[144:147], v115 offset:0
	ds_read_b128 v[148:151], v115 offset:0x1000
	v_add_u32_e32 v115, v128, v107
	ds_read_b128 v[182:185], v115 offset:0
	ds_read_b128 v[186:189], v115 offset:0x1000
	ds_read_b128 v[190:193], v115 offset:0x2000
	s_waitcnt lgkmcnt(5)
	s_nop 0
	v_mfma_f32_32x32x16_bf16 v[64:79], v[116:119], v[124:127], v[64:79]
	v_mfma_f32_32x32x16_bf16 v[32:47], v[116:119], v[130:133], v[32:47]
	v_mfma_f32_32x32x16_bf16 v[0:15], v[116:119], v[134:137], v[0:15]
	v_mfma_f32_32x32x16_bf16 v[80:95], v[120:123], v[124:127], v[80:95]
	v_mfma_f32_32x32x16_bf16 v[48:63], v[120:123], v[130:133], v[48:63]
	v_mfma_f32_32x32x16_bf16 v[16:31], v[120:123], v[134:137], v[16:31]
	s_waitcnt lgkmcnt(0)
	s_nop 0
	v_mfma_f32_32x32x16_bf16 v[64:79], v[144:147], v[182:185], v[64:79]
	v_mfma_f32_32x32x16_bf16 v[32:47], v[144:147], v[186:189], v[32:47]
	v_mfma_f32_32x32x16_bf16 v[0:15], v[144:147], v[190:193], v[0:15]
	v_mfma_f32_32x32x16_bf16 v[80:95], v[148:151], v[182:185], v[80:95]
	v_mfma_f32_32x32x16_bf16 v[48:63], v[148:151], v[186:189], v[48:63]
	v_mfma_f32_32x32x16_bf16 v[16:31], v[148:151], v[190:193], v[16:31]
	s_add_u32 s2, s2, 0x80
	s_addc_u32 s3, s3, 0
	s_cmpk_eq_i32 s2, 0x1f80
	s_mov_b32 s7, s9
	s_cbranch_scc0 .LBB0_1434
	s_waitcnt vmcnt(0)
	s_waitcnt vmcnt(0) lgkmcnt(0)
	s_barrier
	v_add_u32_e32 v109, 0x14000, v112
	v_add_u32_e32 v112, v109, v111
	ds_read_b128 v[96:99], v112 offset:0
	v_add_u32_e32 v128, 0xe000, v113
	ds_read_b128 v[112:115], v112 offset:0x1000
	v_add_u32_e32 v111, v128, v111
	ds_read_b128 v[116:119], v111 offset:0
	ds_read_b128 v[120:123], v111 offset:0x1000
	ds_read_b128 v[124:127], v111 offset:0x2000
	v_add_u32_e32 v111, v109, v110
	ds_read_b128 v[130:133], v111 offset:0
	ds_read_b128 v[134:137], v111 offset:0x1000
	v_add_u32_e32 v110, v128, v110
	ds_read_b128 v[144:147], v110 offset:0
	ds_read_b128 v[148:151], v110 offset:0x1000
	ds_read_b128 v[182:185], v110 offset:0x2000
	s_waitcnt lgkmcnt(5)
	s_nop 0
	v_mfma_f32_32x32x16_bf16 v[64:79], v[96:99], v[116:119], v[64:79]
	v_mfma_f32_32x32x16_bf16 v[32:47], v[96:99], v[120:123], v[32:47]
	v_mfma_f32_32x32x16_bf16 v[0:15], v[96:99], v[124:127], v[0:15]
	v_mfma_f32_32x32x16_bf16 v[48:63], v[112:115], v[120:123], v[48:63]
	v_mfma_f32_32x32x16_bf16 v[16:31], v[112:115], v[124:127], v[16:31]
	v_mfma_f32_32x32x16_bf16 v[80:95], v[112:115], v[116:119], v[80:95]
	v_add_u32_e32 v110, v109, v108
	ds_read_b128 v[96:99], v110 offset:0
	ds_read_b128 v[110:113], v110 offset:0x1000
	v_add_u32_e32 v108, v128, v108
	ds_read_b128 v[114:117], v108 offset:0
	ds_read_b128 v[118:121], v108 offset:0x1000
	ds_read_b128 v[122:125], v108 offset:0x2000
	s_waitcnt lgkmcnt(5)
	s_nop 0
	v_mfma_f32_32x32x16_bf16 v[64:79], v[130:133], v[144:147], v[64:79]
	v_mfma_f32_32x32x16_bf16 v[32:47], v[130:133], v[148:151], v[32:47]
	v_mfma_f32_32x32x16_bf16 v[0:15], v[130:133], v[182:185], v[0:15]
	v_mfma_f32_32x32x16_bf16 v[48:63], v[134:137], v[148:151], v[48:63]
	v_mfma_f32_32x32x16_bf16 v[16:31], v[134:137], v[182:185], v[16:31]
	v_mfma_f32_32x32x16_bf16 v[80:95], v[134:137], v[144:147], v[80:95]
	v_add_u32_e32 v108, v109, v107
	ds_read_b128 v[130:133], v108 offset:0
	ds_read_b128 v[134:137], v108 offset:0x1000
	v_add_u32_e32 v107, v128, v107
	ds_read_b128 v[144:147], v107 offset:0
	ds_read_b128 v[148:151], v107 offset:0x1000
	ds_read_b128 v[182:185], v107 offset:0x2000
	s_waitcnt lgkmcnt(5)
	s_nop 0
	v_mfma_f32_32x32x16_bf16 v[64:79], v[96:99], v[114:117], v[64:79]
	v_mfma_f32_32x32x16_bf16 v[32:47], v[96:99], v[118:121], v[32:47]
	v_mfma_f32_32x32x16_bf16 v[0:15], v[96:99], v[122:125], v[0:15]
	v_mfma_f32_32x32x16_bf16 v[48:63], v[110:113], v[118:121], v[48:63]
	v_mfma_f32_32x32x16_bf16 v[16:31], v[110:113], v[122:125], v[16:31]
	v_mfma_f32_32x32x16_bf16 v[80:95], v[110:113], v[114:117], v[80:95]
	s_waitcnt lgkmcnt(0)
	s_nop 0
	v_mfma_f32_32x32x16_bf16 v[64:79], v[130:133], v[144:147], v[64:79]
	v_mfma_f32_32x32x16_bf16 v[32:47], v[130:133], v[148:151], v[32:47]
	v_mfma_f32_32x32x16_bf16 v[0:15], v[130:133], v[182:185], v[0:15]
	v_mfma_f32_32x32x16_bf16 v[48:63], v[134:137], v[148:151], v[48:63]
	v_mfma_f32_32x32x16_bf16 v[16:31], v[134:137], v[182:185], v[16:31]
	v_mfma_f32_32x32x16_bf16 v[80:95], v[134:137], v[144:147], v[80:95]
	v_add_u32_e32 v96, s4, v106
	v_lshrrev_b32_e32 v128, 4, v101
	v_and_b32_e32 v112, 15, v100
	v_or_b32_e32 v100, v96, v128
	v_add_u32_e32 v105, s8, v105
	v_ashrrev_i32_e32 v101, 31, v100
	v_lshl_or_b32 v98, v112, 2, v105
	v_lshlrev_b64 v[106:107], 12, v[100:101]
	v_ashrrev_i32_e32 v99, 31, v98
	v_lshl_add_u64 v[106:107], s[40:41], 0, v[106:107]
	v_lshl_add_u64 v[110:111], v[98:99], 2, v[106:107]
	s_barrier
	global_load_dwordx4 v[198:201], v[110:111], off
	v_add_co_u32_e32 v182, vcc, 0x4000, v110
	s_nop 1
	v_addc_co_u32_e32 v183, vcc, 0, v111, vcc
	global_load_dwordx4 v[202:205], v[182:183], off
	v_add_co_u32_e32 v182, vcc, 0x4000, v182
	s_nop 1
	v_addc_co_u32_e32 v183, vcc, 0, v183, vcc
	global_load_dwordx4 v[206:209], v[182:183], off
	v_add_co_u32_e32 v182, vcc, 0x4000, v182
	s_nop 1
	v_addc_co_u32_e32 v183, vcc, 0, v183, vcc
	global_load_dwordx4 v[210:213], v[182:183], off
	v_add_co_u32_e32 v182, vcc, 0x4000, v182
	s_nop 1
	v_addc_co_u32_e32 v183, vcc, 0, v183, vcc
	global_load_dwordx4 v[214:217], v[182:183], off
	v_add_co_u32_e32 v182, vcc, 0x4000, v182
	s_nop 1
	v_addc_co_u32_e32 v183, vcc, 0, v183, vcc
	global_load_dwordx4 v[218:221], v[182:183], off
	v_add_co_u32_e32 v182, vcc, 0x4000, v182
	s_nop 1
	v_addc_co_u32_e32 v183, vcc, 0, v183, vcc
	global_load_dwordx4 v[222:225], v[182:183], off
	v_add_co_u32_e32 v182, vcc, 0x4000, v182
	s_nop 1
	v_addc_co_u32_e32 v183, vcc, 0, v183, vcc
	global_load_dwordx4 v[226:229], v[182:183], off
	v_add_co_u32_e32 v182, vcc, 0x4000, v182
	s_nop 1
	v_addc_co_u32_e32 v183, vcc, 0, v183, vcc
	global_load_dwordx4 v[184:187], v[182:183], off
	v_add_co_u32_e32 v182, vcc, 0x4000, v182
	s_nop 1
	v_addc_co_u32_e32 v183, vcc, 0, v183, vcc
	global_load_dwordx4 v[188:191], v[182:183], off
	v_add_co_u32_e32 v182, vcc, 0x4000, v182
	s_nop 1
	v_addc_co_u32_e32 v183, vcc, 0, v183, vcc
	global_load_dwordx4 v[192:195], v[182:183], off
	v_add_co_u32_e32 v182, vcc, 0x4000, v182
	s_nop 1
	v_addc_co_u32_e32 v183, vcc, 0, v183, vcc
	global_load_dwordx4 v[116:119], v[182:183], off
	v_add_co_u32_e32 v182, vcc, 0x4000, v182
	s_nop 1
	v_addc_co_u32_e32 v183, vcc, 0, v183, vcc
	global_load_dwordx4 v[120:123], v[182:183], off
	v_add_co_u32_e32 v182, vcc, 0x4000, v182
	s_nop 1
	v_addc_co_u32_e32 v183, vcc, 0, v183, vcc
	global_load_dwordx4 v[124:127], v[182:183], off
	v_add_co_u32_e32 v182, vcc, 0x4000, v182
	s_nop 1
	v_addc_co_u32_e32 v183, vcc, 0, v183, vcc
	global_load_dwordx4 v[130:133], v[182:183], off
	v_add_co_u32_e32 v182, vcc, 0x4000, v182
	s_nop 1
	v_addc_co_u32_e32 v183, vcc, 0, v183, vcc
	global_load_dwordx4 v[134:137], v[182:183], off
	s_movk_i32 s2, 0x2400
	s_cmp_lt_i32 s5, 22
	v_mul_lo_u32 v97, v103, s2
	s_cselect_b64 s[2:3], -1, 0
	s_cmp_gt_i32 s5, 21
	s_movk_i32 s5, 0x110
	v_and_b32_e32 v103, 16, v104
	v_mad_u32_u24 v104, v102, s5, v97
	v_add_u32_e32 v113, 0xfffff000, v96
	v_cndmask_b32_e64 v102, 0, 1, s[2:3]
	s_cselect_b64 s[2:3], -1, 0
	s_add_i32 s7, s4, 0xfffff000
	v_add_u32_e32 v104, v104, v103
	ds_write_b128 v104, v[64:67]
	ds_write_b128 v104, v[68:71] offset:32
	ds_write_b128 v104, v[72:75] offset:64
	ds_write_b128 v104, v[76:79] offset:96
	ds_write_b128 v104, v[80:83] offset:128
	ds_write_b128 v104, v[84:87] offset:160
	ds_write_b128 v104, v[88:91] offset:192
	ds_write_b128 v104, v[92:95] offset:224
	v_xor_b32_e32 v64, s7, v113
	s_movk_i32 s4, 0x400
	v_lshl_or_b32 v97, v112, 4, v97
	v_cmp_gt_u32_e32 vcc, s4, v64
	v_mad_u32_u24 v115, v128, s5, v97
	s_and_b64 s[4:5], s[2:3], vcc
	v_cndmask_b32_e64 v71, 0, 1, s[4:5]
	s_movk_i32 s4, 0x1000
	v_cmp_gt_i32_e32 vcc, s4, v100
	v_subrev_u32_e32 v114, s8, v98
	v_lshl_add_u32 v103, v114, 2, v167
	v_cndmask_b32_e32 v64, v71, v102, vcc
	v_and_b32_e32 v64, 1, v64
	v_cmp_eq_u32_e32 vcc, 1, v64
	v_ashrrev_i32_e32 v68, 6, v105
	s_mov_b32 s4, 0xc000
	v_cndmask_b32_e64 v64, v171, 0, vcc
	v_add_u32_e32 v70, v103, v64
	ds_read_b128 v[64:67], v115
	ds_read_b128 v[72:75], v70
	v_cmp_eq_u32_e64 s[36:37], 0, v112
	v_mad_i64_i32 v[68:69], s[4:5], v68, s4, 0
	s_and_b64 vcc, exec, s[0:1]
	s_waitcnt vmcnt(15) lgkmcnt(0)
	v_pk_fma_f32 v[66:67], v[66:67], v[74:75], v[200:201]
	v_pk_fma_f32 v[64:65], v[64:65], v[72:73], v[198:199]
	global_store_dwordx4 v[110:111], v[64:67], off
	s_cbranch_vccnz .LBB0_1439
	ds_read_b128 v[72:75], v70 offset:2048
	v_lshlrev_b64 v[76:77], 10, v[100:101]
	v_lshl_add_u64 v[76:77], v[76:77], 1, s[50:51]
	v_lshl_add_u64 v[76:77], v[98:99], 1, v[76:77]
	s_waitcnt lgkmcnt(0)
	v_pk_mul_f32 v[72:73], v[64:65], v[72:73]
	v_pk_mul_f32 v[64:65], v[64:65], v[64:65]
	v_pk_mul_f32 v[74:75], v[66:67], v[74:75]
	v_pk_mul_f32 v[66:67], v[66:67], v[66:67]
	v_add_f32_e32 v64, v64, v65
	v_add_f32_e32 v64, v66, v64
	v_add_f32_e32 v64, v67, v64
	v_cvt_pk_bf16_f32 v72, v72, v73
	v_cvt_pk_bf16_f32 v73, v74, v75
	v_add_f32_dpp v64, v64, v64 quad_perm:[1,0,3,2] row_mask:0xf bank_mask:0xf bound_ctrl:1
	global_store_dwordx2 v[76:77], v[72:73], off
	s_nop 0
	v_add_f32_dpp v64, v64, v64 quad_perm:[2,3,0,1] row_mask:0xf bank_mask:0xf bound_ctrl:1
	s_nop 1
	v_add_f32_dpp v64, v64, v64 row_half_mirror row_mask:0xf bank_mask:0xf bound_ctrl:1
	s_nop 1
	v_mov_b32_dpp v65, v64 row_mirror row_mask:0xf bank_mask:0xf bound_ctrl:1
	s_and_saveexec_b64 s[4:5], s[36:37]
	s_cbranch_execz .LBB0_1438
	v_lshl_add_u64 v[66:67], s[54:55], 0, v[68:69]
	v_lshl_add_u64 v[66:67], v[100:101], 2, v[66:67]
	v_add_f32_e32 v64, v64, v65
	global_store_dword v[66:67], v64, off

.LBB0_1439:
	v_or_b32_e32 v70, 4, v128
	v_or_b32_e32 v72, v96, v70
	v_ashrrev_i32_e32 v73, 31, v72
	v_lshlrev_b64 v[64:65], 12, v[72:73]
	v_lshl_add_u64 v[64:65], s[40:41], 0, v[64:65]
	v_lshl_add_u64 v[84:85], v[98:99], 2, v[64:65]
	s_movk_i32 s4, 0x1000
	v_mul_u32_u24_e32 v74, 0x110, v128
	v_cmp_gt_i32_e32 vcc, s4, v72
	v_add_u32_e32 v86, v74, v97
	s_nop 0
	v_cndmask_b32_e32 v74, v71, v102, vcc
	v_and_b32_e32 v74, 1, v74
	v_cmp_eq_u32_e32 vcc, 1, v74
	s_nop 1
	v_cndmask_b32_e64 v74, v171, 0, vcc
	v_add_u32_e32 v74, v103, v74
	ds_read_b128 v[76:79], v86 offset:1088
	ds_read_b128 v[80:83], v74
	s_and_b64 vcc, exec, s[0:1]
	s_waitcnt vmcnt(15) lgkmcnt(0)
	v_pk_fma_f32 v[66:67], v[78:79], v[82:83], v[204:205]
	v_pk_fma_f32 v[64:65], v[76:77], v[80:81], v[202:203]
	global_store_dwordx4 v[84:85], v[64:67], off
	s_cbranch_vccnz .LBB0_1443
	ds_read_b128 v[74:77], v74 offset:2048
	v_lshlrev_b64 v[72:73], 10, v[72:73]
	v_lshl_add_u64 v[72:73], v[72:73], 1, s[50:51]
	v_lshl_add_u64 v[72:73], v[98:99], 1, v[72:73]
	s_waitcnt lgkmcnt(0)
	v_pk_mul_f32 v[74:75], v[64:65], v[74:75]
	v_pk_mul_f32 v[64:65], v[64:65], v[64:65]
	v_pk_mul_f32 v[76:77], v[66:67], v[76:77]
	v_pk_mul_f32 v[66:67], v[66:67], v[66:67]
	v_add_f32_e32 v64, v64, v65
	v_add_f32_e32 v64, v66, v64
	v_add_f32_e32 v64, v67, v64
	v_cvt_pk_bf16_f32 v74, v74, v75
	v_cvt_pk_bf16_f32 v75, v76, v77
	v_add_f32_dpp v64, v64, v64 quad_perm:[1,0,3,2] row_mask:0xf bank_mask:0xf bound_ctrl:1
	global_store_dwordx2 v[72:73], v[74:75], off
	s_nop 0
	v_add_f32_dpp v64, v64, v64 quad_perm:[2,3,0,1] row_mask:0xf bank_mask:0xf bound_ctrl:1
	s_nop 1
	v_add_f32_dpp v64, v64, v64 row_half_mirror row_mask:0xf bank_mask:0xf bound_ctrl:1
	s_nop 1
	v_mov_b32_dpp v65, v64 row_mirror row_mask:0xf bank_mask:0xf bound_ctrl:1
	s_and_saveexec_b64 s[4:5], s[36:37]
	s_cbranch_execz .LBB0_1442
	v_ashrrev_i32_e32 v97, 31, v96
	v_lshl_add_u64 v[66:67], s[54:55], 0, v[68:69]
	v_lshl_add_u64 v[72:73], v[96:97], 0, v[128:129]
	v_lshl_add_u64 v[66:67], v[72:73], 2, v[66:67]
	v_add_f32_e32 v64, v64, v65
	global_store_dword v[66:67], v64, off offset:16

.LBB0_1443:
	v_or_b32_e32 v72, 8, v128
	v_or_b32_e32 v74, v96, v72
	v_ashrrev_i32_e32 v75, 31, v74
	v_lshlrev_b64 v[64:65], 12, v[74:75]
	v_lshl_add_u64 v[64:65], s[40:41], 0, v[64:65]
	v_lshl_add_u64 v[84:85], v[98:99], 2, v[64:65]
	s_movk_i32 s4, 0x1000
	v_cmp_gt_i32_e32 vcc, s4, v74
	s_nop 1
	v_cndmask_b32_e32 v73, v71, v102, vcc
	v_and_b32_e32 v73, 1, v73
	v_cmp_eq_u32_e32 vcc, 1, v73
	s_nop 1
	v_cndmask_b32_e64 v73, v171, 0, vcc
	v_add_u32_e32 v73, v103, v73
	ds_read_b128 v[76:79], v86 offset:2176
	ds_read_b128 v[80:83], v73
	s_and_b64 vcc, exec, s[0:1]
	s_waitcnt vmcnt(15) lgkmcnt(0)
	v_pk_fma_f32 v[66:67], v[78:79], v[82:83], v[208:209]
	v_pk_fma_f32 v[64:65], v[76:77], v[80:81], v[206:207]
	global_store_dwordx4 v[84:85], v[64:67], off
	s_cbranch_vccnz .LBB0_1447
	ds_read_b128 v[76:79], v73 offset:2048
	v_lshlrev_b64 v[74:75], 10, v[74:75]
	v_lshl_add_u64 v[74:75], v[74:75], 1, s[50:51]
	v_lshl_add_u64 v[74:75], v[98:99], 1, v[74:75]
	s_waitcnt lgkmcnt(0)
	v_pk_mul_f32 v[76:77], v[64:65], v[76:77]
	v_pk_mul_f32 v[64:65], v[64:65], v[64:65]
	v_pk_mul_f32 v[78:79], v[66:67], v[78:79]
	v_pk_mul_f32 v[66:67], v[66:67], v[66:67]
	v_add_f32_e32 v64, v64, v65
	v_add_f32_e32 v64, v66, v64
	v_add_f32_e32 v64, v67, v64
	v_cvt_pk_bf16_f32 v76, v76, v77
	v_cvt_pk_bf16_f32 v77, v78, v79
	v_add_f32_dpp v64, v64, v64 quad_perm:[1,0,3,2] row_mask:0xf bank_mask:0xf bound_ctrl:1
	global_store_dwordx2 v[74:75], v[76:77], off
	s_nop 0
	v_add_f32_dpp v64, v64, v64 quad_perm:[2,3,0,1] row_mask:0xf bank_mask:0xf bound_ctrl:1
	s_nop 1
	v_add_f32_dpp v64, v64, v64 row_half_mirror row_mask:0xf bank_mask:0xf bound_ctrl:1
	s_nop 1
	v_mov_b32_dpp v65, v64 row_mirror row_mask:0xf bank_mask:0xf bound_ctrl:1
	s_and_saveexec_b64 s[4:5], s[36:37]
	s_cbranch_execz .LBB0_1446
	v_ashrrev_i32_e32 v97, 31, v96
	v_lshl_add_u64 v[66:67], s[54:55], 0, v[68:69]
	v_lshl_add_u64 v[74:75], v[96:97], 0, v[128:129]
	v_lshl_add_u64 v[66:67], v[74:75], 2, v[66:67]
	v_add_f32_e32 v64, v64, v65
	global_store_dword v[66:67], v64, off offset:32

.LBB0_1447:
	v_or_b32_e32 v74, 12, v128
	v_or_b32_e32 v76, v96, v74
	v_ashrrev_i32_e32 v77, 31, v76
	v_lshlrev_b64 v[64:65], 12, v[76:77]
	v_lshl_add_u64 v[64:65], s[40:41], 0, v[64:65]
	v_lshl_add_u64 v[88:89], v[98:99], 2, v[64:65]
	s_movk_i32 s4, 0x1000
	v_cmp_gt_i32_e32 vcc, s4, v76
	s_nop 1
	v_cndmask_b32_e32 v73, v71, v102, vcc
	v_and_b32_e32 v73, 1, v73
	v_cmp_eq_u32_e32 vcc, 1, v73
	s_nop 1
	v_cndmask_b32_e64 v73, v171, 0, vcc
	v_add_u32_e32 v73, v103, v73
	ds_read_b128 v[78:81], v86 offset:3264
	ds_read_b128 v[82:85], v73
	s_and_b64 vcc, exec, s[0:1]
	s_waitcnt vmcnt(15) lgkmcnt(0)
	v_pk_fma_f32 v[66:67], v[80:81], v[84:85], v[212:213]
	v_pk_fma_f32 v[64:65], v[78:79], v[82:83], v[210:211]
	global_store_dwordx4 v[88:89], v[64:67], off
	s_cbranch_vccnz .LBB0_1451
	ds_read_b128 v[78:81], v73 offset:2048
	v_lshlrev_b64 v[76:77], 10, v[76:77]
	v_lshl_add_u64 v[76:77], v[76:77], 1, s[50:51]
	v_lshl_add_u64 v[76:77], v[98:99], 1, v[76:77]
	s_waitcnt lgkmcnt(0)
	v_pk_mul_f32 v[78:79], v[64:65], v[78:79]
	v_pk_mul_f32 v[64:65], v[64:65], v[64:65]
	v_pk_mul_f32 v[80:81], v[66:67], v[80:81]
	v_pk_mul_f32 v[66:67], v[66:67], v[66:67]
	v_add_f32_e32 v64, v64, v65
	v_add_f32_e32 v64, v66, v64
	v_add_f32_e32 v64, v67, v64
	v_cvt_pk_bf16_f32 v78, v78, v79
	v_cvt_pk_bf16_f32 v79, v80, v81
	v_add_f32_dpp v64, v64, v64 quad_perm:[1,0,3,2] row_mask:0xf bank_mask:0xf bound_ctrl:1
	global_store_dwordx2 v[76:77], v[78:79], off
	s_nop 0
	v_add_f32_dpp v64, v64, v64 quad_perm:[2,3,0,1] row_mask:0xf bank_mask:0xf bound_ctrl:1
	s_nop 1
	v_add_f32_dpp v64, v64, v64 row_half_mirror row_mask:0xf bank_mask:0xf bound_ctrl:1
	s_nop 1
	v_mov_b32_dpp v65, v64 row_mirror row_mask:0xf bank_mask:0xf bound_ctrl:1
	s_and_saveexec_b64 s[4:5], s[36:37]
	s_cbranch_execz .LBB0_1450
	v_ashrrev_i32_e32 v97, 31, v96
	v_lshl_add_u64 v[66:67], s[54:55], 0, v[68:69]
	v_lshl_add_u64 v[76:77], v[96:97], 0, v[128:129]
	v_lshl_add_u64 v[66:67], v[76:77], 2, v[66:67]
	v_add_f32_e32 v64, v64, v65
	global_store_dword v[66:67], v64, off offset:48

.LBB0_1451:
	v_or_b32_e32 v76, 16, v128
	v_or_b32_e32 v78, v96, v76
	v_ashrrev_i32_e32 v79, 31, v78
	v_lshlrev_b64 v[64:65], 12, v[78:79]
	v_lshl_add_u64 v[64:65], s[40:41], 0, v[64:65]
	v_lshl_add_u64 v[84:85], v[98:99], 2, v[64:65]
	s_movk_i32 s4, 0x1000
	v_cmp_gt_i32_e32 vcc, s4, v78
	s_nop 1
	v_cndmask_b32_e32 v73, v71, v102, vcc
	v_and_b32_e32 v73, 1, v73
	v_cmp_eq_u32_e32 vcc, 1, v73
	s_nop 1
	v_cndmask_b32_e64 v73, v171, 0, vcc
	v_add_u32_e32 v73, v103, v73
	ds_read_b128 v[80:83], v86 offset:4352
	ds_read_b128 v[88:91], v73
	s_and_b64 vcc, exec, s[0:1]
	s_waitcnt vmcnt(15) lgkmcnt(0)
	v_pk_fma_f32 v[66:67], v[82:83], v[90:91], v[216:217]
	v_pk_fma_f32 v[64:65], v[80:81], v[88:89], v[214:215]
	global_store_dwordx4 v[84:85], v[64:67], off
	s_cbranch_vccnz .LBB0_1455
	ds_read_b128 v[80:83], v73 offset:2048
	v_lshlrev_b64 v[78:79], 10, v[78:79]
	v_lshl_add_u64 v[78:79], v[78:79], 1, s[50:51]
	v_lshl_add_u64 v[78:79], v[98:99], 1, v[78:79]
	s_waitcnt lgkmcnt(0)
	v_pk_mul_f32 v[80:81], v[64:65], v[80:81]
	v_pk_mul_f32 v[64:65], v[64:65], v[64:65]
	v_pk_mul_f32 v[82:83], v[66:67], v[82:83]
	v_pk_mul_f32 v[66:67], v[66:67], v[66:67]
	v_add_f32_e32 v64, v64, v65
	v_add_f32_e32 v64, v66, v64
	v_add_f32_e32 v64, v67, v64
	v_cvt_pk_bf16_f32 v80, v80, v81
	v_cvt_pk_bf16_f32 v81, v82, v83
	v_add_f32_dpp v64, v64, v64 quad_perm:[1,0,3,2] row_mask:0xf bank_mask:0xf bound_ctrl:1
	global_store_dwordx2 v[78:79], v[80:81], off
	s_nop 0
	v_add_f32_dpp v64, v64, v64 quad_perm:[2,3,0,1] row_mask:0xf bank_mask:0xf bound_ctrl:1
	s_nop 1
	v_add_f32_dpp v64, v64, v64 row_half_mirror row_mask:0xf bank_mask:0xf bound_ctrl:1
	s_nop 1
	v_mov_b32_dpp v65, v64 row_mirror row_mask:0xf bank_mask:0xf bound_ctrl:1
	s_and_saveexec_b64 s[4:5], s[36:37]
	s_cbranch_execz .LBB0_1454
	v_ashrrev_i32_e32 v97, 31, v96
	v_lshl_add_u64 v[66:67], s[54:55], 0, v[68:69]
	v_lshl_add_u64 v[78:79], v[96:97], 0, v[128:129]
	v_lshl_add_u64 v[66:67], v[78:79], 2, v[66:67]
	v_add_f32_e32 v64, v64, v65
	global_store_dword v[66:67], v64, off offset:64

.LBB0_1455:
	v_or_b32_e32 v78, 20, v128
	v_or_b32_e32 v80, v96, v78
	v_ashrrev_i32_e32 v81, 31, v80
	v_lshlrev_b64 v[64:65], 12, v[80:81]
	v_lshl_add_u64 v[64:65], s[40:41], 0, v[64:65]
	v_lshl_add_u64 v[92:93], v[98:99], 2, v[64:65]
	s_movk_i32 s4, 0x1000
	v_cmp_gt_i32_e32 vcc, s4, v80
	s_nop 1
	v_cndmask_b32_e32 v73, v71, v102, vcc
	v_and_b32_e32 v73, 1, v73
	v_cmp_eq_u32_e32 vcc, 1, v73
	s_nop 1
	v_cndmask_b32_e64 v73, v171, 0, vcc
	v_add_u32_e32 v73, v103, v73
	ds_read_b128 v[82:85], v86 offset:5440
	ds_read_b128 v[88:91], v73
	s_and_b64 vcc, exec, s[0:1]
	s_waitcnt vmcnt(15) lgkmcnt(0)
	v_pk_fma_f32 v[66:67], v[84:85], v[90:91], v[220:221]
	v_pk_fma_f32 v[64:65], v[82:83], v[88:89], v[218:219]
	global_store_dwordx4 v[92:93], v[64:67], off
	s_cbranch_vccnz .LBB0_1459
	ds_read_b128 v[82:85], v73 offset:2048
	v_lshlrev_b64 v[80:81], 10, v[80:81]
	v_lshl_add_u64 v[80:81], v[80:81], 1, s[50:51]
	v_lshl_add_u64 v[80:81], v[98:99], 1, v[80:81]
	s_waitcnt lgkmcnt(0)
	v_pk_mul_f32 v[82:83], v[64:65], v[82:83]
	v_pk_mul_f32 v[64:65], v[64:65], v[64:65]
	v_pk_mul_f32 v[84:85], v[66:67], v[84:85]
	v_pk_mul_f32 v[66:67], v[66:67], v[66:67]
	v_add_f32_e32 v64, v64, v65
	v_add_f32_e32 v64, v66, v64
	v_add_f32_e32 v64, v67, v64
	v_cvt_pk_bf16_f32 v82, v82, v83
	v_cvt_pk_bf16_f32 v83, v84, v85
	v_add_f32_dpp v64, v64, v64 quad_perm:[1,0,3,2] row_mask:0xf bank_mask:0xf bound_ctrl:1
	global_store_dwordx2 v[80:81], v[82:83], off
	s_nop 0
	v_add_f32_dpp v64, v64, v64 quad_perm:[2,3,0,1] row_mask:0xf bank_mask:0xf bound_ctrl:1
	s_nop 1
	v_add_f32_dpp v64, v64, v64 row_half_mirror row_mask:0xf bank_mask:0xf bound_ctrl:1
	s_nop 1
	v_mov_b32_dpp v65, v64 row_mirror row_mask:0xf bank_mask:0xf bound_ctrl:1
	s_and_saveexec_b64 s[4:5], s[36:37]
	s_cbranch_execz .LBB0_1458
	v_ashrrev_i32_e32 v97, 31, v96
	v_lshl_add_u64 v[66:67], s[54:55], 0, v[68:69]
	v_lshl_add_u64 v[80:81], v[96:97], 0, v[128:129]
	v_lshl_add_u64 v[66:67], v[80:81], 2, v[66:67]
	v_add_f32_e32 v64, v64, v65
	global_store_dword v[66:67], v64, off offset:80

.LBB0_1459:
	v_or_b32_e32 v80, 24, v128
	v_or_b32_e32 v82, v96, v80
	v_ashrrev_i32_e32 v83, 31, v82
	v_lshlrev_b64 v[64:65], 12, v[82:83]
	v_lshl_add_u64 v[64:65], s[40:41], 0, v[64:65]
	v_lshl_add_u64 v[84:85], v[98:99], 2, v[64:65]
	s_movk_i32 s4, 0x1000
	v_cmp_gt_i32_e32 vcc, s4, v82
	s_nop 1
	v_cndmask_b32_e32 v73, v71, v102, vcc
	v_and_b32_e32 v73, 1, v73
	v_cmp_eq_u32_e32 vcc, 1, v73
	s_nop 1
	v_cndmask_b32_e64 v73, v171, 0, vcc
	v_add_u32_e32 v73, v103, v73
	ds_read_b128 v[88:91], v86 offset:6528
	ds_read_b128 v[92:95], v73
	s_and_b64 vcc, exec, s[0:1]
	s_waitcnt vmcnt(15) lgkmcnt(0)
	v_pk_fma_f32 v[66:67], v[90:91], v[94:95], v[224:225]
	v_pk_fma_f32 v[64:65], v[88:89], v[92:93], v[222:223]
	global_store_dwordx4 v[84:85], v[64:67], off
	s_cbranch_vccnz .LBB0_1463
	ds_read_b128 v[88:91], v73 offset:2048
	v_lshlrev_b64 v[82:83], 10, v[82:83]
	v_lshl_add_u64 v[82:83], v[82:83], 1, s[50:51]
	v_lshl_add_u64 v[82:83], v[98:99], 1, v[82:83]
	s_waitcnt lgkmcnt(0)
	v_pk_mul_f32 v[88:89], v[64:65], v[88:89]
	v_pk_mul_f32 v[64:65], v[64:65], v[64:65]
	v_pk_mul_f32 v[84:85], v[66:67], v[90:91]
	v_pk_mul_f32 v[66:67], v[66:67], v[66:67]
	v_add_f32_e32 v64, v64, v65
	v_add_f32_e32 v64, v66, v64
	v_add_f32_e32 v64, v67, v64
	v_cvt_pk_bf16_f32 v88, v88, v89
	v_cvt_pk_bf16_f32 v89, v84, v85
	v_add_f32_dpp v64, v64, v64 quad_perm:[1,0,3,2] row_mask:0xf bank_mask:0xf bound_ctrl:1
	global_store_dwordx2 v[82:83], v[88:89], off
	s_nop 0
	v_add_f32_dpp v64, v64, v64 quad_perm:[2,3,0,1] row_mask:0xf bank_mask:0xf bound_ctrl:1
	s_nop 1
	v_add_f32_dpp v64, v64, v64 row_half_mirror row_mask:0xf bank_mask:0xf bound_ctrl:1
	s_nop 1
	v_mov_b32_dpp v65, v64 row_mirror row_mask:0xf bank_mask:0xf bound_ctrl:1
	s_and_saveexec_b64 s[4:5], s[36:37]
	s_cbranch_execz .LBB0_1462
	v_ashrrev_i32_e32 v97, 31, v96
	v_lshl_add_u64 v[66:67], s[54:55], 0, v[68:69]
	v_lshl_add_u64 v[82:83], v[96:97], 0, v[128:129]
	v_lshl_add_u64 v[66:67], v[82:83], 2, v[66:67]
	v_add_f32_e32 v64, v64, v65
	global_store_dword v[66:67], v64, off offset:96

.LBB0_1463:
	v_or_b32_e32 v82, 28, v128
	v_or_b32_e32 v84, v96, v82
	v_ashrrev_i32_e32 v85, 31, v84
	v_lshlrev_b64 v[64:65], 12, v[84:85]
	v_lshl_add_u64 v[64:65], s[40:41], 0, v[64:65]
	v_lshl_add_u64 v[100:101], v[98:99], 2, v[64:65]
	s_movk_i32 s4, 0x1000
	v_cmp_gt_i32_e32 vcc, s4, v84
	s_nop 1
	v_cndmask_b32_e32 v71, v71, v102, vcc
	v_and_b32_e32 v71, 1, v71
	v_cmp_eq_u32_e32 vcc, 1, v71
	s_nop 1
	v_cndmask_b32_e64 v71, v171, 0, vcc
	v_add_u32_e32 v71, v103, v71
	ds_read_b128 v[88:91], v86 offset:7616
	ds_read_b128 v[92:95], v71
	s_and_b64 vcc, exec, s[0:1]
	s_waitcnt vmcnt(15) lgkmcnt(0)
	v_pk_fma_f32 v[66:67], v[90:91], v[94:95], v[228:229]
	v_pk_fma_f32 v[64:65], v[88:89], v[92:93], v[226:227]
	global_store_dwordx4 v[100:101], v[64:67], off
	s_cbranch_vccnz .LBB0_1467
	ds_read_b128 v[88:91], v71 offset:2048
	v_lshlrev_b64 v[84:85], 10, v[84:85]
	v_lshl_add_u64 v[84:85], v[84:85], 1, s[50:51]
	v_lshl_add_u64 v[84:85], v[98:99], 1, v[84:85]
	s_waitcnt lgkmcnt(0)
	v_pk_mul_f32 v[88:89], v[64:65], v[88:89]
	v_pk_mul_f32 v[64:65], v[64:65], v[64:65]
	v_pk_mul_f32 v[90:91], v[66:67], v[90:91]
	v_pk_mul_f32 v[66:67], v[66:67], v[66:67]
	v_add_f32_e32 v64, v64, v65
	v_add_f32_e32 v64, v66, v64
	v_add_f32_e32 v64, v67, v64
	v_cvt_pk_bf16_f32 v88, v88, v89
	v_cvt_pk_bf16_f32 v89, v90, v91
	v_add_f32_dpp v64, v64, v64 quad_perm:[1,0,3,2] row_mask:0xf bank_mask:0xf bound_ctrl:1
	global_store_dwordx2 v[84:85], v[88:89], off
	s_nop 0
	v_add_f32_dpp v64, v64, v64 quad_perm:[2,3,0,1] row_mask:0xf bank_mask:0xf bound_ctrl:1
	s_nop 1
	v_add_f32_dpp v64, v64, v64 row_half_mirror row_mask:0xf bank_mask:0xf bound_ctrl:1
	s_nop 1
	v_mov_b32_dpp v65, v64 row_mirror row_mask:0xf bank_mask:0xf bound_ctrl:1
	s_and_saveexec_b64 s[4:5], s[36:37]
	s_cbranch_execz .LBB0_1466
	v_ashrrev_i32_e32 v97, 31, v96
	v_lshl_add_u64 v[66:67], s[54:55], 0, v[68:69]
	v_lshl_add_u64 v[84:85], v[96:97], 0, v[128:129]
	v_lshl_add_u64 v[66:67], v[84:85], 2, v[66:67]
	v_add_f32_e32 v64, v64, v65
	global_store_dword v[66:67], v64, off offset:112

.LBB0_1467:
	s_nop 0
	v_add_u32_e32 v66, 32, v96
	v_or_b32_e32 v64, v66, v128
	v_ashrrev_i32_e32 v65, 31, v64
	v_lshlrev_b64 v[84:85], 12, v[64:65]
	v_lshl_add_u64 v[84:85], s[40:41], 0, v[84:85]
	v_lshl_add_u64 v[84:85], v[98:99], 2, v[84:85]
	v_add_co_u32_e32 v182, vcc, 0x20000, v84
	s_nop 1
	v_addc_co_u32_e32 v183, vcc, 0, v85, vcc
	global_load_dwordx4 v[198:201], v[182:183], off
	v_add_co_u32_e32 v182, vcc, 0x4000, v182
	s_nop 1
	v_addc_co_u32_e32 v183, vcc, 0, v183, vcc
	global_load_dwordx4 v[202:205], v[182:183], off
	v_add_co_u32_e32 v182, vcc, 0x4000, v182
	s_nop 1
	v_addc_co_u32_e32 v183, vcc, 0, v183, vcc
	global_load_dwordx4 v[206:209], v[182:183], off
	v_add_co_u32_e32 v182, vcc, 0x4000, v182
	s_nop 1
	v_addc_co_u32_e32 v183, vcc, 0, v183, vcc
	global_load_dwordx4 v[210:213], v[182:183], off
	v_add_co_u32_e32 v182, vcc, 0x4000, v182
	s_nop 1
	v_addc_co_u32_e32 v183, vcc, 0, v183, vcc
	global_load_dwordx4 v[214:217], v[182:183], off
	v_add_co_u32_e32 v182, vcc, 0x4000, v182
	s_nop 1
	v_addc_co_u32_e32 v183, vcc, 0, v183, vcc
	global_load_dwordx4 v[218:221], v[182:183], off
	v_add_co_u32_e32 v182, vcc, 0x4000, v182
	s_nop 1
	v_addc_co_u32_e32 v183, vcc, 0, v183, vcc
	global_load_dwordx4 v[222:225], v[182:183], off
	v_add_co_u32_e32 v182, vcc, 0x4000, v182
	s_nop 1
	v_addc_co_u32_e32 v183, vcc, 0, v183, vcc
	global_load_dwordx4 v[226:229], v[182:183], off
	ds_write_b128 v104, v[32:35]
	ds_write_b128 v104, v[36:39] offset:32
	ds_write_b128 v104, v[40:43] offset:64
	ds_write_b128 v104, v[44:47] offset:96
	ds_write_b128 v104, v[48:51] offset:128
	ds_write_b128 v104, v[52:55] offset:160
	ds_write_b128 v104, v[56:59] offset:192
	ds_write_b128 v104, v[60:63] offset:224
	v_add_u32_e32 v32, 0xfffff020, v96
	v_xor_b32_e32 v32, s7, v32
	s_movk_i32 s4, 0x400
	v_cmp_gt_u32_e32 vcc, s4, v32
	s_and_b64 s[4:5], s[2:3], vcc
	v_cndmask_b32_e64 v38, 0, 1, s[4:5]
	s_movk_i32 s4, 0x1000
	v_cmp_gt_i32_e32 vcc, s4, v64
	s_nop 1
	v_cndmask_b32_e32 v32, v38, v102, vcc
	v_and_b32_e32 v32, 1, v32
	v_cmp_eq_u32_e32 vcc, 1, v32
	s_nop 1
	v_cndmask_b32_e64 v32, v171, 0, vcc
	v_add_u32_e32 v36, v103, v32
	ds_read_b128 v[32:35], v86
	ds_read_b128 v[40:43], v36
	s_and_b64 vcc, exec, s[0:1]
	s_waitcnt vmcnt(23) lgkmcnt(0)
	v_pk_fma_f32 v[34:35], v[34:35], v[42:43], v[186:187]
	v_pk_fma_f32 v[32:33], v[32:33], v[40:41], v[184:185]
	global_store_dwordx4 v[84:85], v[32:35], off
	s_cbranch_vccnz .LBB0_1471
	ds_read_b128 v[40:43], v36 offset:2048
	v_lshlrev_b64 v[36:37], 10, v[64:65]
	v_lshl_add_u64 v[36:37], v[36:37], 1, s[50:51]
	v_lshl_add_u64 v[36:37], v[98:99], 1, v[36:37]
	s_waitcnt lgkmcnt(0)
	v_pk_mul_f32 v[40:41], v[32:33], v[40:41]
	v_pk_mul_f32 v[32:33], v[32:33], v[32:33]
	v_pk_mul_f32 v[42:43], v[34:35], v[42:43]
	v_pk_mul_f32 v[34:35], v[34:35], v[34:35]
	v_add_f32_e32 v32, v32, v33
	v_add_f32_e32 v32, v34, v32
	v_add_f32_e32 v32, v35, v32
	v_cvt_pk_bf16_f32 v40, v40, v41
	v_cvt_pk_bf16_f32 v41, v42, v43
	v_add_f32_dpp v32, v32, v32 quad_perm:[1,0,3,2] row_mask:0xf bank_mask:0xf bound_ctrl:1
	global_store_dwordx2 v[36:37], v[40:41], off
	s_nop 0
	v_add_f32_dpp v32, v32, v32 quad_perm:[2,3,0,1] row_mask:0xf bank_mask:0xf bound_ctrl:1
	s_nop 1
	v_add_f32_dpp v32, v32, v32 row_half_mirror row_mask:0xf bank_mask:0xf bound_ctrl:1
	s_nop 1
	v_mov_b32_dpp v33, v32 row_mirror row_mask:0xf bank_mask:0xf bound_ctrl:1
	s_and_saveexec_b64 s[4:5], s[36:37]
	s_cbranch_execz .LBB0_1470
	v_ashrrev_i32_e32 v97, 31, v96
	v_lshl_add_u64 v[34:35], s[54:55], 0, v[68:69]
	v_lshl_add_u64 v[36:37], v[96:97], 0, v[128:129]
	v_lshl_add_u64 v[34:35], v[36:37], 2, v[34:35]
	v_add_f32_e32 v32, v32, v33
	global_store_dword v[34:35], v32, off offset:128

.LBB0_1471:
	v_or_b32_e32 v36, v66, v70
	v_ashrrev_i32_e32 v37, 31, v36
	v_lshlrev_b64 v[32:33], 12, v[36:37]
	v_lshl_add_u64 v[32:33], s[40:41], 0, v[32:33]
	v_lshl_add_u64 v[48:49], v[98:99], 2, v[32:33]
	s_movk_i32 s4, 0x1000
	v_cmp_gt_i32_e32 vcc, s4, v36
	s_nop 1
	v_cndmask_b32_e32 v39, v38, v102, vcc
	v_and_b32_e32 v39, 1, v39
	v_cmp_eq_u32_e32 vcc, 1, v39
	s_nop 1
	v_cndmask_b32_e64 v39, v171, 0, vcc
	v_add_u32_e32 v39, v103, v39
	ds_read_b128 v[40:43], v86 offset:1088
	ds_read_b128 v[44:47], v39
	s_and_b64 vcc, exec, s[0:1]
	s_waitcnt vmcnt(23) lgkmcnt(0)
	v_pk_fma_f32 v[34:35], v[42:43], v[46:47], v[190:191]
	v_pk_fma_f32 v[32:33], v[40:41], v[44:45], v[188:189]
	global_store_dwordx4 v[48:49], v[32:35], off
	s_cbranch_vccnz .LBB0_1475
	ds_read_b128 v[40:43], v39 offset:2048
	v_lshlrev_b64 v[36:37], 10, v[36:37]
	v_lshl_add_u64 v[36:37], v[36:37], 1, s[50:51]
	v_lshl_add_u64 v[36:37], v[98:99], 1, v[36:37]
	s_waitcnt lgkmcnt(0)
	v_pk_mul_f32 v[40:41], v[32:33], v[40:41]
	v_pk_mul_f32 v[32:33], v[32:33], v[32:33]
	v_pk_mul_f32 v[42:43], v[34:35], v[42:43]
	v_pk_mul_f32 v[34:35], v[34:35], v[34:35]
	v_add_f32_e32 v32, v32, v33
	v_add_f32_e32 v32, v34, v32
	v_add_f32_e32 v32, v35, v32
	v_cvt_pk_bf16_f32 v40, v40, v41
	v_cvt_pk_bf16_f32 v41, v42, v43
	v_add_f32_dpp v32, v32, v32 quad_perm:[1,0,3,2] row_mask:0xf bank_mask:0xf bound_ctrl:1
	global_store_dwordx2 v[36:37], v[40:41], off
	s_nop 0
	v_add_f32_dpp v32, v32, v32 quad_perm:[2,3,0,1] row_mask:0xf bank_mask:0xf bound_ctrl:1
	s_nop 1
	v_add_f32_dpp v32, v32, v32 row_half_mirror row_mask:0xf bank_mask:0xf bound_ctrl:1
	s_nop 1
	v_mov_b32_dpp v33, v32 row_mirror row_mask:0xf bank_mask:0xf bound_ctrl:1
	s_and_saveexec_b64 s[4:5], s[36:37]
	s_cbranch_execz .LBB0_1474
	v_mov_b32_e32 v71, v129
	v_ashrrev_i32_e32 v97, 31, v96
	v_lshl_add_u64 v[34:35], s[54:55], 0, v[68:69]
	v_lshl_add_u64 v[36:37], v[96:97], 0, v[70:71]
	v_lshl_add_u64 v[34:35], v[36:37], 2, v[34:35]
	v_add_f32_e32 v32, v32, v33
	global_store_dword v[34:35], v32, off offset:128

.LBB0_1475:
	v_or_b32_e32 v36, v66, v72
	v_ashrrev_i32_e32 v37, 31, v36
	v_lshlrev_b64 v[32:33], 12, v[36:37]
	v_lshl_add_u64 v[32:33], s[40:41], 0, v[32:33]
	v_lshl_add_u64 v[48:49], v[98:99], 2, v[32:33]
	s_movk_i32 s4, 0x1000
	v_cmp_gt_i32_e32 vcc, s4, v36
	s_nop 1
	v_cndmask_b32_e32 v39, v38, v102, vcc
	v_and_b32_e32 v39, 1, v39
	v_cmp_eq_u32_e32 vcc, 1, v39
	s_nop 1
	v_cndmask_b32_e64 v39, v171, 0, vcc
	v_add_u32_e32 v39, v103, v39
	ds_read_b128 v[40:43], v86 offset:2176
	ds_read_b128 v[44:47], v39
	s_and_b64 vcc, exec, s[0:1]
	s_waitcnt vmcnt(23) lgkmcnt(0)
	v_pk_fma_f32 v[34:35], v[42:43], v[46:47], v[194:195]
	v_pk_fma_f32 v[32:33], v[40:41], v[44:45], v[192:193]
	global_store_dwordx4 v[48:49], v[32:35], off
	s_cbranch_vccnz .LBB0_1479
	ds_read_b128 v[40:43], v39 offset:2048
	v_lshlrev_b64 v[36:37], 10, v[36:37]
	v_lshl_add_u64 v[36:37], v[36:37], 1, s[50:51]
	v_lshl_add_u64 v[36:37], v[98:99], 1, v[36:37]
	s_waitcnt lgkmcnt(0)
	v_pk_mul_f32 v[40:41], v[32:33], v[40:41]
	v_pk_mul_f32 v[32:33], v[32:33], v[32:33]
	v_pk_mul_f32 v[42:43], v[34:35], v[42:43]
	v_pk_mul_f32 v[34:35], v[34:35], v[34:35]
	v_add_f32_e32 v32, v32, v33
	v_add_f32_e32 v32, v34, v32
	v_add_f32_e32 v32, v35, v32
	v_cvt_pk_bf16_f32 v40, v40, v41
	v_cvt_pk_bf16_f32 v41, v42, v43
	v_add_f32_dpp v32, v32, v32 quad_perm:[1,0,3,2] row_mask:0xf bank_mask:0xf bound_ctrl:1
	global_store_dwordx2 v[36:37], v[40:41], off
	s_nop 0
	v_add_f32_dpp v32, v32, v32 quad_perm:[2,3,0,1] row_mask:0xf bank_mask:0xf bound_ctrl:1
	s_nop 1
	v_add_f32_dpp v32, v32, v32 row_half_mirror row_mask:0xf bank_mask:0xf bound_ctrl:1
	s_nop 1
	v_mov_b32_dpp v33, v32 row_mirror row_mask:0xf bank_mask:0xf bound_ctrl:1
	s_and_saveexec_b64 s[4:5], s[36:37]
	s_cbranch_execz .LBB0_1478
	v_mov_b32_e32 v73, v129
	v_ashrrev_i32_e32 v97, 31, v96
	v_lshl_add_u64 v[34:35], s[54:55], 0, v[68:69]
	v_lshl_add_u64 v[36:37], v[96:97], 0, v[72:73]
	v_lshl_add_u64 v[34:35], v[36:37], 2, v[34:35]
	v_add_f32_e32 v32, v32, v33
	global_store_dword v[34:35], v32, off offset:128

.LBB0_1479:
	v_or_b32_e32 v36, v66, v74
	v_ashrrev_i32_e32 v37, 31, v36
	v_lshlrev_b64 v[32:33], 12, v[36:37]
	v_lshl_add_u64 v[32:33], s[40:41], 0, v[32:33]
	v_lshl_add_u64 v[48:49], v[98:99], 2, v[32:33]
	s_movk_i32 s4, 0x1000
	v_cmp_gt_i32_e32 vcc, s4, v36
	s_nop 1
	v_cndmask_b32_e32 v39, v38, v102, vcc
	v_and_b32_e32 v39, 1, v39
	v_cmp_eq_u32_e32 vcc, 1, v39
	s_nop 1
	v_cndmask_b32_e64 v39, v171, 0, vcc
	v_add_u32_e32 v39, v103, v39
	ds_read_b128 v[40:43], v86 offset:3264
	ds_read_b128 v[44:47], v39
	s_and_b64 vcc, exec, s[0:1]
	s_waitcnt vmcnt(23) lgkmcnt(0)
	v_pk_fma_f32 v[34:35], v[42:43], v[46:47], v[118:119]
	v_pk_fma_f32 v[32:33], v[40:41], v[44:45], v[116:117]
	global_store_dwordx4 v[48:49], v[32:35], off
	s_cbranch_vccnz .LBB0_1483
	ds_read_b128 v[40:43], v39 offset:2048
	v_lshlrev_b64 v[36:37], 10, v[36:37]
	v_lshl_add_u64 v[36:37], v[36:37], 1, s[50:51]
	v_lshl_add_u64 v[36:37], v[98:99], 1, v[36:37]
	s_waitcnt lgkmcnt(0)
	v_pk_mul_f32 v[40:41], v[32:33], v[40:41]
	v_pk_mul_f32 v[32:33], v[32:33], v[32:33]
	v_pk_mul_f32 v[42:43], v[34:35], v[42:43]
	v_pk_mul_f32 v[34:35], v[34:35], v[34:35]
	v_add_f32_e32 v32, v32, v33
	v_add_f32_e32 v32, v34, v32
	v_add_f32_e32 v32, v35, v32
	v_cvt_pk_bf16_f32 v40, v40, v41
	v_cvt_pk_bf16_f32 v41, v42, v43
	v_add_f32_dpp v32, v32, v32 quad_perm:[1,0,3,2] row_mask:0xf bank_mask:0xf bound_ctrl:1
	global_store_dwordx2 v[36:37], v[40:41], off
	s_nop 0
	v_add_f32_dpp v32, v32, v32 quad_perm:[2,3,0,1] row_mask:0xf bank_mask:0xf bound_ctrl:1
	s_nop 1
	v_add_f32_dpp v32, v32, v32 row_half_mirror row_mask:0xf bank_mask:0xf bound_ctrl:1
	s_nop 1
	v_mov_b32_dpp v33, v32 row_mirror row_mask:0xf bank_mask:0xf bound_ctrl:1
	s_and_saveexec_b64 s[4:5], s[36:37]
	s_cbranch_execz .LBB0_1482
	v_mov_b32_e32 v75, v129
	v_ashrrev_i32_e32 v97, 31, v96
	v_lshl_add_u64 v[34:35], s[54:55], 0, v[68:69]
	v_lshl_add_u64 v[36:37], v[96:97], 0, v[74:75]
	v_lshl_add_u64 v[34:35], v[36:37], 2, v[34:35]
	v_add_f32_e32 v32, v32, v33
	global_store_dword v[34:35], v32, off offset:128

.LBB0_1483:
	v_or_b32_e32 v36, v66, v76
	v_ashrrev_i32_e32 v37, 31, v36
	v_lshlrev_b64 v[32:33], 12, v[36:37]
	v_lshl_add_u64 v[32:33], s[40:41], 0, v[32:33]
	v_lshl_add_u64 v[48:49], v[98:99], 2, v[32:33]
	s_movk_i32 s4, 0x1000
	v_cmp_gt_i32_e32 vcc, s4, v36
	s_nop 1
	v_cndmask_b32_e32 v39, v38, v102, vcc
	v_and_b32_e32 v39, 1, v39
	v_cmp_eq_u32_e32 vcc, 1, v39
	s_nop 1
	v_cndmask_b32_e64 v39, v171, 0, vcc
	v_add_u32_e32 v39, v103, v39
	ds_read_b128 v[40:43], v86 offset:4352
	ds_read_b128 v[44:47], v39
	s_and_b64 vcc, exec, s[0:1]
	s_waitcnt vmcnt(23) lgkmcnt(0)
	v_pk_fma_f32 v[34:35], v[42:43], v[46:47], v[122:123]
	v_pk_fma_f32 v[32:33], v[40:41], v[44:45], v[120:121]
	global_store_dwordx4 v[48:49], v[32:35], off
	s_cbranch_vccnz .LBB0_1487
	ds_read_b128 v[40:43], v39 offset:2048
	v_lshlrev_b64 v[36:37], 10, v[36:37]
	v_lshl_add_u64 v[36:37], v[36:37], 1, s[50:51]
	v_lshl_add_u64 v[36:37], v[98:99], 1, v[36:37]
	s_waitcnt lgkmcnt(0)
	v_pk_mul_f32 v[40:41], v[32:33], v[40:41]
	v_pk_mul_f32 v[32:33], v[32:33], v[32:33]
	v_pk_mul_f32 v[42:43], v[34:35], v[42:43]
	v_pk_mul_f32 v[34:35], v[34:35], v[34:35]
	v_add_f32_e32 v32, v32, v33
	v_add_f32_e32 v32, v34, v32
	v_add_f32_e32 v32, v35, v32
	v_cvt_pk_bf16_f32 v40, v40, v41
	v_cvt_pk_bf16_f32 v41, v42, v43
	v_add_f32_dpp v32, v32, v32 quad_perm:[1,0,3,2] row_mask:0xf bank_mask:0xf bound_ctrl:1
	global_store_dwordx2 v[36:37], v[40:41], off
	s_nop 0
	v_add_f32_dpp v32, v32, v32 quad_perm:[2,3,0,1] row_mask:0xf bank_mask:0xf bound_ctrl:1
	s_nop 1
	v_add_f32_dpp v32, v32, v32 row_half_mirror row_mask:0xf bank_mask:0xf bound_ctrl:1
	s_nop 1
	v_mov_b32_dpp v33, v32 row_mirror row_mask:0xf bank_mask:0xf bound_ctrl:1
	s_and_saveexec_b64 s[4:5], s[36:37]
	s_cbranch_execz .LBB0_1486
	v_mov_b32_e32 v77, v129
	v_ashrrev_i32_e32 v97, 31, v96
	v_lshl_add_u64 v[34:35], s[54:55], 0, v[68:69]
	v_lshl_add_u64 v[36:37], v[96:97], 0, v[76:77]
	v_lshl_add_u64 v[34:35], v[36:37], 2, v[34:35]
	v_add_f32_e32 v32, v32, v33
	global_store_dword v[34:35], v32, off offset:128

.LBB0_1487:
	v_or_b32_e32 v36, v66, v78
	v_ashrrev_i32_e32 v37, 31, v36
	v_lshlrev_b64 v[32:33], 12, v[36:37]
	v_lshl_add_u64 v[32:33], s[40:41], 0, v[32:33]
	v_lshl_add_u64 v[48:49], v[98:99], 2, v[32:33]
	s_movk_i32 s4, 0x1000
	v_cmp_gt_i32_e32 vcc, s4, v36
	s_nop 1
	v_cndmask_b32_e32 v39, v38, v102, vcc
	v_and_b32_e32 v39, 1, v39
	v_cmp_eq_u32_e32 vcc, 1, v39
	s_nop 1
	v_cndmask_b32_e64 v39, v171, 0, vcc
	v_add_u32_e32 v39, v103, v39
	ds_read_b128 v[40:43], v86 offset:5440
	ds_read_b128 v[44:47], v39
	s_and_b64 vcc, exec, s[0:1]
	s_waitcnt vmcnt(23) lgkmcnt(0)
	v_pk_fma_f32 v[34:35], v[42:43], v[46:47], v[126:127]
	v_pk_fma_f32 v[32:33], v[40:41], v[44:45], v[124:125]
	global_store_dwordx4 v[48:49], v[32:35], off
	s_cbranch_vccnz .LBB0_1491
	ds_read_b128 v[40:43], v39 offset:2048
	v_lshlrev_b64 v[36:37], 10, v[36:37]
	v_lshl_add_u64 v[36:37], v[36:37], 1, s[50:51]
	v_lshl_add_u64 v[36:37], v[98:99], 1, v[36:37]
	s_waitcnt lgkmcnt(0)
	v_pk_mul_f32 v[40:41], v[32:33], v[40:41]
	v_pk_mul_f32 v[32:33], v[32:33], v[32:33]
	v_pk_mul_f32 v[42:43], v[34:35], v[42:43]
	v_pk_mul_f32 v[34:35], v[34:35], v[34:35]
	v_add_f32_e32 v32, v32, v33
	v_add_f32_e32 v32, v34, v32
	v_add_f32_e32 v32, v35, v32
	v_cvt_pk_bf16_f32 v40, v40, v41
	v_cvt_pk_bf16_f32 v41, v42, v43
	v_add_f32_dpp v32, v32, v32 quad_perm:[1,0,3,2] row_mask:0xf bank_mask:0xf bound_ctrl:1
	global_store_dwordx2 v[36:37], v[40:41], off
	s_nop 0
	v_add_f32_dpp v32, v32, v32 quad_perm:[2,3,0,1] row_mask:0xf bank_mask:0xf bound_ctrl:1
	s_nop 1
	v_add_f32_dpp v32, v32, v32 row_half_mirror row_mask:0xf bank_mask:0xf bound_ctrl:1
	s_nop 1
	v_mov_b32_dpp v33, v32 row_mirror row_mask:0xf bank_mask:0xf bound_ctrl:1
	s_and_saveexec_b64 s[4:5], s[36:37]
	s_cbranch_execz .LBB0_1490
	v_mov_b32_e32 v79, v129
	v_ashrrev_i32_e32 v97, 31, v96
	v_lshl_add_u64 v[34:35], s[54:55], 0, v[68:69]
	v_lshl_add_u64 v[36:37], v[96:97], 0, v[78:79]
	v_lshl_add_u64 v[34:35], v[36:37], 2, v[34:35]
	v_add_f32_e32 v32, v32, v33
	global_store_dword v[34:35], v32, off offset:128

.LBB0_1491:
	v_or_b32_e32 v36, v66, v80
	v_ashrrev_i32_e32 v37, 31, v36
	v_lshlrev_b64 v[32:33], 12, v[36:37]
	v_lshl_add_u64 v[32:33], s[40:41], 0, v[32:33]
	v_lshl_add_u64 v[48:49], v[98:99], 2, v[32:33]
	s_movk_i32 s4, 0x1000
	v_cmp_gt_i32_e32 vcc, s4, v36
	s_nop 1
	v_cndmask_b32_e32 v39, v38, v102, vcc
	v_and_b32_e32 v39, 1, v39
	v_cmp_eq_u32_e32 vcc, 1, v39
	s_nop 1
	v_cndmask_b32_e64 v39, v171, 0, vcc
	v_add_u32_e32 v39, v103, v39
	ds_read_b128 v[40:43], v86 offset:6528
	ds_read_b128 v[44:47], v39
	s_and_b64 vcc, exec, s[0:1]
	s_waitcnt vmcnt(23) lgkmcnt(0)
	v_pk_fma_f32 v[34:35], v[42:43], v[46:47], v[132:133]
	v_pk_fma_f32 v[32:33], v[40:41], v[44:45], v[130:131]
	global_store_dwordx4 v[48:49], v[32:35], off
	s_cbranch_vccnz .LBB0_1495
	ds_read_b128 v[40:43], v39 offset:2048
	v_lshlrev_b64 v[36:37], 10, v[36:37]
	v_lshl_add_u64 v[36:37], v[36:37], 1, s[50:51]
	v_lshl_add_u64 v[36:37], v[98:99], 1, v[36:37]
	s_waitcnt lgkmcnt(0)
	v_pk_mul_f32 v[40:41], v[32:33], v[40:41]
	v_pk_mul_f32 v[32:33], v[32:33], v[32:33]
	v_pk_mul_f32 v[42:43], v[34:35], v[42:43]
	v_pk_mul_f32 v[34:35], v[34:35], v[34:35]
	v_add_f32_e32 v32, v32, v33
	v_add_f32_e32 v32, v34, v32
	v_add_f32_e32 v32, v35, v32
	v_cvt_pk_bf16_f32 v40, v40, v41
	v_cvt_pk_bf16_f32 v41, v42, v43
	v_add_f32_dpp v32, v32, v32 quad_perm:[1,0,3,2] row_mask:0xf bank_mask:0xf bound_ctrl:1
	global_store_dwordx2 v[36:37], v[40:41], off
	s_nop 0
	v_add_f32_dpp v32, v32, v32 quad_perm:[2,3,0,1] row_mask:0xf bank_mask:0xf bound_ctrl:1
	s_nop 1
	v_add_f32_dpp v32, v32, v32 row_half_mirror row_mask:0xf bank_mask:0xf bound_ctrl:1
	s_nop 1
	v_mov_b32_dpp v33, v32 row_mirror row_mask:0xf bank_mask:0xf bound_ctrl:1
	s_and_saveexec_b64 s[4:5], s[36:37]
	s_cbranch_execz .LBB0_1494
	v_mov_b32_e32 v81, v129
	v_ashrrev_i32_e32 v97, 31, v96
	v_lshl_add_u64 v[34:35], s[54:55], 0, v[68:69]
	v_lshl_add_u64 v[36:37], v[96:97], 0, v[80:81]
	v_lshl_add_u64 v[34:35], v[36:37], 2, v[34:35]
	v_add_f32_e32 v32, v32, v33
	global_store_dword v[34:35], v32, off offset:128

.LBB0_1495:
	v_or_b32_e32 v36, v66, v82
	v_ashrrev_i32_e32 v37, 31, v36
	v_lshlrev_b64 v[32:33], 12, v[36:37]
	v_lshl_add_u64 v[32:33], s[40:41], 0, v[32:33]
	v_lshl_add_u64 v[48:49], v[98:99], 2, v[32:33]
	s_movk_i32 s4, 0x1000
	v_cmp_gt_i32_e32 vcc, s4, v36
	s_nop 1
	v_cndmask_b32_e32 v38, v38, v102, vcc
	v_and_b32_e32 v38, 1, v38
	v_cmp_eq_u32_e32 vcc, 1, v38
	s_nop 1
	v_cndmask_b32_e64 v38, v171, 0, vcc
	v_add_u32_e32 v38, v103, v38
	ds_read_b128 v[40:43], v86 offset:7616
	ds_read_b128 v[44:47], v38
	s_and_b64 vcc, exec, s[0:1]
	s_waitcnt vmcnt(23) lgkmcnt(0)
	v_pk_fma_f32 v[34:35], v[42:43], v[46:47], v[136:137]
	v_pk_fma_f32 v[32:33], v[40:41], v[44:45], v[134:135]
	global_store_dwordx4 v[48:49], v[32:35], off
	s_cbranch_vccnz .LBB0_1499
	ds_read_b128 v[38:41], v38 offset:2048
	v_lshlrev_b64 v[36:37], 10, v[36:37]
	v_lshl_add_u64 v[36:37], v[36:37], 1, s[50:51]
	v_lshl_add_u64 v[36:37], v[98:99], 1, v[36:37]
	s_waitcnt lgkmcnt(0)
	v_pk_mul_f32 v[38:39], v[32:33], v[38:39]
	v_pk_mul_f32 v[32:33], v[32:33], v[32:33]
	v_pk_mul_f32 v[40:41], v[34:35], v[40:41]
	v_pk_mul_f32 v[34:35], v[34:35], v[34:35]
	v_add_f32_e32 v32, v32, v33
	v_add_f32_e32 v32, v34, v32
	v_add_f32_e32 v32, v35, v32
	v_cvt_pk_bf16_f32 v38, v38, v39
	v_cvt_pk_bf16_f32 v39, v40, v41
	v_add_f32_dpp v32, v32, v32 quad_perm:[1,0,3,2] row_mask:0xf bank_mask:0xf bound_ctrl:1
	global_store_dwordx2 v[36:37], v[38:39], off
	s_nop 0
	v_add_f32_dpp v32, v32, v32 quad_perm:[2,3,0,1] row_mask:0xf bank_mask:0xf bound_ctrl:1
	s_nop 1
	v_add_f32_dpp v32, v32, v32 row_half_mirror row_mask:0xf bank_mask:0xf bound_ctrl:1
	s_nop 1
	v_mov_b32_dpp v33, v32 row_mirror row_mask:0xf bank_mask:0xf bound_ctrl:1
	s_and_saveexec_b64 s[4:5], s[36:37]
	s_cbranch_execz .LBB0_1498
	v_mov_b32_e32 v83, v129
	v_ashrrev_i32_e32 v97, 31, v96
	v_lshl_add_u64 v[34:35], s[54:55], 0, v[68:69]
	v_lshl_add_u64 v[36:37], v[96:97], 0, v[82:83]
	v_lshl_add_u64 v[34:35], v[36:37], 2, v[34:35]
	v_add_f32_e32 v32, v32, v33
	global_store_dword v[34:35], v32, off offset:128

.LBB0_1499:
	s_nop 0
	v_add_u32_e32 v34, 64, v96
	v_or_b32_e32 v32, v34, v128
	v_ashrrev_i32_e32 v33, 31, v32
	v_lshlrev_b64 v[36:37], 12, v[32:33]
	v_lshl_add_u64 v[36:37], s[40:41], 0, v[36:37]
	v_lshl_add_u64 v[40:41], v[98:99], 2, v[36:37]
	ds_write_b128 v104, v[0:3]
	ds_write_b128 v104, v[4:7] offset:32
	ds_write_b128 v104, v[8:11] offset:64
	ds_write_b128 v104, v[12:15] offset:96
	ds_write_b128 v104, v[16:19] offset:128
	ds_write_b128 v104, v[20:23] offset:160
	ds_write_b128 v104, v[24:27] offset:192
	ds_write_b128 v104, v[28:31] offset:224
	v_add_u32_e32 v0, 0xfffff040, v96
	v_xor_b32_e32 v0, s7, v0
	s_movk_i32 s4, 0x400
	v_cmp_gt_u32_e32 vcc, s4, v0
	s_and_b64 s[2:3], s[2:3], vcc
	v_cndmask_b32_e64 v6, 0, 1, s[2:3]
	s_movk_i32 s2, 0x1000
	v_cmp_gt_i32_e32 vcc, s2, v32
	s_nop 1
	v_cndmask_b32_e32 v0, v6, v102, vcc
	v_and_b32_e32 v0, 1, v0
	v_cmp_eq_u32_e32 vcc, 1, v0
	s_nop 1
	v_cndmask_b32_e64 v0, v171, 0, vcc
	v_add_u32_e32 v4, v103, v0
	ds_read_b128 v[0:3], v86
	ds_read_b128 v[8:11], v4
	s_and_b64 vcc, exec, s[0:1]
	s_waitcnt vmcnt(15) lgkmcnt(0)
	v_pk_fma_f32 v[2:3], v[2:3], v[10:11], v[200:201]
	v_pk_fma_f32 v[0:1], v[0:1], v[8:9], v[198:199]
	global_store_dwordx4 v[40:41], v[0:3], off
	s_cbranch_vccnz .LBB0_1503
	ds_read_b128 v[8:11], v4 offset:2048
	v_lshlrev_b64 v[4:5], 10, v[32:33]
	v_lshl_add_u64 v[4:5], v[4:5], 1, s[50:51]
	v_lshl_add_u64 v[4:5], v[98:99], 1, v[4:5]
	s_waitcnt lgkmcnt(0)
	v_pk_mul_f32 v[8:9], v[0:1], v[8:9]
	v_pk_mul_f32 v[0:1], v[0:1], v[0:1]
	v_pk_mul_f32 v[10:11], v[2:3], v[10:11]
	v_pk_mul_f32 v[2:3], v[2:3], v[2:3]
	v_add_f32_e32 v0, v0, v1
	v_add_f32_e32 v0, v2, v0
	v_add_f32_e32 v0, v3, v0
	v_cvt_pk_bf16_f32 v8, v8, v9
	v_cvt_pk_bf16_f32 v9, v10, v11
	v_add_f32_dpp v0, v0, v0 quad_perm:[1,0,3,2] row_mask:0xf bank_mask:0xf bound_ctrl:1
	global_store_dwordx2 v[4:5], v[8:9], off
	s_nop 0
	v_add_f32_dpp v0, v0, v0 quad_perm:[2,3,0,1] row_mask:0xf bank_mask:0xf bound_ctrl:1
	s_nop 1
	v_add_f32_dpp v0, v0, v0 row_half_mirror row_mask:0xf bank_mask:0xf bound_ctrl:1
	s_nop 1
	v_mov_b32_dpp v1, v0 row_mirror row_mask:0xf bank_mask:0xf bound_ctrl:1
	s_and_saveexec_b64 s[2:3], s[36:37]
	s_cbranch_execz .LBB0_1502
	v_ashrrev_i32_e32 v97, 31, v96
	v_lshl_add_u64 v[2:3], s[54:55], 0, v[68:69]
	v_lshl_add_u64 v[4:5], v[96:97], 0, v[128:129]
	v_lshl_add_u64 v[2:3], v[4:5], 2, v[2:3]
	v_add_f32_e32 v0, v0, v1
	global_store_dword v[2:3], v0, off offset:256

.LBB0_1503:
	v_or_b32_e32 v4, v34, v70
	v_ashrrev_i32_e32 v5, 31, v4
	v_lshlrev_b64 v[0:1], 12, v[4:5]
	v_lshl_add_u64 v[0:1], s[40:41], 0, v[0:1]
	v_lshl_add_u64 v[16:17], v[98:99], 2, v[0:1]
	s_movk_i32 s2, 0x1000
	v_cmp_gt_i32_e32 vcc, s2, v4
	s_nop 1
	v_cndmask_b32_e32 v7, v6, v102, vcc
	v_and_b32_e32 v7, 1, v7
	v_cmp_eq_u32_e32 vcc, 1, v7
	s_nop 1
	v_cndmask_b32_e64 v7, v171, 0, vcc
	v_add_u32_e32 v7, v103, v7
	ds_read_b128 v[8:11], v86 offset:1088
	ds_read_b128 v[12:15], v7
	s_and_b64 vcc, exec, s[0:1]
	s_waitcnt vmcnt(15) lgkmcnt(0)
	v_pk_fma_f32 v[2:3], v[10:11], v[14:15], v[204:205]
	v_pk_fma_f32 v[0:1], v[8:9], v[12:13], v[202:203]
	global_store_dwordx4 v[16:17], v[0:3], off
	s_cbranch_vccnz .LBB0_1507
	ds_read_b128 v[8:11], v7 offset:2048
	v_lshlrev_b64 v[4:5], 10, v[4:5]
	v_lshl_add_u64 v[4:5], v[4:5], 1, s[50:51]
	v_lshl_add_u64 v[4:5], v[98:99], 1, v[4:5]
	s_waitcnt lgkmcnt(0)
	v_pk_mul_f32 v[8:9], v[0:1], v[8:9]
	v_pk_mul_f32 v[0:1], v[0:1], v[0:1]
	v_pk_mul_f32 v[10:11], v[2:3], v[10:11]
	v_pk_mul_f32 v[2:3], v[2:3], v[2:3]
	v_add_f32_e32 v0, v0, v1
	v_add_f32_e32 v0, v2, v0
	v_add_f32_e32 v0, v3, v0
	v_cvt_pk_bf16_f32 v8, v8, v9
	v_cvt_pk_bf16_f32 v9, v10, v11
	v_add_f32_dpp v0, v0, v0 quad_perm:[1,0,3,2] row_mask:0xf bank_mask:0xf bound_ctrl:1
	global_store_dwordx2 v[4:5], v[8:9], off
	s_nop 0
	v_add_f32_dpp v0, v0, v0 quad_perm:[2,3,0,1] row_mask:0xf bank_mask:0xf bound_ctrl:1
	s_nop 1
	v_add_f32_dpp v0, v0, v0 row_half_mirror row_mask:0xf bank_mask:0xf bound_ctrl:1
	s_nop 1
	v_mov_b32_dpp v1, v0 row_mirror row_mask:0xf bank_mask:0xf bound_ctrl:1
	s_and_saveexec_b64 s[2:3], s[36:37]
	s_cbranch_execz .LBB0_1506
	v_mov_b32_e32 v71, v129
	v_ashrrev_i32_e32 v97, 31, v96
	v_lshl_add_u64 v[2:3], s[54:55], 0, v[68:69]
	v_lshl_add_u64 v[4:5], v[96:97], 0, v[70:71]
	v_lshl_add_u64 v[2:3], v[4:5], 2, v[2:3]
	v_add_f32_e32 v0, v0, v1
	global_store_dword v[2:3], v0, off offset:256

.LBB0_1507:
	v_or_b32_e32 v4, v34, v72
	v_ashrrev_i32_e32 v5, 31, v4
	v_lshlrev_b64 v[0:1], 12, v[4:5]
	v_lshl_add_u64 v[0:1], s[40:41], 0, v[0:1]
	v_lshl_add_u64 v[16:17], v[98:99], 2, v[0:1]
	s_movk_i32 s2, 0x1000
	v_cmp_gt_i32_e32 vcc, s2, v4
	s_nop 1
	v_cndmask_b32_e32 v7, v6, v102, vcc
	v_and_b32_e32 v7, 1, v7
	v_cmp_eq_u32_e32 vcc, 1, v7
	s_nop 1
	v_cndmask_b32_e64 v7, v171, 0, vcc
	v_add_u32_e32 v7, v103, v7
	ds_read_b128 v[8:11], v86 offset:2176
	ds_read_b128 v[12:15], v7
	s_and_b64 vcc, exec, s[0:1]
	s_waitcnt vmcnt(15) lgkmcnt(0)
	v_pk_fma_f32 v[2:3], v[10:11], v[14:15], v[208:209]
	v_pk_fma_f32 v[0:1], v[8:9], v[12:13], v[206:207]
	global_store_dwordx4 v[16:17], v[0:3], off
	s_cbranch_vccnz .LBB0_1511
	ds_read_b128 v[8:11], v7 offset:2048
	v_lshlrev_b64 v[4:5], 10, v[4:5]
	v_lshl_add_u64 v[4:5], v[4:5], 1, s[50:51]
	v_lshl_add_u64 v[4:5], v[98:99], 1, v[4:5]
	s_waitcnt lgkmcnt(0)
	v_pk_mul_f32 v[8:9], v[0:1], v[8:9]
	v_pk_mul_f32 v[0:1], v[0:1], v[0:1]
	v_pk_mul_f32 v[10:11], v[2:3], v[10:11]
	v_pk_mul_f32 v[2:3], v[2:3], v[2:3]
	v_add_f32_e32 v0, v0, v1
	v_add_f32_e32 v0, v2, v0
	v_add_f32_e32 v0, v3, v0
	v_cvt_pk_bf16_f32 v8, v8, v9
	v_cvt_pk_bf16_f32 v9, v10, v11
	v_add_f32_dpp v0, v0, v0 quad_perm:[1,0,3,2] row_mask:0xf bank_mask:0xf bound_ctrl:1
	global_store_dwordx2 v[4:5], v[8:9], off
	s_nop 0
	v_add_f32_dpp v0, v0, v0 quad_perm:[2,3,0,1] row_mask:0xf bank_mask:0xf bound_ctrl:1
	s_nop 1
	v_add_f32_dpp v0, v0, v0 row_half_mirror row_mask:0xf bank_mask:0xf bound_ctrl:1
	s_nop 1
	v_mov_b32_dpp v1, v0 row_mirror row_mask:0xf bank_mask:0xf bound_ctrl:1
	s_and_saveexec_b64 s[2:3], s[36:37]
	s_cbranch_execz .LBB0_1510
	v_mov_b32_e32 v73, v129
	v_ashrrev_i32_e32 v97, 31, v96
	v_lshl_add_u64 v[2:3], s[54:55], 0, v[68:69]
	v_lshl_add_u64 v[4:5], v[96:97], 0, v[72:73]
	v_lshl_add_u64 v[2:3], v[4:5], 2, v[2:3]
	v_add_f32_e32 v0, v0, v1
	global_store_dword v[2:3], v0, off offset:256

.LBB0_1511:
	v_or_b32_e32 v4, v34, v74
	v_ashrrev_i32_e32 v5, 31, v4
	v_lshlrev_b64 v[0:1], 12, v[4:5]
	v_lshl_add_u64 v[0:1], s[40:41], 0, v[0:1]
	v_lshl_add_u64 v[16:17], v[98:99], 2, v[0:1]
	s_movk_i32 s2, 0x1000
	v_cmp_gt_i32_e32 vcc, s2, v4
	s_nop 1
	v_cndmask_b32_e32 v7, v6, v102, vcc
	v_and_b32_e32 v7, 1, v7
	v_cmp_eq_u32_e32 vcc, 1, v7
	s_nop 1
	v_cndmask_b32_e64 v7, v171, 0, vcc
	v_add_u32_e32 v7, v103, v7
	ds_read_b128 v[8:11], v86 offset:3264
	ds_read_b128 v[12:15], v7
	s_and_b64 vcc, exec, s[0:1]
	s_waitcnt vmcnt(15) lgkmcnt(0)
	v_pk_fma_f32 v[2:3], v[10:11], v[14:15], v[212:213]
	v_pk_fma_f32 v[0:1], v[8:9], v[12:13], v[210:211]
	global_store_dwordx4 v[16:17], v[0:3], off
	s_cbranch_vccnz .LBB0_1515
	ds_read_b128 v[8:11], v7 offset:2048
	v_lshlrev_b64 v[4:5], 10, v[4:5]
	v_lshl_add_u64 v[4:5], v[4:5], 1, s[50:51]
	v_lshl_add_u64 v[4:5], v[98:99], 1, v[4:5]
	s_waitcnt lgkmcnt(0)
	v_pk_mul_f32 v[8:9], v[0:1], v[8:9]
	v_pk_mul_f32 v[0:1], v[0:1], v[0:1]
	v_pk_mul_f32 v[10:11], v[2:3], v[10:11]
	v_pk_mul_f32 v[2:3], v[2:3], v[2:3]
	v_add_f32_e32 v0, v0, v1
	v_add_f32_e32 v0, v2, v0
	v_add_f32_e32 v0, v3, v0
	v_cvt_pk_bf16_f32 v8, v8, v9
	v_cvt_pk_bf16_f32 v9, v10, v11
	v_add_f32_dpp v0, v0, v0 quad_perm:[1,0,3,2] row_mask:0xf bank_mask:0xf bound_ctrl:1
	global_store_dwordx2 v[4:5], v[8:9], off
	s_nop 0
	v_add_f32_dpp v0, v0, v0 quad_perm:[2,3,0,1] row_mask:0xf bank_mask:0xf bound_ctrl:1
	s_nop 1
	v_add_f32_dpp v0, v0, v0 row_half_mirror row_mask:0xf bank_mask:0xf bound_ctrl:1
	s_nop 1
	v_mov_b32_dpp v1, v0 row_mirror row_mask:0xf bank_mask:0xf bound_ctrl:1
	s_and_saveexec_b64 s[2:3], s[36:37]
	s_cbranch_execz .LBB0_1514
	v_mov_b32_e32 v75, v129
	v_ashrrev_i32_e32 v97, 31, v96
	v_lshl_add_u64 v[2:3], s[54:55], 0, v[68:69]
	v_lshl_add_u64 v[4:5], v[96:97], 0, v[74:75]
	v_lshl_add_u64 v[2:3], v[4:5], 2, v[2:3]
	v_add_f32_e32 v0, v0, v1
	global_store_dword v[2:3], v0, off offset:256

.LBB0_1515:
	v_or_b32_e32 v4, v34, v76
	v_ashrrev_i32_e32 v5, 31, v4
	v_lshlrev_b64 v[0:1], 12, v[4:5]
	v_lshl_add_u64 v[0:1], s[40:41], 0, v[0:1]
	v_lshl_add_u64 v[16:17], v[98:99], 2, v[0:1]
	s_movk_i32 s2, 0x1000
	v_cmp_gt_i32_e32 vcc, s2, v4
	s_nop 1
	v_cndmask_b32_e32 v7, v6, v102, vcc
	v_and_b32_e32 v7, 1, v7
	v_cmp_eq_u32_e32 vcc, 1, v7
	s_nop 1
	v_cndmask_b32_e64 v7, v171, 0, vcc
	v_add_u32_e32 v7, v103, v7
	ds_read_b128 v[8:11], v86 offset:4352
	ds_read_b128 v[12:15], v7
	s_and_b64 vcc, exec, s[0:1]
	s_waitcnt vmcnt(15) lgkmcnt(0)
	v_pk_fma_f32 v[2:3], v[10:11], v[14:15], v[216:217]
	v_pk_fma_f32 v[0:1], v[8:9], v[12:13], v[214:215]
	global_store_dwordx4 v[16:17], v[0:3], off
	s_cbranch_vccnz .LBB0_1519
	ds_read_b128 v[8:11], v7 offset:2048
	v_lshlrev_b64 v[4:5], 10, v[4:5]
	v_lshl_add_u64 v[4:5], v[4:5], 1, s[50:51]
	v_lshl_add_u64 v[4:5], v[98:99], 1, v[4:5]
	s_waitcnt lgkmcnt(0)
	v_pk_mul_f32 v[8:9], v[0:1], v[8:9]
	v_pk_mul_f32 v[0:1], v[0:1], v[0:1]
	v_pk_mul_f32 v[10:11], v[2:3], v[10:11]
	v_pk_mul_f32 v[2:3], v[2:3], v[2:3]
	v_add_f32_e32 v0, v0, v1
	v_add_f32_e32 v0, v2, v0
	v_add_f32_e32 v0, v3, v0
	v_cvt_pk_bf16_f32 v8, v8, v9
	v_cvt_pk_bf16_f32 v9, v10, v11
	v_add_f32_dpp v0, v0, v0 quad_perm:[1,0,3,2] row_mask:0xf bank_mask:0xf bound_ctrl:1
	global_store_dwordx2 v[4:5], v[8:9], off
	s_nop 0
	v_add_f32_dpp v0, v0, v0 quad_perm:[2,3,0,1] row_mask:0xf bank_mask:0xf bound_ctrl:1
	s_nop 1
	v_add_f32_dpp v0, v0, v0 row_half_mirror row_mask:0xf bank_mask:0xf bound_ctrl:1
	s_nop 1
	v_mov_b32_dpp v1, v0 row_mirror row_mask:0xf bank_mask:0xf bound_ctrl:1
	s_and_saveexec_b64 s[2:3], s[36:37]
	s_cbranch_execz .LBB0_1518
	v_mov_b32_e32 v77, v129
	v_ashrrev_i32_e32 v97, 31, v96
	v_lshl_add_u64 v[2:3], s[54:55], 0, v[68:69]
	v_lshl_add_u64 v[4:5], v[96:97], 0, v[76:77]
	v_lshl_add_u64 v[2:3], v[4:5], 2, v[2:3]
	v_add_f32_e32 v0, v0, v1
	global_store_dword v[2:3], v0, off offset:256

.LBB0_1519:
	v_or_b32_e32 v4, v34, v78
	v_ashrrev_i32_e32 v5, 31, v4
	v_lshlrev_b64 v[0:1], 12, v[4:5]
	v_lshl_add_u64 v[0:1], s[40:41], 0, v[0:1]
	v_lshl_add_u64 v[16:17], v[98:99], 2, v[0:1]
	s_movk_i32 s2, 0x1000
	v_cmp_gt_i32_e32 vcc, s2, v4
	s_nop 1
	v_cndmask_b32_e32 v7, v6, v102, vcc
	v_and_b32_e32 v7, 1, v7
	v_cmp_eq_u32_e32 vcc, 1, v7
	s_nop 1
	v_cndmask_b32_e64 v7, v171, 0, vcc
	v_add_u32_e32 v7, v103, v7
	ds_read_b128 v[8:11], v86 offset:5440
	ds_read_b128 v[12:15], v7
	s_and_b64 vcc, exec, s[0:1]
	s_waitcnt vmcnt(15) lgkmcnt(0)
	v_pk_fma_f32 v[2:3], v[10:11], v[14:15], v[220:221]
	v_pk_fma_f32 v[0:1], v[8:9], v[12:13], v[218:219]
	global_store_dwordx4 v[16:17], v[0:3], off
	s_cbranch_vccnz .LBB0_1523
	ds_read_b128 v[8:11], v7 offset:2048
	v_lshlrev_b64 v[4:5], 10, v[4:5]
	v_lshl_add_u64 v[4:5], v[4:5], 1, s[50:51]
	v_lshl_add_u64 v[4:5], v[98:99], 1, v[4:5]
	s_waitcnt lgkmcnt(0)
	v_pk_mul_f32 v[8:9], v[0:1], v[8:9]
	v_pk_mul_f32 v[0:1], v[0:1], v[0:1]
	v_pk_mul_f32 v[10:11], v[2:3], v[10:11]
	v_pk_mul_f32 v[2:3], v[2:3], v[2:3]
	v_add_f32_e32 v0, v0, v1
	v_add_f32_e32 v0, v2, v0
	v_add_f32_e32 v0, v3, v0
	v_cvt_pk_bf16_f32 v8, v8, v9
	v_cvt_pk_bf16_f32 v9, v10, v11
	v_add_f32_dpp v0, v0, v0 quad_perm:[1,0,3,2] row_mask:0xf bank_mask:0xf bound_ctrl:1
	global_store_dwordx2 v[4:5], v[8:9], off
	s_nop 0
	v_add_f32_dpp v0, v0, v0 quad_perm:[2,3,0,1] row_mask:0xf bank_mask:0xf bound_ctrl:1
	s_nop 1
	v_add_f32_dpp v0, v0, v0 row_half_mirror row_mask:0xf bank_mask:0xf bound_ctrl:1
	s_nop 1
	v_mov_b32_dpp v1, v0 row_mirror row_mask:0xf bank_mask:0xf bound_ctrl:1
	s_and_saveexec_b64 s[2:3], s[36:37]
	s_cbranch_execz .LBB0_1522
	v_mov_b32_e32 v79, v129
	v_ashrrev_i32_e32 v97, 31, v96
	v_lshl_add_u64 v[2:3], s[54:55], 0, v[68:69]
	v_lshl_add_u64 v[4:5], v[96:97], 0, v[78:79]
	v_lshl_add_u64 v[2:3], v[4:5], 2, v[2:3]
	v_add_f32_e32 v0, v0, v1
	global_store_dword v[2:3], v0, off offset:256

.LBB0_1523:
	v_or_b32_e32 v4, v34, v80
	v_ashrrev_i32_e32 v5, 31, v4
	v_lshlrev_b64 v[0:1], 12, v[4:5]
	v_lshl_add_u64 v[0:1], s[40:41], 0, v[0:1]
	v_lshl_add_u64 v[16:17], v[98:99], 2, v[0:1]
	s_movk_i32 s2, 0x1000
	v_cmp_gt_i32_e32 vcc, s2, v4
	s_nop 1
	v_cndmask_b32_e32 v7, v6, v102, vcc
	v_and_b32_e32 v7, 1, v7
	v_cmp_eq_u32_e32 vcc, 1, v7
	s_nop 1
	v_cndmask_b32_e64 v7, v171, 0, vcc
	v_add_u32_e32 v7, v103, v7
	ds_read_b128 v[8:11], v86 offset:6528
	ds_read_b128 v[12:15], v7
	s_and_b64 vcc, exec, s[0:1]
	s_waitcnt vmcnt(15) lgkmcnt(0)
	v_pk_fma_f32 v[2:3], v[10:11], v[14:15], v[224:225]
	v_pk_fma_f32 v[0:1], v[8:9], v[12:13], v[222:223]
	global_store_dwordx4 v[16:17], v[0:3], off
	s_cbranch_vccnz .LBB0_1527
	ds_read_b128 v[8:11], v7 offset:2048
	v_lshlrev_b64 v[4:5], 10, v[4:5]
	v_lshl_add_u64 v[4:5], v[4:5], 1, s[50:51]
	v_lshl_add_u64 v[4:5], v[98:99], 1, v[4:5]
	s_waitcnt lgkmcnt(0)
	v_pk_mul_f32 v[8:9], v[0:1], v[8:9]
	v_pk_mul_f32 v[0:1], v[0:1], v[0:1]
	v_pk_mul_f32 v[10:11], v[2:3], v[10:11]
	v_pk_mul_f32 v[2:3], v[2:3], v[2:3]
	v_add_f32_e32 v0, v0, v1
	v_add_f32_e32 v0, v2, v0
	v_add_f32_e32 v0, v3, v0
	v_cvt_pk_bf16_f32 v8, v8, v9
	v_cvt_pk_bf16_f32 v9, v10, v11
	v_add_f32_dpp v0, v0, v0 quad_perm:[1,0,3,2] row_mask:0xf bank_mask:0xf bound_ctrl:1
	global_store_dwordx2 v[4:5], v[8:9], off
	s_nop 0
	v_add_f32_dpp v0, v0, v0 quad_perm:[2,3,0,1] row_mask:0xf bank_mask:0xf bound_ctrl:1
	s_nop 1
	v_add_f32_dpp v0, v0, v0 row_half_mirror row_mask:0xf bank_mask:0xf bound_ctrl:1
	s_nop 1
	v_mov_b32_dpp v1, v0 row_mirror row_mask:0xf bank_mask:0xf bound_ctrl:1
	s_and_saveexec_b64 s[2:3], s[36:37]
	s_cbranch_execz .LBB0_1526
	v_mov_b32_e32 v81, v129
	v_ashrrev_i32_e32 v97, 31, v96
	v_lshl_add_u64 v[2:3], s[54:55], 0, v[68:69]
	v_lshl_add_u64 v[4:5], v[96:97], 0, v[80:81]
	v_lshl_add_u64 v[2:3], v[4:5], 2, v[2:3]
	v_add_f32_e32 v0, v0, v1
	global_store_dword v[2:3], v0, off offset:256

.LBB0_1527:
	v_or_b32_e32 v4, v34, v82
	v_ashrrev_i32_e32 v5, 31, v4
	v_lshlrev_b64 v[0:1], 12, v[4:5]
	v_lshl_add_u64 v[0:1], s[40:41], 0, v[0:1]
	v_lshl_add_u64 v[16:17], v[98:99], 2, v[0:1]
	s_movk_i32 s2, 0x1000
	v_cmp_gt_i32_e32 vcc, s2, v4
	s_nop 1
	v_cndmask_b32_e32 v6, v6, v102, vcc
	v_and_b32_e32 v6, 1, v6
	v_cmp_eq_u32_e32 vcc, 1, v6
	s_nop 1
	v_cndmask_b32_e64 v6, v171, 0, vcc
	v_add_u32_e32 v6, v103, v6
	ds_read_b128 v[8:11], v86 offset:7616
	ds_read_b128 v[12:15], v6
	s_and_b64 vcc, exec, s[0:1]
	s_waitcnt vmcnt(15) lgkmcnt(0)
	v_pk_fma_f32 v[2:3], v[10:11], v[14:15], v[228:229]
	v_pk_fma_f32 v[0:1], v[8:9], v[12:13], v[226:227]
	global_store_dwordx4 v[16:17], v[0:3], off
	s_cbranch_vccnz .LBB0_1430
	ds_read_b128 v[6:9], v6 offset:2048
	v_lshlrev_b64 v[4:5], 10, v[4:5]
	v_lshl_add_u64 v[4:5], v[4:5], 1, s[50:51]
	v_lshl_add_u64 v[4:5], v[98:99], 1, v[4:5]
	s_waitcnt lgkmcnt(0)
	v_pk_mul_f32 v[6:7], v[0:1], v[6:7]
	v_pk_mul_f32 v[0:1], v[0:1], v[0:1]
	v_pk_mul_f32 v[8:9], v[2:3], v[8:9]
	v_pk_mul_f32 v[2:3], v[2:3], v[2:3]
	v_add_f32_e32 v0, v0, v1
	v_add_f32_e32 v0, v2, v0
	v_add_f32_e32 v0, v3, v0
	v_cvt_pk_bf16_f32 v6, v6, v7
	v_cvt_pk_bf16_f32 v7, v8, v9
	v_add_f32_dpp v0, v0, v0 quad_perm:[1,0,3,2] row_mask:0xf bank_mask:0xf bound_ctrl:1
	global_store_dwordx2 v[4:5], v[6:7], off
	s_nop 0
	v_add_f32_dpp v0, v0, v0 quad_perm:[2,3,0,1] row_mask:0xf bank_mask:0xf bound_ctrl:1
	s_nop 1
	v_add_f32_dpp v0, v0, v0 row_half_mirror row_mask:0xf bank_mask:0xf bound_ctrl:1
	s_nop 1
	v_mov_b32_dpp v1, v0 row_mirror row_mask:0xf bank_mask:0xf bound_ctrl:1
	s_and_saveexec_b64 s[0:1], s[36:37]
	s_cbranch_execz .LBB0_1429
	v_mov_b32_e32 v83, v129
	v_ashrrev_i32_e32 v97, 31, v96
	v_lshl_add_u64 v[2:3], s[54:55], 0, v[68:69]
	v_lshl_add_u64 v[4:5], v[96:97], 0, v[82:83]
	v_lshl_add_u64 v[2:3], v[4:5], 2, v[2:3]
	v_add_f32_e32 v0, v0, v1
	global_store_dword v[2:3], v0, off offset:256
	s_branch .LBB0_1429
